# P7 bu via 4x4x4 bf16 MFMA broadcast-A in lane-per-state layout, in-lane 16-term Horner replaces cross-lane swaps
# baseline (speedup 1.0000x reference)
; template <int DIR>
; __device__ __forceinline__ void s5_local_dir(const bf16_t* UZ, unsigned char* ws, int gw, int NGW, int lane) {
;     float* E = (float*)(ws + WS_E);
;     const int pair = gw & 127, g = pair & 63, fr = lane & 15, fq = lane >> 4;
;     const bf16_t* Bb = (const bf16_t*)(ws + WS_BB) + (size_t)pair * 128 * 16;
;     bf16x4 Bre[4][4], Bim[4][4]; float a1r[4], a1i[4], a64r[4], a64i[4], wr_[4], wi_[4];
; #pragma unroll
;     for (int t = 0; t < 4; ++t) {
;         const int p = 16 * t + fr;
;         const bf16x4 b_re = *(const bf16x4*)(Bb + (2 * p) * 16 + 4 * fq), b_im = *(const bf16x4*)(Bb + (2 * p + 1) * 16 + 4 * fq);
;         const f32x4 ap = ((const f32x4*)(ws + WS_APOW))[pair * 64 + p];
;         const float ar = ap.x, ai = ap.y;
;         float r2 = ar, i2 = ai; cmul(r2, i2, ar, ai);
;         float r4 = r2, i4 = i2; cmul(r4, i4, r2, i2);
;         float r8 = r4, i8 = i4; cmul(r8, i8, r4, i4);
;         float r12 = r8, i12 = i8; cmul(r12, i12, r4, i4);
;         float r16 = r8, i16 = i8; cmul(r16, i16, r8, i8);
;         float r32 = r16, i32 = i16; cmul(r32, i32, r16, i16);
;         float r48 = r32, i48 = i32; cmul(r48, i48, r16, i16);
;         a1r[t] = ar; a1i[t] = ai; a64r[t] = ap.z; a64i[t] = ap.w;
;         const int e = DIR ? fq : 3 - fq;
;         wr_[t] = e == 0 ? 1.f : e == 1 ? r4 : e == 2 ? r8 : r12; wi_[t] = e == 0 ? 0.f : e == 1 ? i4 : e == 2 ? i8 : i12;
; #pragma unroll
;         for (int m = 0; m < 4; ++m) {
;             const int em = DIR ? m : 3 - m;
;             const float pr = em == 0 ? 1.f : em == 1 ? r16 : em == 2 ? r32 : r48, pi = em == 0 ? 0.f : em == 1 ? i16 : em == 2 ? i32 : i48;
;             Bre[m][t] = cscale_bf(b_re, b_im, pr, pi, false); Bim[m][t] = cscale_bf(b_re, b_im, pr, pi, true);
;         }
;     }
;     const int qd = gw >> 7, b = qd >> 2, q = qd & 3;
;     if (qd >= 16) return;
;     const int c0 = 17 * q, c1 = q < 3 ? c0 + 17 : 67;
;     float Rr[4] = {0.f, 0.f, 0.f, 0.f}, Ri[4] = {0.f, 0.f, 0.f, 0.f};
;     float* ebase = E + ((size_t)((b * 2 + DIR) * 64 + g) * NCHUNK) * 128;
;     bf16x4 Un[4];
;     load_uf(Un, UZ, chunk_rowbase(b, DIR, c0), g, lane);
;     for (int c = c0; c < c1; ++c) {
;         bf16x4 Uf[4];
; #pragma unroll
;         for (int m = 0; m < 4; ++m) Uf[m] = Un[m];
;         if (c + 1 < c1) load_uf(Un, UZ, chunk_rowbase(b, DIR, c + 1), g, lane);
.LBB0_644:
	s_cmp_lt_i32 s68, 8
	s_cselect_b64 s[0:1], -1, 0
	s_and_b64 s[0:1], s[0:1], s[2:3]
	s_andn2_b64 vcc, exec, s[0:1]
	s_cbranch_vccnz .LBB0_690
	v_readfirstlane_b32 s2, v192
	s_lshr_b32 s40, s2, 6
	s_lshl_b32 s2, s12, 3
	s_add_i32 s40, s40, s2
	s_and_b32 s2, s40, 64
	s_add_u32 s41, s30, 0x100000
	s_addc_u32 s42, s31, 0
	s_add_u32 s4, s30, 0x80000
	s_addc_u32 s5, s31, 0
	v_and_b32_e32 v127, 15, v192
	v_bfe_u32 v128, v192, 4, 2
	v_and_b32_e32 v126, 63, v192
	s_cmp_eq_u32 s2, 0
	v_lshlrev_b32_e32 v129, 2, v128
	v_lshlrev_b32_e32 v130, 5, v127
	s_cbranch_scc1 .LBB0_662
	s_ashr_i32 s2, s40, 7
	s_cmp_lt_i32 s2, 16
	s_mov_b64 s[22:23], 0
	s_cbranch_scc0 .LBB0_663
	s_and_b32 s43, s2, 3
	s_mul_i32 s38, s43, 17
	s_ashr_i32 s36, s40, 9
	s_and_b32 s44, s40, 63
	s_add_i32 s37, s38, 17
	s_cmp_lg_u32 s43, 3
	s_cselect_b64 s[24:25], -1, 0
	s_and_b64 s[2:3], s[24:25], exec
	s_cselect_b32 s46, s37, 0x43
	s_lshl_b32 s45, s36, 7
	v_cmp_gt_u32_e64 s[8:9], 16, v126
	v_mov_b32_e32 v115, 0
	v_mov_b32_e32 v240, 0
	v_mov_b32_e32 v241, 0
	s_cmp_ge_u32 s38, s46
	v_mov_b32_e32 v114, 0
	v_mov_b32_e32 v112, 0
	v_mov_b32_e32 v110, 0
	v_mov_b32_e32 v113, 0
	v_mov_b32_e32 v111, 0
	v_mov_b32_e32 v109, 0
	v_mov_b32_e32 v108, 0
	s_cbranch_scc1 .LBB0_684
	s_and_b32 s37, s40, 0x7f
	s_lshl_b32 s2, s37, 12
	s_add_u32 s2, s41, s2
	s_addc_u32 s3, s42, 0
	s_lshl_b32 s37, s37, 6
	s_waitcnt vmcnt(0)
	v_or_b32_e32 v0, s37, v127
	v_lshlrev_b32_e32 v0, 4, v0
	global_load_dwordx4 v[0:3], v0, s[4:5]
	v_lshlrev_b32_e32 v16, 1, v130
	v_mov_b32_e32 v17, 0
	v_lshl_add_u64 v[4:5], s[2:3], 0, v[16:17]
	v_lshlrev_b32_e32 v16, 1, v129
	v_lshl_add_u64 v[4:5], v[4:5], 0, v[16:17]
	global_load_dwordx2 v[22:23], v[4:5], off
	global_load_dwordx2 v[26:27], v[4:5], off offset:32
	v_or_b32_e32 v10, 16, v127
	v_or_b32_e32 v11, 32, v127
	v_or_b32_e32 v12, 48, v126
	v_lshlrev_b32_e32 v4, 6, v10
	v_mov_b32_e32 v5, v17
	v_lshlrev_b32_e32 v6, 6, v11
	v_mov_b32_e32 v7, v17
	v_lshlrev_b32_e32 v8, 6, v12
	v_mov_b32_e32 v9, v17
	v_lshl_add_u64 v[4:5], s[2:3], 0, v[4:5]
	v_lshrrev_b32_e32 v13, 1, v192
	v_or_b32_e32 v10, s37, v10
	v_lshl_add_u64 v[6:7], s[2:3], 0, v[6:7]
	v_or_b32_e32 v11, s37, v11
	v_lshl_add_u64 v[8:9], s[2:3], 0, v[8:9]
	v_or_b32_e32 v12, s37, v12
	v_lshl_add_u64 v[18:19], v[4:5], 0, v[16:17]
	v_lshlrev_b32_e32 v28, 4, v10
	v_lshl_add_u64 v[20:21], v[6:7], 0, v[16:17]
	v_lshlrev_b32_e32 v29, 4, v11
	v_lshl_add_u64 v[24:25], v[8:9], 0, v[16:17]
	v_lshlrev_b32_e32 v30, 4, v12
	v_and_b32_e32 v16, 24, v13
	global_load_dwordx2 v[50:51], v[18:19], off
	global_load_dwordx2 v[48:49], v[18:19], off offset:32
	global_load_dwordx4 v[4:7], v28, s[4:5]
	global_load_dwordx2 v[72:73], v[20:21], off
	global_load_dwordx2 v[70:71], v[20:21], off offset:32
	global_load_dwordx4 v[8:11], v29, s[4:5]
	global_load_dwordx2 v[94:95], v[24:25], off
	global_load_dwordx2 v[92:93], v[24:25], off offset:32
	global_load_dwordx4 v[12:15], v30, s[4:5]
	s_lshl_b32 s98, s36, 8
	s_addk_i32 s98, 0x40c0
	s_lshl_b32 s99, s36, 12
	s_addk_i32 s99, 0x10c0
	s_cmp_eq_u32 s43, 0
	s_cselect_b32 s98, s98, s99
	s_mul_i32 s99, s43, 0xfffffbc0
	s_lshl_b32 s100, s44, 5
	s_add_u32 s100, s18, s100
	s_addc_u32 s101, s19, 0
	v_or_b32_e32 v160, s99, v127
	v_add_u32_e32 v160, s98, v160
	v_ashrrev_i32_e32 v161, 31, v160
	v_lshlrev_b64 v[162:163], 12, v[160:161]
	v_lshrrev_b32_e32 v164, 1, v192
	v_and_b32_e32 v164, 24, v164
	v_mov_b32_e32 v165, 0
	v_lshl_add_u64 v[162:163], s[100:101], 0, v[162:163]
	v_lshl_add_u64 v[162:163], v[162:163], 0, v[164:165]
	s_mov_b32 s98, 0x10000
	s_mov_b32 s99, 0
	v_lshl_add_u64 v[164:165], v[162:163], 0, s[98:99]
	v_lshl_add_u64 v[166:167], v[164:165], 0, s[98:99]
	v_lshl_add_u64 v[168:169], v[166:167], 0, s[98:99]
	global_load_dwordx2 v[152:153], v[162:163], off
	global_load_dwordx2 v[154:155], v[164:165], off
	global_load_dwordx2 v[156:157], v[166:167], off
	global_load_dwordx2 v[158:159], v[168:169], off
	s_lshl_b32 s39, s44, 5
	s_add_u32 s2, s18, s39
	s_addc_u32 s3, s19, 0
	v_cmp_eq_u32_e32 vcc, 2, v128
	v_lshl_add_u64 v[18:19], s[2:3], 0, v[16:17]
	v_cmp_eq_u32_e64 s[2:3], 1, v128
	s_mov_b32 s37, 0x5040100
	s_lshl_b32 s47, s36, 8
	s_lshl_b32 s48, s36, 12
	s_addk_i32 s47, 0x40c0
	s_addk_i32 s48, 0x10c0
	s_cmp_eq_u32 s43, 0
	s_waitcnt vmcnt(15)
	v_pk_mul_f32 v[24:25], v[0:1], v[0:1] op_sel:[1,1] op_sel_hi:[1,0]
	s_nop 0
	v_pk_fma_f32 v[28:29], v[0:1], v[0:1], v[24:25] op_sel_hi:[1,0,1] neg_lo:[0,0,1] neg_hi:[0,0,1]
	v_pk_fma_f32 v[24:25], v[0:1], v[0:1], v[24:25] op_sel_hi:[1,0,1]
	v_mov_b32_e32 v30, v28
	v_pk_mov_b32 v[32:33], v[24:25], v[28:29] op_sel:[1,0]
	v_mov_b32_e32 v31, v25
	v_pk_mul_f32 v[24:25], v[24:25], v[32:33] op_sel:[1,0]
	v_mov_b32_e32 v20, v0
	v_pk_fma_f32 v[32:33], v[28:29], v[30:31], v[24:25] op_sel_hi:[0,1,1] neg_lo:[0,0,1] neg_hi:[0,0,1]
	v_pk_fma_f32 v[24:25], v[28:29], v[30:31], v[24:25] op_sel_hi:[0,1,1]
	v_pk_mov_b32 v[30:31], v[24:25], v[32:33] op_sel:[1,0]
	v_mov_b32_e32 v28, v32
	v_mov_b32_e32 v29, v25
	v_pk_mul_f32 v[30:31], v[24:25], v[30:31] op_sel:[1,0]
	v_mov_b32_e32 v21, v0
	v_pk_fma_f32 v[34:35], v[32:33], v[28:29], v[30:31] op_sel_hi:[0,1,1] neg_lo:[0,0,1] neg_hi:[0,0,1]
	v_pk_fma_f32 v[30:31], v[32:33], v[28:29], v[30:31] op_sel_hi:[0,1,1]
	v_pk_mov_b32 v[38:39], v[30:31], v[34:35] op_sel:[1,0]
	v_mov_b32_e32 v36, v34
	v_mov_b32_e32 v37, v31
	v_pk_mul_f32 v[38:39], v[30:31], v[38:39] op_sel:[1,0]
	v_mul_f32_e32 v0, v25, v34
	v_pk_mul_f32 v[28:29], v[28:29], v[36:37]
	v_pk_fma_f32 v[44:45], v[34:35], v[36:37], v[38:39] op_sel_hi:[0,1,1] neg_lo:[0,0,1] neg_hi:[0,0,1]
	v_pk_fma_f32 v[36:37], v[34:35], v[36:37], v[38:39] op_sel_hi:[0,1,1]
	v_fmac_f32_e32 v0, v32, v31
	v_pk_mov_b32 v[38:39], v[36:37], v[44:45] op_sel:[1,0]
	v_sub_f32_e32 v16, v28, v29
	v_mov_b32_e32 v28, v44
	v_mov_b32_e32 v29, v37
	v_cndmask_b32_e32 v0, v0, v31, vcc
	v_pk_mul_f32 v[30:31], v[36:37], v[38:39] op_sel:[1,0]
	v_cndmask_b32_e64 v0, v0, v25, s[2:3]
	v_pk_fma_f32 v[46:47], v[44:45], v[28:29], v[30:31] op_sel_hi:[0,1,1] neg_lo:[0,0,1] neg_hi:[0,0,1]
	v_pk_fma_f32 v[52:53], v[44:45], v[28:29], v[30:31] op_sel_hi:[0,1,1]
	s_waitcnt vmcnt(13)
; template <int DIR>
; __device__ __forceinline__ void s5_local_dir(const bf16_t* UZ, unsigned char* ws, int gw, int NGW, int lane) {
;     ...
;     for (int t = 0; t < 4; ++t) {
;         const int p = 16 * t + fr;
;         const bf16x4 b_re = *(const bf16x4*)(Bb + (2 * p) * 16 + 4 * fq), b_im = *(const bf16x4*)(Bb + (2 * p + 1) * 16 + 4 * fq);
;         const f32x4 ap = ((const f32x4*)(ws + WS_APOW))[pair * 64 + p];
;         const float ar = ap.x, ai = ap.y;
;         float r2 = ar, i2 = ai; cmul(r2, i2, ar, ai);
;         float r4 = r2, i4 = i2; cmul(r4, i4, r2, i2);
;         float r8 = r4, i8 = i4; cmul(r8, i8, r4, i4);
;         float r12 = r8, i12 = i8; cmul(r12, i12, r4, i4);
;         float r16 = r8, i16 = i8; cmul(r16, i16, r8, i8);
;         float r32 = r16, i32 = i16; cmul(r32, i32, r16, i16);
;         float r48 = r32, i48 = i32; cmul(r48, i48, r16, i16);
;         a1r[t] = ar; a1i[t] = ai; a64r[t] = ap.z; a64i[t] = ap.w;
;         const int e = DIR ? fq : 3 - fq;
;         wr_[t] = e == 0 ? 1.f : e == 1 ? r4 : e == 2 ? r8 : r12; wi_[t] = e == 0 ? 0.f : e == 1 ? i4 : e == 2 ? i8 : i12;
; #pragma unroll
;         for (int m = 0; m < 4; ++m) {
;             const int em = DIR ? m : 3 - m;
;             const float pr = em == 0 ? 1.f : em == 1 ? r16 : em == 2 ? r32 : r48, pi = em == 0 ? 0.f : em == 1 ? i16 : em == 2 ? i32 : i48;
;             Bre[m][t] = cscale_bf(b_re, b_im, pr, pi, false); Bim[m][t] = cscale_bf(b_re, b_im, pr, pi, true);
;         }
	v_and_b32_e32 v43, 0xffff0000, v26
	v_lshlrev_b32_e32 v42, 16, v26
	v_cndmask_b32_e32 v16, v16, v34, vcc
	v_cndmask_b32_e64 v25, v0, 0, s[8:9]
	v_mov_b32_e32 v30, v46
	v_mov_b32_e32 v31, v53
	v_mul_f32_e32 v0, v37, v53
	v_and_b32_e32 v61, 0xffff0000, v27
	v_lshlrev_b32_e32 v60, 16, v27
	v_and_b32_e32 v41, 0xffff0000, v22
	v_lshlrev_b32_e32 v40, 16, v22
	v_cndmask_b32_e64 v16, v16, v32, s[2:3]
	v_pk_fma_f32 v[54:55], v[28:29], v[30:31], v[0:1] op_sel_hi:[1,1,0] neg_lo:[0,0,1] neg_hi:[0,0,1]
	v_and_b32_e32 v59, 0xffff0000, v23
	v_lshlrev_b32_e32 v58, 16, v23
	v_xor_b32_e32 v27, 0x80000000, v61
	v_xor_b32_e32 v26, 0x80000000, v60
	v_xor_b32_e32 v29, 0x80000000, v43
	v_xor_b32_e32 v28, 0x80000000, v42
	v_cndmask_b32_e64 v22, v16, 1.0, s[8:9]
	v_mul_f32_e32 v16, v44, v53
	v_pk_fma_f32 v[26:27], v[26:27], 0, v[58:59] op_sel_hi:[1,0,1]
	v_pk_fma_f32 v[28:29], v[28:29], 0, v[40:41] op_sel_hi:[1,0,1]
	v_pk_fma_f32 v[56:57], v[38:39], v[30:31], v[16:17] op_sel_hi:[1,1,0]
	v_cvt_pk_bf16_f32 v0, v28, s0
	v_cvt_pk_bf16_f32 v16, v29, s0
	v_cvt_pk_bf16_f32 v23, v26, s0
	v_cvt_pk_bf16_f32 v24, v27, s0
	v_pk_fma_f32 v[28:29], v[58:59], 0, v[60:61] op_sel_hi:[1,0,1]
	v_pk_fma_f32 v[30:31], v[40:41], 0, v[42:43] op_sel_hi:[1,0,1]
	v_pk_mul_f32 v[32:33], v[36:37], v[60:61] op_sel:[1,0]
	v_perm_b32 v27, v24, v23, s37
	v_perm_b32 v26, v16, v0, s37
	v_cvt_pk_bf16_f32 v0, v30, s0
	v_cvt_pk_bf16_f32 v16, v31, s0
	v_cvt_pk_bf16_f32 v23, v28, s0
	v_cvt_pk_bf16_f32 v24, v29, s0
	v_pk_mul_f32 v[30:31], v[36:37], v[42:43] op_sel:[1,0]
	v_pk_fma_f32 v[32:33], v[44:45], v[58:59], v[32:33] op_sel_hi:[0,1,1] neg_lo:[0,0,1] neg_hi:[0,0,1]
	v_pk_mul_f32 v[34:35], v[36:37], v[58:59] op_sel:[1,0]
	v_perm_b32 v29, v24, v23, s37
	v_pk_fma_f32 v[30:31], v[44:45], v[40:41], v[30:31] op_sel_hi:[0,1,1] neg_lo:[0,0,1] neg_hi:[0,0,1]
	v_cvt_pk_bf16_f32 v23, v32, s0
	v_cvt_pk_bf16_f32 v24, v33, s0
	v_pk_mul_f32 v[32:33], v[36:37], v[40:41] op_sel:[1,0]
	v_pk_fma_f32 v[34:35], v[44:45], v[60:61], v[34:35] op_sel_hi:[0,1,1]
	v_pk_mul_f32 v[36:37], v[52:53], v[60:61] op_sel:[1,0]
	v_perm_b32 v28, v16, v0, s37
	v_cvt_pk_bf16_f32 v0, v30, s0
	v_cvt_pk_bf16_f32 v16, v31, s0
	v_perm_b32 v31, v24, v23, s37
	v_pk_fma_f32 v[32:33], v[44:45], v[42:43], v[32:33] op_sel_hi:[0,1,1]
	v_cvt_pk_bf16_f32 v23, v34, s0
	v_cvt_pk_bf16_f32 v24, v35, s0
	v_pk_mul_f32 v[34:35], v[52:53], v[42:43] op_sel:[1,0]
	v_pk_fma_f32 v[36:37], v[46:47], v[58:59], v[36:37] op_sel_hi:[0,1,1] neg_lo:[0,0,1] neg_hi:[0,0,1]
	v_pk_mul_f32 v[38:39], v[52:53], v[58:59] op_sel:[1,0]
	v_perm_b32 v30, v16, v0, s37
	v_cvt_pk_bf16_f32 v0, v32, s0
	v_cvt_pk_bf16_f32 v16, v33, s0
	v_perm_b32 v33, v24, v23, s37
	v_pk_fma_f32 v[34:35], v[46:47], v[40:41], v[34:35] op_sel_hi:[0,1,1] neg_lo:[0,0,1] neg_hi:[0,0,1]
	v_cvt_pk_bf16_f32 v23, v36, s0
	v_cvt_pk_bf16_f32 v24, v37, s0
	v_pk_mul_f32 v[36:37], v[52:53], v[40:41] op_sel:[1,0]
	v_pk_fma_f32 v[38:39], v[46:47], v[60:61], v[38:39] op_sel_hi:[0,1,1]
	v_pk_mul_f32 v[44:45], v[56:57], v[60:61] op_sel_hi:[0,1]
	v_perm_b32 v32, v16, v0, s37
	v_cvt_pk_bf16_f32 v0, v34, s0
	v_cvt_pk_bf16_f32 v16, v35, s0
	v_perm_b32 v35, v24, v23, s37
	v_pk_fma_f32 v[36:37], v[46:47], v[42:43], v[36:37] op_sel_hi:[0,1,1]
	v_cvt_pk_bf16_f32 v23, v38, s0
	v_cvt_pk_bf16_f32 v24, v39, s0
	v_pk_fma_f32 v[44:45], v[54:55], v[58:59], v[44:45] op_sel_hi:[0,1,1] neg_lo:[0,0,1] neg_hi:[0,0,1]
	v_perm_b32 v34, v16, v0, s37
	v_cvt_pk_bf16_f32 v16, v37, s0
	v_perm_b32 v37, v24, v23, s37
	v_pk_mul_f32 v[38:39], v[56:57], v[42:43] op_sel_hi:[0,1]
	v_cvt_pk_bf16_f32 v23, v44, s0
	v_cvt_pk_bf16_f32 v24, v45, s0
	v_pk_mul_f32 v[44:45], v[56:57], v[58:59] op_sel_hi:[0,1]
	v_cvt_pk_bf16_f32 v0, v36, s0
	v_pk_fma_f32 v[38:39], v[54:55], v[40:41], v[38:39] op_sel_hi:[0,1,1] neg_lo:[0,0,1] neg_hi:[0,0,1]
	v_pk_fma_f32 v[44:45], v[54:55], v[60:61], v[44:45] op_sel_hi:[0,1,1]
	v_perm_b32 v36, v16, v0, s37
	v_cvt_pk_bf16_f32 v16, v39, s0
	v_perm_b32 v39, v24, v23, s37
	v_cvt_pk_bf16_f32 v23, v44, s0
	v_cvt_pk_bf16_f32 v24, v45, s0
	s_waitcnt vmcnt(10)
	v_pk_mul_f32 v[44:45], v[4:5], v[4:5] op_sel:[1,1] op_sel_hi:[1,0]
	v_pk_mul_f32 v[40:41], v[56:57], v[40:41] op_sel_hi:[0,1]
	v_pk_fma_f32 v[46:47], v[4:5], v[4:5], v[44:45] op_sel_hi:[1,0,1] neg_lo:[0,0,1] neg_hi:[0,0,1]
	v_pk_fma_f32 v[44:45], v[4:5], v[4:5], v[44:45] op_sel_hi:[1,0,1]
	v_pk_fma_f32 v[40:41], v[54:55], v[42:43], v[40:41] op_sel_hi:[0,1,1]
	v_pk_mov_b32 v[54:55], v[44:45], v[46:47] op_sel:[1,0]
	v_mov_b32_e32 v52, v46
	v_mov_b32_e32 v53, v45
	v_pk_mul_f32 v[44:45], v[44:45], v[54:55] op_sel:[1,0]
	v_cvt_pk_bf16_f32 v0, v38, s0
	v_pk_fma_f32 v[54:55], v[46:47], v[52:53], v[44:45] op_sel_hi:[0,1,1] neg_lo:[0,0,1] neg_hi:[0,0,1]
	v_pk_fma_f32 v[44:45], v[46:47], v[52:53], v[44:45] op_sel_hi:[0,1,1]
	v_pk_mov_b32 v[52:53], v[44:45], v[54:55] op_sel:[1,0]
	v_mov_b32_e32 v46, v54
	v_mov_b32_e32 v47, v45
	v_pk_mul_f32 v[52:53], v[44:45], v[52:53] op_sel:[1,0]
	v_perm_b32 v38, v16, v0, s37
	v_pk_fma_f32 v[56:57], v[54:55], v[46:47], v[52:53] op_sel_hi:[0,1,1] neg_lo:[0,0,1] neg_hi:[0,0,1]
	v_pk_fma_f32 v[52:53], v[54:55], v[46:47], v[52:53] op_sel_hi:[0,1,1]
	v_pk_mov_b32 v[60:61], v[52:53], v[56:57] op_sel:[1,0]
	v_mov_b32_e32 v58, v56
	v_mov_b32_e32 v59, v53
	v_pk_mul_f32 v[60:61], v[52:53], v[60:61] op_sel:[1,0]
	v_cvt_pk_bf16_f32 v0, v40, s0
	v_pk_fma_f32 v[62:63], v[56:57], v[58:59], v[60:61] op_sel_hi:[0,1,1] neg_lo:[0,0,1] neg_hi:[0,0,1]
	v_pk_fma_f32 v[60:61], v[56:57], v[58:59], v[60:61] op_sel_hi:[0,1,1]
	v_pk_mov_b32 v[66:67], v[60:61], v[62:63] op_sel:[1,0]
	v_mov_b32_e32 v64, v62
	v_mov_b32_e32 v65, v61
	v_pk_mul_f32 v[68:69], v[60:61], v[66:67] op_sel:[1,0]
; template <int DIR>
; __device__ __forceinline__ void s5_local_dir(const bf16_t* UZ, unsigned char* ws, int gw, int NGW, int lane) {
;     ...
;     for (int t = 0; t < 4; ++t) {
;         const int p = 16 * t + fr;
;         const bf16x4 b_re = *(const bf16x4*)(Bb + (2 * p) * 16 + 4 * fq), b_im = *(const bf16x4*)(Bb + (2 * p + 1) * 16 + 4 * fq);
;         const f32x4 ap = ((const f32x4*)(ws + WS_APOW))[pair * 64 + p];
;         const float ar = ap.x, ai = ap.y;
;         float r2 = ar, i2 = ai; cmul(r2, i2, ar, ai);
;         float r4 = r2, i4 = i2; cmul(r4, i4, r2, i2);
;         float r8 = r4, i8 = i4; cmul(r8, i8, r4, i4);
;         float r12 = r8, i12 = i8; cmul(r12, i12, r4, i4);
;         float r16 = r8, i16 = i8; cmul(r16, i16, r8, i8);
;         float r32 = r16, i32 = i16; cmul(r32, i32, r16, i16);
;         float r48 = r32, i48 = i32; cmul(r48, i48, r16, i16);
;         a1r[t] = ar; a1i[t] = ai; a64r[t] = ap.z; a64i[t] = ap.w;
;         const int e = DIR ? fq : 3 - fq;
;         wr_[t] = e == 0 ? 1.f : e == 1 ? r4 : e == 2 ? r8 : r12; wi_[t] = e == 0 ? 0.f : e == 1 ? i4 : e == 2 ? i8 : i12;
; #pragma unroll
;         for (int m = 0; m < 4; ++m) {
;             const int em = DIR ? m : 3 - m;
;             const float pr = em == 0 ? 1.f : em == 1 ? r16 : em == 2 ? r32 : r48, pi = em == 0 ? 0.f : em == 1 ? i16 : em == 2 ? i32 : i48;
;             Bre[m][t] = cscale_bf(b_re, b_im, pr, pi, false); Bim[m][t] = cscale_bf(b_re, b_im, pr, pi, true);
;         }
	v_cvt_pk_bf16_f32 v16, v41, s0
	v_pk_fma_f32 v[74:75], v[62:63], v[64:65], v[68:69] op_sel_hi:[0,1,1] neg_lo:[0,0,1] neg_hi:[0,0,1]
	v_pk_fma_f32 v[68:69], v[62:63], v[64:65], v[68:69] op_sel_hi:[0,1,1]
	v_perm_b32 v40, v16, v0, s37
	v_mov_b32_e32 v76, v74
	v_mov_b32_e32 v77, v69
	v_mul_f32_e32 v0, v61, v69
	v_pk_fma_f32 v[64:65], v[64:65], v[76:77], v[0:1] op_sel_hi:[1,1,0] neg_lo:[0,0,1] neg_hi:[0,0,1]
	v_mul_f32_e32 v0, v62, v69
	v_pk_fma_f32 v[66:67], v[66:67], v[76:77], v[0:1] op_sel_hi:[1,1,0]
	v_mul_f32_e32 v0, v45, v56
	v_pk_mul_f32 v[46:47], v[46:47], v[58:59]
	v_mov_b32_e32 v42, v4
	v_mov_b32_e32 v43, v4
	v_fmac_f32_e32 v0, v54, v53
	v_sub_f32_e32 v4, v46, v47
	v_and_b32_e32 v79, 0xffff0000, v48
	v_lshlrev_b32_e32 v78, 16, v48
	v_and_b32_e32 v83, 0xffff0000, v49
	v_lshlrev_b32_e32 v82, 16, v49
	v_cndmask_b32_e32 v4, v4, v56, vcc
	v_cndmask_b32_e32 v0, v0, v53, vcc
	v_and_b32_e32 v77, 0xffff0000, v50
	v_lshlrev_b32_e32 v76, 16, v50
	v_and_b32_e32 v81, 0xffff0000, v51
	v_lshlrev_b32_e32 v80, 16, v51
	v_xor_b32_e32 v49, 0x80000000, v83
	v_xor_b32_e32 v48, 0x80000000, v82
	v_xor_b32_e32 v51, 0x80000000, v79
	v_xor_b32_e32 v50, 0x80000000, v78
	v_cndmask_b32_e64 v4, v4, v54, s[2:3]
	v_cndmask_b32_e64 v0, v0, v45, s[2:3]
	v_pk_fma_f32 v[48:49], v[48:49], 0, v[80:81] op_sel_hi:[1,0,1]
	v_pk_fma_f32 v[50:51], v[50:51], 0, v[76:77] op_sel_hi:[1,0,1]
	v_perm_b32 v41, v24, v23, s37
	v_cndmask_b32_e64 v44, v4, 1.0, s[8:9]
	v_cndmask_b32_e64 v47, v0, 0, s[8:9]
	v_cvt_pk_bf16_f32 v0, v50, s0
	v_cvt_pk_bf16_f32 v4, v51, s0
	v_cvt_pk_bf16_f32 v16, v48, s0
	v_cvt_pk_bf16_f32 v23, v49, s0
	v_pk_fma_f32 v[50:51], v[80:81], 0, v[82:83] op_sel_hi:[1,0,1]
	v_pk_fma_f32 v[52:53], v[76:77], 0, v[78:79] op_sel_hi:[1,0,1]
	v_pk_mul_f32 v[54:55], v[60:61], v[82:83] op_sel:[1,0]
	v_perm_b32 v49, v23, v16, s37
	v_perm_b32 v48, v4, v0, s37
	v_cvt_pk_bf16_f32 v0, v52, s0
	v_cvt_pk_bf16_f32 v4, v53, s0
	v_cvt_pk_bf16_f32 v16, v50, s0
	v_cvt_pk_bf16_f32 v23, v51, s0
	v_pk_mul_f32 v[52:53], v[60:61], v[78:79] op_sel:[1,0]
	v_pk_fma_f32 v[54:55], v[62:63], v[80:81], v[54:55] op_sel_hi:[0,1,1] neg_lo:[0,0,1] neg_hi:[0,0,1]
	v_pk_mul_f32 v[56:57], v[60:61], v[80:81] op_sel:[1,0]
	v_perm_b32 v51, v23, v16, s37
	v_pk_fma_f32 v[52:53], v[62:63], v[76:77], v[52:53] op_sel_hi:[0,1,1] neg_lo:[0,0,1] neg_hi:[0,0,1]
	v_cvt_pk_bf16_f32 v16, v54, s0
	v_cvt_pk_bf16_f32 v23, v55, s0
	v_pk_mul_f32 v[54:55], v[60:61], v[76:77] op_sel:[1,0]
	v_pk_fma_f32 v[56:57], v[62:63], v[82:83], v[56:57] op_sel_hi:[0,1,1]
	v_pk_mul_f32 v[58:59], v[68:69], v[82:83] op_sel:[1,0]
	v_perm_b32 v50, v4, v0, s37
	v_cvt_pk_bf16_f32 v0, v52, s0
	v_cvt_pk_bf16_f32 v4, v53, s0
	v_perm_b32 v53, v23, v16, s37
	v_pk_fma_f32 v[54:55], v[62:63], v[78:79], v[54:55] op_sel_hi:[0,1,1]
	v_cvt_pk_bf16_f32 v16, v56, s0
	v_cvt_pk_bf16_f32 v23, v57, s0
	v_pk_mul_f32 v[56:57], v[68:69], v[78:79] op_sel:[1,0]
	v_pk_fma_f32 v[58:59], v[74:75], v[80:81], v[58:59] op_sel_hi:[0,1,1] neg_lo:[0,0,1] neg_hi:[0,0,1]
	v_pk_mul_f32 v[60:61], v[68:69], v[80:81] op_sel:[1,0]
	v_perm_b32 v52, v4, v0, s37
	v_cvt_pk_bf16_f32 v0, v54, s0
	v_cvt_pk_bf16_f32 v4, v55, s0
	v_perm_b32 v55, v23, v16, s37
	v_pk_fma_f32 v[56:57], v[74:75], v[76:77], v[56:57] op_sel_hi:[0,1,1] neg_lo:[0,0,1] neg_hi:[0,0,1]
	v_cvt_pk_bf16_f32 v16, v58, s0
	v_cvt_pk_bf16_f32 v23, v59, s0
	v_pk_mul_f32 v[58:59], v[68:69], v[76:77] op_sel:[1,0]
	v_pk_fma_f32 v[60:61], v[74:75], v[82:83], v[60:61] op_sel_hi:[0,1,1]
	v_pk_mul_f32 v[62:63], v[66:67], v[82:83] op_sel_hi:[0,1]
	v_perm_b32 v54, v4, v0, s37
	v_cvt_pk_bf16_f32 v0, v56, s0
	v_cvt_pk_bf16_f32 v4, v57, s0
	v_perm_b32 v57, v23, v16, s37
	v_pk_fma_f32 v[58:59], v[74:75], v[78:79], v[58:59] op_sel_hi:[0,1,1]
	v_cvt_pk_bf16_f32 v16, v60, s0
	v_cvt_pk_bf16_f32 v23, v61, s0
	v_pk_fma_f32 v[62:63], v[64:65], v[80:81], v[62:63] op_sel_hi:[0,1,1] neg_lo:[0,0,1] neg_hi:[0,0,1]
	v_perm_b32 v56, v4, v0, s37
	v_cvt_pk_bf16_f32 v4, v59, s0
	v_perm_b32 v59, v23, v16, s37
	v_pk_mul_f32 v[60:61], v[66:67], v[78:79] op_sel_hi:[0,1]
	v_cvt_pk_bf16_f32 v16, v62, s0
	v_cvt_pk_bf16_f32 v23, v63, s0
	v_pk_mul_f32 v[62:63], v[66:67], v[76:77] op_sel_hi:[0,1]
	v_pk_mul_f32 v[66:67], v[66:67], v[80:81] op_sel_hi:[0,1]
	v_cvt_pk_bf16_f32 v0, v58, s0
	v_pk_fma_f32 v[60:61], v[64:65], v[76:77], v[60:61] op_sel_hi:[0,1,1] neg_lo:[0,0,1] neg_hi:[0,0,1]
	v_pk_fma_f32 v[66:67], v[64:65], v[82:83], v[66:67] op_sel_hi:[0,1,1]
	v_perm_b32 v58, v4, v0, s37
	v_cvt_pk_bf16_f32 v4, v61, s0
	v_perm_b32 v61, v23, v16, s37
	v_cvt_pk_bf16_f32 v16, v66, s0
	v_cvt_pk_bf16_f32 v23, v67, s0
	s_waitcnt vmcnt(7)
; template <int DIR>
; __device__ __forceinline__ void s5_local_dir(const bf16_t* UZ, unsigned char* ws, int gw, int NGW, int lane) {
;     ...
;     for (int t = 0; t < 4; ++t) {
;         const int p = 16 * t + fr;
;         const bf16x4 b_re = *(const bf16x4*)(Bb + (2 * p) * 16 + 4 * fq), b_im = *(const bf16x4*)(Bb + (2 * p + 1) * 16 + 4 * fq);
;         const f32x4 ap = ((const f32x4*)(ws + WS_APOW))[pair * 64 + p];
;         const float ar = ap.x, ai = ap.y;
;         float r2 = ar, i2 = ai; cmul(r2, i2, ar, ai);
;         float r4 = r2, i4 = i2; cmul(r4, i4, r2, i2);
;         float r8 = r4, i8 = i4; cmul(r8, i8, r4, i4);
;         float r12 = r8, i12 = i8; cmul(r12, i12, r4, i4);
;         float r16 = r8, i16 = i8; cmul(r16, i16, r8, i8);
;         float r32 = r16, i32 = i16; cmul(r32, i32, r16, i16);
;         float r48 = r32, i48 = i32; cmul(r48, i48, r16, i16);
;         a1r[t] = ar; a1i[t] = ai; a64r[t] = ap.z; a64i[t] = ap.w;
;         const int e = DIR ? fq : 3 - fq;
;         wr_[t] = e == 0 ? 1.f : e == 1 ? r4 : e == 2 ? r8 : r12; wi_[t] = e == 0 ? 0.f : e == 1 ? i4 : e == 2 ? i8 : i12;
; #pragma unroll
;         for (int m = 0; m < 4; ++m) {
;             const int em = DIR ? m : 3 - m;
;             const float pr = em == 0 ? 1.f : em == 1 ? r16 : em == 2 ? r32 : r48, pi = em == 0 ? 0.f : em == 1 ? i16 : em == 2 ? i32 : i48;
;             Bre[m][t] = cscale_bf(b_re, b_im, pr, pi, false); Bim[m][t] = cscale_bf(b_re, b_im, pr, pi, true);
;         }
	v_pk_mul_f32 v[66:67], v[8:9], v[8:9] op_sel:[1,1] op_sel_hi:[1,0]
	v_pk_fma_f32 v[62:63], v[64:65], v[78:79], v[62:63] op_sel_hi:[0,1,1]
	v_pk_fma_f32 v[68:69], v[8:9], v[8:9], v[66:67] op_sel_hi:[1,0,1] neg_lo:[0,0,1] neg_hi:[0,0,1]
	v_pk_fma_f32 v[66:67], v[8:9], v[8:9], v[66:67] op_sel_hi:[1,0,1]
	v_mov_b32_e32 v74, v68
	v_pk_mov_b32 v[76:77], v[66:67], v[68:69] op_sel:[1,0]
	v_mov_b32_e32 v75, v67
	v_pk_mul_f32 v[66:67], v[66:67], v[76:77] op_sel:[1,0]
	v_cvt_pk_bf16_f32 v0, v60, s0
	v_pk_fma_f32 v[76:77], v[68:69], v[74:75], v[66:67] op_sel_hi:[0,1,1] neg_lo:[0,0,1] neg_hi:[0,0,1]
	v_pk_fma_f32 v[66:67], v[68:69], v[74:75], v[66:67] op_sel_hi:[0,1,1]
	v_pk_mov_b32 v[74:75], v[66:67], v[76:77] op_sel:[1,0]
	v_mov_b32_e32 v68, v76
	v_mov_b32_e32 v69, v67
	v_pk_mul_f32 v[74:75], v[66:67], v[74:75] op_sel:[1,0]
	v_perm_b32 v60, v4, v0, s37
	v_pk_fma_f32 v[78:79], v[76:77], v[68:69], v[74:75] op_sel_hi:[0,1,1] neg_lo:[0,0,1] neg_hi:[0,0,1]
	v_pk_fma_f32 v[74:75], v[76:77], v[68:69], v[74:75] op_sel_hi:[0,1,1]
	v_pk_mov_b32 v[82:83], v[74:75], v[78:79] op_sel:[1,0]
	v_mov_b32_e32 v80, v78
	v_mov_b32_e32 v81, v75
	v_pk_mul_f32 v[82:83], v[74:75], v[82:83] op_sel:[1,0]
	v_cvt_pk_bf16_f32 v0, v62, s0
	v_pk_fma_f32 v[84:85], v[78:79], v[80:81], v[82:83] op_sel_hi:[0,1,1] neg_lo:[0,0,1] neg_hi:[0,0,1]
	v_pk_fma_f32 v[82:83], v[78:79], v[80:81], v[82:83] op_sel_hi:[0,1,1]
	v_pk_mov_b32 v[88:89], v[82:83], v[84:85] op_sel:[1,0]
	v_mov_b32_e32 v86, v84
	v_mov_b32_e32 v87, v83
	v_pk_mul_f32 v[90:91], v[82:83], v[88:89] op_sel:[1,0]
	v_cvt_pk_bf16_f32 v4, v63, s0
	v_pk_fma_f32 v[96:97], v[84:85], v[86:87], v[90:91] op_sel_hi:[0,1,1] neg_lo:[0,0,1] neg_hi:[0,0,1]
	v_pk_fma_f32 v[90:91], v[84:85], v[86:87], v[90:91] op_sel_hi:[0,1,1]
	v_perm_b32 v62, v4, v0, s37
	v_mov_b32_e32 v98, v96
	v_mov_b32_e32 v99, v91
	v_mul_f32_e32 v0, v83, v91
	v_pk_fma_f32 v[86:87], v[86:87], v[98:99], v[0:1] op_sel_hi:[1,1,0] neg_lo:[0,0,1] neg_hi:[0,0,1]
	v_mul_f32_e32 v0, v84, v91
	v_pk_fma_f32 v[88:89], v[88:89], v[98:99], v[0:1] op_sel_hi:[1,1,0]
	v_mul_f32_e32 v0, v67, v78
	v_pk_mul_f32 v[68:69], v[68:69], v[80:81]
	v_fmac_f32_e32 v0, v76, v75
	v_sub_f32_e32 v4, v68, v69
	v_and_b32_e32 v101, 0xffff0000, v70
	v_lshlrev_b32_e32 v100, 16, v70
	v_and_b32_e32 v105, 0xffff0000, v71
	v_lshlrev_b32_e32 v104, 16, v71
	v_cndmask_b32_e32 v4, v4, v78, vcc
	v_cndmask_b32_e32 v0, v0, v75, vcc
	v_and_b32_e32 v99, 0xffff0000, v72
	v_lshlrev_b32_e32 v98, 16, v72
	v_and_b32_e32 v103, 0xffff0000, v73
	v_lshlrev_b32_e32 v102, 16, v73
	v_xor_b32_e32 v71, 0x80000000, v105
	v_xor_b32_e32 v70, 0x80000000, v104
	v_xor_b32_e32 v73, 0x80000000, v101
	v_xor_b32_e32 v72, 0x80000000, v100
	v_cndmask_b32_e64 v4, v4, v76, s[2:3]
	v_cndmask_b32_e64 v0, v0, v67, s[2:3]
	v_pk_fma_f32 v[70:71], v[70:71], 0, v[102:103] op_sel_hi:[1,0,1]
	v_pk_fma_f32 v[72:73], v[72:73], 0, v[98:99] op_sel_hi:[1,0,1]
	v_perm_b32 v63, v23, v16, s37
	v_mov_b32_e32 v64, v8
	v_mov_b32_e32 v65, v8
	v_cndmask_b32_e64 v66, v4, 1.0, s[8:9]
	v_cndmask_b32_e64 v69, v0, 0, s[8:9]
	v_cvt_pk_bf16_f32 v0, v72, s0
	v_cvt_pk_bf16_f32 v4, v73, s0
	v_cvt_pk_bf16_f32 v8, v70, s0
	v_cvt_pk_bf16_f32 v16, v71, s0
	v_pk_fma_f32 v[72:73], v[102:103], 0, v[104:105] op_sel_hi:[1,0,1]
	v_pk_fma_f32 v[74:75], v[98:99], 0, v[100:101] op_sel_hi:[1,0,1]
	v_pk_mul_f32 v[76:77], v[82:83], v[104:105] op_sel:[1,0]
	v_perm_b32 v71, v16, v8, s37
	v_perm_b32 v70, v4, v0, s37
	v_cvt_pk_bf16_f32 v0, v74, s0
	v_cvt_pk_bf16_f32 v4, v75, s0
	v_cvt_pk_bf16_f32 v8, v72, s0
	v_cvt_pk_bf16_f32 v16, v73, s0
	v_pk_mul_f32 v[74:75], v[82:83], v[100:101] op_sel:[1,0]
	v_pk_fma_f32 v[76:77], v[84:85], v[102:103], v[76:77] op_sel_hi:[0,1,1] neg_lo:[0,0,1] neg_hi:[0,0,1]
	v_pk_mul_f32 v[78:79], v[82:83], v[102:103] op_sel:[1,0]
	v_perm_b32 v73, v16, v8, s37
	v_pk_fma_f32 v[74:75], v[84:85], v[98:99], v[74:75] op_sel_hi:[0,1,1] neg_lo:[0,0,1] neg_hi:[0,0,1]
	v_cvt_pk_bf16_f32 v8, v76, s0
	v_cvt_pk_bf16_f32 v16, v77, s0
	v_pk_mul_f32 v[76:77], v[82:83], v[98:99] op_sel:[1,0]
	v_pk_fma_f32 v[78:79], v[84:85], v[104:105], v[78:79] op_sel_hi:[0,1,1]
	v_pk_mul_f32 v[80:81], v[90:91], v[104:105] op_sel:[1,0]
	v_perm_b32 v72, v4, v0, s37
	v_cvt_pk_bf16_f32 v0, v74, s0
	v_cvt_pk_bf16_f32 v4, v75, s0
	v_perm_b32 v75, v16, v8, s37
	v_pk_fma_f32 v[76:77], v[84:85], v[100:101], v[76:77] op_sel_hi:[0,1,1]
	v_cvt_pk_bf16_f32 v8, v78, s0
	v_cvt_pk_bf16_f32 v16, v79, s0
	v_pk_mul_f32 v[78:79], v[90:91], v[100:101] op_sel:[1,0]
	v_pk_fma_f32 v[80:81], v[96:97], v[102:103], v[80:81] op_sel_hi:[0,1,1] neg_lo:[0,0,1] neg_hi:[0,0,1]
	v_pk_mul_f32 v[82:83], v[90:91], v[102:103] op_sel:[1,0]
	v_perm_b32 v74, v4, v0, s37
	v_cvt_pk_bf16_f32 v0, v76, s0
	v_cvt_pk_bf16_f32 v4, v77, s0
	v_perm_b32 v77, v16, v8, s37
	v_pk_fma_f32 v[78:79], v[96:97], v[98:99], v[78:79] op_sel_hi:[0,1,1] neg_lo:[0,0,1] neg_hi:[0,0,1]
	v_cvt_pk_bf16_f32 v8, v80, s0
	v_cvt_pk_bf16_f32 v16, v81, s0
	v_pk_mul_f32 v[80:81], v[90:91], v[98:99] op_sel:[1,0]
	v_pk_fma_f32 v[82:83], v[96:97], v[104:105], v[82:83] op_sel_hi:[0,1,1]
	v_pk_mul_f32 v[84:85], v[88:89], v[104:105] op_sel_hi:[0,1]
	v_perm_b32 v76, v4, v0, s37
	v_cvt_pk_bf16_f32 v0, v78, s0
	v_cvt_pk_bf16_f32 v4, v79, s0
	v_perm_b32 v79, v16, v8, s37
	v_pk_fma_f32 v[80:81], v[96:97], v[100:101], v[80:81] op_sel_hi:[0,1,1]
	v_cvt_pk_bf16_f32 v8, v82, s0
	v_cvt_pk_bf16_f32 v16, v83, s0
	v_pk_fma_f32 v[84:85], v[86:87], v[102:103], v[84:85] op_sel_hi:[0,1,1] neg_lo:[0,0,1] neg_hi:[0,0,1]
	v_perm_b32 v78, v4, v0, s37
	v_cvt_pk_bf16_f32 v4, v81, s0
	v_perm_b32 v81, v16, v8, s37
	v_pk_mul_f32 v[82:83], v[88:89], v[100:101] op_sel_hi:[0,1]
	v_cvt_pk_bf16_f32 v8, v84, s0
	v_cvt_pk_bf16_f32 v16, v85, s0
	v_pk_mul_f32 v[84:85], v[88:89], v[98:99] op_sel_hi:[0,1]
	v_pk_mul_f32 v[88:89], v[88:89], v[102:103] op_sel_hi:[0,1]
	v_cvt_pk_bf16_f32 v0, v80, s0
	v_pk_fma_f32 v[82:83], v[86:87], v[98:99], v[82:83] op_sel_hi:[0,1,1] neg_lo:[0,0,1] neg_hi:[0,0,1]
	v_pk_fma_f32 v[88:89], v[86:87], v[104:105], v[88:89] op_sel_hi:[0,1,1]
	v_perm_b32 v80, v4, v0, s37
	v_cvt_pk_bf16_f32 v4, v83, s0
	v_perm_b32 v83, v16, v8, s37
	v_cvt_pk_bf16_f32 v8, v88, s0
	v_cvt_pk_bf16_f32 v16, v89, s0
	s_waitcnt vmcnt(4)
; __device__ __forceinline__ void load_uf(bf16x4 (&Uf)[4], const bf16_t* UZ, int rowbase, int g, int lane) {
; #pragma unroll
;     for (int m = 0; m < 4; ++m) Uf[m] = *(const bf16x4*)(UZ + (size_t)(rowbase + 16 * m + (lane & 15)) * NUZ + 16 * g + 4 * (lane >> 4));
; }
; template <int DIR>
; __device__ __forceinline__ void s5_local_dir(const bf16_t* UZ, unsigned char* ws, int gw, int NGW, int lane) {
;     ...
;     for (int t = 0; t < 4; ++t) {
;         const int p = 16 * t + fr;
;         const bf16x4 b_re = *(const bf16x4*)(Bb + (2 * p) * 16 + 4 * fq), b_im = *(const bf16x4*)(Bb + (2 * p + 1) * 16 + 4 * fq);
;         const f32x4 ap = ((const f32x4*)(ws + WS_APOW))[pair * 64 + p];
;         const float ar = ap.x, ai = ap.y;
;         float r2 = ar, i2 = ai; cmul(r2, i2, ar, ai);
;         float r4 = r2, i4 = i2; cmul(r4, i4, r2, i2);
;         float r8 = r4, i8 = i4; cmul(r8, i8, r4, i4);
;         float r12 = r8, i12 = i8; cmul(r12, i12, r4, i4);
;         float r16 = r8, i16 = i8; cmul(r16, i16, r8, i8);
;         float r32 = r16, i32 = i16; cmul(r32, i32, r16, i16);
;         float r48 = r32, i48 = i32; cmul(r48, i48, r16, i16);
;         a1r[t] = ar; a1i[t] = ai; a64r[t] = ap.z; a64i[t] = ap.w;
;         const int e = DIR ? fq : 3 - fq;
;         wr_[t] = e == 0 ? 1.f : e == 1 ? r4 : e == 2 ? r8 : r12; wi_[t] = e == 0 ? 0.f : e == 1 ? i4 : e == 2 ? i8 : i12;
; #pragma unroll
;         for (int m = 0; m < 4; ++m) {
;             const int em = DIR ? m : 3 - m;
;             const float pr = em == 0 ? 1.f : em == 1 ? r16 : em == 2 ? r32 : r48, pi = em == 0 ? 0.f : em == 1 ? i16 : em == 2 ? i32 : i48;
;             Bre[m][t] = cscale_bf(b_re, b_im, pr, pi, false); Bim[m][t] = cscale_bf(b_re, b_im, pr, pi, true);
;         }
	v_pk_mul_f32 v[88:89], v[12:13], v[12:13] op_sel:[1,1] op_sel_hi:[1,0]
	v_pk_fma_f32 v[84:85], v[86:87], v[100:101], v[84:85] op_sel_hi:[0,1,1]
	v_pk_fma_f32 v[90:91], v[12:13], v[12:13], v[88:89] op_sel_hi:[1,0,1] neg_lo:[0,0,1] neg_hi:[0,0,1]
	v_pk_fma_f32 v[88:89], v[12:13], v[12:13], v[88:89] op_sel_hi:[1,0,1]
	v_mov_b32_e32 v96, v90
	v_pk_mov_b32 v[98:99], v[88:89], v[90:91] op_sel:[1,0]
	v_mov_b32_e32 v97, v89
	v_pk_mul_f32 v[88:89], v[88:89], v[98:99] op_sel:[1,0]
	v_cvt_pk_bf16_f32 v0, v82, s0
	v_pk_fma_f32 v[98:99], v[90:91], v[96:97], v[88:89] op_sel_hi:[0,1,1] neg_lo:[0,0,1] neg_hi:[0,0,1]
	v_pk_fma_f32 v[88:89], v[90:91], v[96:97], v[88:89] op_sel_hi:[0,1,1]
	v_pk_mov_b32 v[96:97], v[88:89], v[98:99] op_sel:[1,0]
	v_mov_b32_e32 v90, v98
	v_mov_b32_e32 v91, v89
	v_pk_mul_f32 v[96:97], v[88:89], v[96:97] op_sel:[1,0]
	v_perm_b32 v82, v4, v0, s37
	v_pk_fma_f32 v[100:101], v[98:99], v[90:91], v[96:97] op_sel_hi:[0,1,1] neg_lo:[0,0,1] neg_hi:[0,0,1]
	v_pk_fma_f32 v[96:97], v[98:99], v[90:91], v[96:97] op_sel_hi:[0,1,1]
	v_pk_mov_b32 v[104:105], v[96:97], v[100:101] op_sel:[1,0]
	v_mov_b32_e32 v102, v100
	v_mov_b32_e32 v103, v97
	v_pk_mul_f32 v[104:105], v[96:97], v[104:105] op_sel:[1,0]
	v_cvt_pk_bf16_f32 v0, v84, s0
	v_pk_fma_f32 v[106:107], v[100:101], v[102:103], v[104:105] op_sel_hi:[0,1,1] neg_lo:[0,0,1] neg_hi:[0,0,1]
	v_pk_fma_f32 v[104:105], v[100:101], v[102:103], v[104:105] op_sel_hi:[0,1,1]
	v_pk_mov_b32 v[110:111], v[104:105], v[106:107] op_sel:[1,0]
	v_mov_b32_e32 v108, v106
	v_mov_b32_e32 v109, v105
	v_pk_mul_f32 v[112:113], v[104:105], v[110:111] op_sel:[1,0]
	v_cvt_pk_bf16_f32 v4, v85, s0
	v_pk_fma_f32 v[116:117], v[106:107], v[108:109], v[112:113] op_sel_hi:[0,1,1] neg_lo:[0,0,1] neg_hi:[0,0,1]
	v_pk_fma_f32 v[112:113], v[106:107], v[108:109], v[112:113] op_sel_hi:[0,1,1]
	v_perm_b32 v84, v4, v0, s37
	v_mov_b32_e32 v114, v116
	v_mov_b32_e32 v115, v113
	v_mul_f32_e32 v0, v105, v113
	v_pk_fma_f32 v[118:119], v[108:109], v[114:115], v[0:1] op_sel_hi:[1,1,0] neg_lo:[0,0,1] neg_hi:[0,0,1]
	v_mul_f32_e32 v0, v106, v113
	v_pk_fma_f32 v[120:121], v[110:111], v[114:115], v[0:1] op_sel_hi:[1,1,0]
	v_mul_f32_e32 v0, v89, v100
	v_pk_mul_f32 v[90:91], v[90:91], v[102:103]
	v_fmac_f32_e32 v0, v98, v97
	v_sub_f32_e32 v4, v90, v91
	v_and_b32_e32 v125, 0xffff0000, v92
	v_lshlrev_b32_e32 v124, 16, v92
	v_and_b32_e32 v135, 0xffff0000, v93
	v_lshlrev_b32_e32 v134, 16, v93
	v_cndmask_b32_e32 v4, v4, v100, vcc
	v_cndmask_b32_e32 v0, v0, v97, vcc
	v_and_b32_e32 v123, 0xffff0000, v94
	v_lshlrev_b32_e32 v122, 16, v94
	v_and_b32_e32 v133, 0xffff0000, v95
	v_lshlrev_b32_e32 v132, 16, v95
	v_xor_b32_e32 v93, 0x80000000, v135
	v_xor_b32_e32 v92, 0x80000000, v134
	v_xor_b32_e32 v95, 0x80000000, v125
	v_xor_b32_e32 v94, 0x80000000, v124
	v_cndmask_b32_e64 v4, v4, v98, s[2:3]
	v_cndmask_b32_e64 v0, v0, v89, s[2:3]
	v_pk_fma_f32 v[92:93], v[92:93], 0, v[132:133] op_sel_hi:[1,0,1]
	v_pk_fma_f32 v[94:95], v[94:95], 0, v[122:123] op_sel_hi:[1,0,1]
	v_perm_b32 v85, v16, v8, s37
	v_mov_b32_e32 v86, v12
	v_mov_b32_e32 v87, v12
	v_cndmask_b32_e64 v88, v4, 1.0, s[8:9]
	v_cndmask_b32_e64 v91, v0, 0, s[8:9]
	v_cvt_pk_bf16_f32 v0, v94, s0
	v_cvt_pk_bf16_f32 v4, v95, s0
	v_cvt_pk_bf16_f32 v8, v92, s0
	v_cvt_pk_bf16_f32 v12, v93, s0
	v_pk_fma_f32 v[94:95], v[132:133], 0, v[134:135] op_sel_hi:[1,0,1]
	v_pk_fma_f32 v[96:97], v[122:123], 0, v[124:125] op_sel_hi:[1,0,1]
	v_pk_mul_f32 v[98:99], v[104:105], v[134:135] op_sel:[1,0]
	v_perm_b32 v93, v12, v8, s37
	v_perm_b32 v92, v4, v0, s37
	v_cvt_pk_bf16_f32 v0, v96, s0
	v_cvt_pk_bf16_f32 v4, v97, s0
	v_cvt_pk_bf16_f32 v8, v94, s0
	v_cvt_pk_bf16_f32 v12, v95, s0
	v_pk_mul_f32 v[96:97], v[104:105], v[124:125] op_sel:[1,0]
	v_pk_fma_f32 v[98:99], v[106:107], v[132:133], v[98:99] op_sel_hi:[0,1,1] neg_lo:[0,0,1] neg_hi:[0,0,1]
	v_pk_mul_f32 v[100:101], v[104:105], v[132:133] op_sel:[1,0]
	v_perm_b32 v95, v12, v8, s37
	v_pk_fma_f32 v[96:97], v[106:107], v[122:123], v[96:97] op_sel_hi:[0,1,1] neg_lo:[0,0,1] neg_hi:[0,0,1]
	v_cvt_pk_bf16_f32 v8, v98, s0
	v_cvt_pk_bf16_f32 v12, v99, s0
	v_pk_mul_f32 v[98:99], v[104:105], v[122:123] op_sel:[1,0]
	v_pk_fma_f32 v[100:101], v[106:107], v[134:135], v[100:101] op_sel_hi:[0,1,1]
	v_perm_b32 v94, v4, v0, s37
	v_cvt_pk_bf16_f32 v0, v96, s0
	v_cvt_pk_bf16_f32 v4, v97, s0
	v_perm_b32 v97, v12, v8, s37
	v_pk_fma_f32 v[98:99], v[106:107], v[124:125], v[98:99] op_sel_hi:[0,1,1]
	v_cvt_pk_bf16_f32 v8, v100, s0
	v_cvt_pk_bf16_f32 v12, v101, s0
	v_pk_mul_f32 v[100:101], v[112:113], v[124:125] op_sel:[1,0]
	v_perm_b32 v96, v4, v0, s37
	v_cvt_pk_bf16_f32 v0, v98, s0
	v_cvt_pk_bf16_f32 v4, v99, s0
	v_pk_fma_f32 v[100:101], v[116:117], v[122:123], v[100:101] op_sel_hi:[0,1,1] neg_lo:[0,0,1] neg_hi:[0,0,1]
	v_perm_b32 v98, v4, v0, s37
	v_cvt_pk_bf16_f32 v0, v100, s0
	v_cvt_pk_bf16_f32 v4, v101, s0
	s_mul_i32 s2, s43, 0xfffffbc0
	v_perm_b32 v100, v4, v0, s37
	v_or_b32_e32 v0, s2, v127
	s_cselect_b32 s2, s47, s48
	v_add_u32_e32 v106, s2, v0
	v_or_b32_e32 v110, 16, v106
	v_ashrrev_i32_e32 v111, 31, v110
	v_ashrrev_i32_e32 v107, 31, v106
	v_lshlrev_b64 v[110:111], 12, v[110:111]
	v_lshlrev_b64 v[108:109], 12, v[106:107]
	v_lshl_add_u64 v[136:137], v[18:19], 0, v[110:111]
	v_or_b32_e32 v110, 32, v106
	v_or_b32_e32 v106, 48, v106
	v_pk_mul_f32 v[102:103], v[112:113], v[134:135] op_sel:[1,0]
	v_ashrrev_i32_e32 v111, 31, v110
	v_ashrrev_i32_e32 v107, 31, v106
	v_pk_fma_f32 v[102:103], v[116:117], v[132:133], v[102:103] op_sel_hi:[0,1,1] neg_lo:[0,0,1] neg_hi:[0,0,1]
	v_lshl_add_u64 v[108:109], v[18:19], 0, v[108:109]
	v_lshlrev_b64 v[110:111], 12, v[110:111]
	v_lshlrev_b64 v[106:107], 12, v[106:107]
	v_perm_b32 v99, v12, v8, s37
	v_cvt_pk_bf16_f32 v8, v102, s0
	v_cvt_pk_bf16_f32 v12, v103, s0
	v_pk_mul_f32 v[102:103], v[112:113], v[122:123] op_sel:[1,0]
	v_pk_mul_f32 v[104:105], v[112:113], v[132:133] op_sel:[1,0]
	v_lshl_add_u64 v[138:139], v[18:19], 0, v[110:111]
	v_lshl_add_u64 v[106:107], v[18:19], 0, v[106:107]
	s_waitcnt vmcnt(0)
; template <int DIR>
; __device__ __forceinline__ void s5_local_dir(const bf16_t* UZ, unsigned char* ws, int gw, int NGW, int lane) {
;     ...
;     const int pair = gw & 127, g = pair & 63, fr = lane & 15, fq = lane >> 4;
;     const bf16_t* Bb = (const bf16_t*)(ws + WS_BB) + (size_t)pair * 128 * 16;
;     bf16x4 Bre[4][4], Bim[4][4]; float a1r[4], a1i[4], a64r[4], a64i[4], wr_[4], wi_[4];
; #pragma unroll
;     for (int t = 0; t < 4; ++t) {
;         const int p = 16 * t + fr;
;         const bf16x4 b_re = *(const bf16x4*)(Bb + (2 * p) * 16 + 4 * fq), b_im = *(const bf16x4*)(Bb + (2 * p + 1) * 16 + 4 * fq);
;         const f32x4 ap = ((const f32x4*)(ws + WS_APOW))[pair * 64 + p];
;         const float ar = ap.x, ai = ap.y;
;         float r2 = ar, i2 = ai; cmul(r2, i2, ar, ai);
;         float r4 = r2, i4 = i2; cmul(r4, i4, r2, i2);
;         float r8 = r4, i8 = i4; cmul(r8, i8, r4, i4);
;         float r12 = r8, i12 = i8; cmul(r12, i12, r4, i4);
;         float r16 = r8, i16 = i8; cmul(r16, i16, r8, i8);
;         float r32 = r16, i32 = i16; cmul(r32, i32, r16, i16);
;         float r48 = r32, i48 = i32; cmul(r48, i48, r16, i16);
;         a1r[t] = ar; a1i[t] = ai; a64r[t] = ap.z; a64i[t] = ap.w;
;         const int e = DIR ? fq : 3 - fq;
;         wr_[t] = e == 0 ? 1.f : e == 1 ? r4 : e == 2 ? r8 : r12; wi_[t] = e == 0 ? 0.f : e == 1 ? i4 : e == 2 ? i8 : i12;
; #pragma unroll
;         for (int m = 0; m < 4; ++m) {
;             const int em = DIR ? m : 3 - m;
;             const float pr = em == 0 ? 1.f : em == 1 ? r16 : em == 2 ? r32 : r48, pi = em == 0 ? 0.f : em == 1 ? i16 : em == 2 ? i32 : i48;
;             Bre[m][t] = cscale_bf(b_re, b_im, pr, pi, false); Bim[m][t] = cscale_bf(b_re, b_im, pr, pi, true);
;         }
;     }
;     const int qd = gw >> 7, b = qd >> 2, q = qd & 3;
;     if (qd >= 16) return;
;     const int c0 = 17 * q, c1 = q < 3 ? c0 + 17 : 67;
;     float Rr[4] = {0.f, 0.f, 0.f, 0.f}, Ri[4] = {0.f, 0.f, 0.f, 0.f};
;     float* ebase = E + ((size_t)((b * 2 + DIR) * 64 + g) * NCHUNK) * 128;
	v_mov_b64_e32 v[110:111], v[152:153]
	v_mov_b64_e32 v[112:113], v[154:155]
	v_mov_b64_e32 v[114:115], v[156:157]
	v_mov_b64_e32 v[108:109], v[158:159]
	v_pk_fma_f32 v[104:105], v[116:117], v[134:135], v[104:105] op_sel_hi:[0,1,1]
	v_pk_mul_f32 v[106:107], v[120:121], v[134:135] op_sel_hi:[0,1]
	v_perm_b32 v101, v12, v8, s37
	v_pk_fma_f32 v[102:103], v[116:117], v[124:125], v[102:103] op_sel_hi:[0,1,1]
	v_cvt_pk_bf16_f32 v8, v104, s0
	v_cvt_pk_bf16_f32 v12, v105, s0
	v_pk_mul_f32 v[104:105], v[120:121], v[124:125] op_sel_hi:[0,1]
	v_pk_fma_f32 v[106:107], v[118:119], v[132:133], v[106:107] op_sel_hi:[0,1,1] neg_lo:[0,0,1] neg_hi:[0,0,1]
	v_cvt_pk_bf16_f32 v0, v102, s0
	v_cvt_pk_bf16_f32 v4, v103, s0
	v_perm_b32 v103, v12, v8, s37
	v_pk_fma_f32 v[104:105], v[118:119], v[122:123], v[104:105] op_sel_hi:[0,1,1] neg_lo:[0,0,1] neg_hi:[0,0,1]
	v_cvt_pk_bf16_f32 v8, v106, s0
	v_cvt_pk_bf16_f32 v12, v107, s0
	v_pk_mul_f32 v[106:107], v[120:121], v[122:123] op_sel_hi:[0,1]
	v_perm_b32 v102, v4, v0, s37
	v_cvt_pk_bf16_f32 v0, v104, s0
	v_cvt_pk_bf16_f32 v4, v105, s0
	v_pk_fma_f32 v[106:107], v[118:119], v[124:125], v[106:107] op_sel_hi:[0,1,1]
	v_perm_b32 v104, v4, v0, s37
	v_pk_mul_f32 v[116:117], v[120:121], v[132:133] op_sel_hi:[0,1]
	v_cvt_pk_bf16_f32 v0, v106, s0
	v_cvt_pk_bf16_f32 v4, v107, s0
	s_add_i32 s2, s45, s44
	v_pk_fma_f32 v[116:117], v[118:119], v[134:135], v[116:117] op_sel_hi:[0,1,1]
	v_perm_b32 v106, v4, v0, s37
	v_mbcnt_lo_u32_b32 v0, -1, 0
	s_add_i32 s2, s2, 64
	s_bfe_u32 s36, s40, 0x20007
	v_perm_b32 v105, v12, v8, s37
	v_cvt_pk_bf16_f32 v8, v116, s0
	v_cvt_pk_bf16_f32 v12, v117, s0
	v_mbcnt_hi_u32_b32 v0, -1, v0
	s_mul_hi_i32 s3, s2, 0x8800
	s_mul_i32 s2, s2, 0x8800
	s_mulk_i32 s36, 0x2200
	v_perm_b32 v107, v12, v8, s37
	v_and_b32_e32 v8, 64, v0
	s_add_u32 s2, s2, s36
	v_xor_b32_e32 v4, 16, v0
	v_add_u32_e32 v8, 64, v8
	s_addc_u32 s3, s3, 0
	v_cmp_lt_i32_e32 vcc, v4, v8
	s_add_u32 s2, s30, s2
	v_lshlrev_b32_e32 v16, 2, v126
	v_cndmask_b32_e32 v4, v0, v4, vcc
	s_addc_u32 s3, s31, s3
	v_lshlrev_b32_e32 v131, 2, v4
	v_xor_b32_e32 v4, 32, v0
	v_lshl_add_u64 v[116:117], s[2:3], 0, v[16:17]
	s_mov_b64 s[2:3], 0x1700100
	v_cmp_lt_i32_e32 vcc, v4, v8
	v_lshl_add_u64 v[116:117], v[116:117], 0, s[2:3]
	s_mul_i32 s2, s43, 0x440
	v_cndmask_b32_e32 v0, v0, v4, vcc
	v_subrev_u32_e32 v16, s2, v127
	v_lshlrev_b32_e32 v132, 2, v0
	v_xor_b32_e32 v0, 0x80000000, v1
	v_mov_b32_e32 v23, v22
	v_xor_b32_e32 v24, 0x80000000, v25
	v_xor_b32_e32 v4, 0x80000000, v5
	v_mov_b32_e32 v45, v44
	v_xor_b32_e32 v46, 0x80000000, v47
	v_xor_b32_e32 v8, 0x80000000, v9
	v_mov_b32_e32 v67, v66
	v_xor_b32_e32 v68, 0x80000000, v69
	v_xor_b32_e32 v12, 0x80000000, v13
	v_mov_b32_e32 v89, v88
	v_xor_b32_e32 v90, 0x80000000, v91
	v_subrev_u32_e32 v16, 32, v16
	s_mov_b64 s[2:3], 0x200
	v_mov_b32_e32 v137, v17
	v_mov_b32_e32 v135, v17
	v_mov_b32_e32 v133, v17
	v_mov_b32_e32 v139, v17
	v_mov_b32_e32 v138, v17
	v_mov_b32_e32 v136, v17
	v_mov_b32_e32 v134, v17
	v_and_b32_e32 v244, 16, v126
	v_and_b32_e32 v245, 32, v126
	v_cmp_ne_u32_e64 s[96:97], 0, v244
	v_cmp_ne_u32_e32 vcc, 0, v245
	s_nop 1
	v_cndmask_b32_e32 v244, v2, v10, vcc
	v_cndmask_b32_e32 v245, v6, v14, vcc
	v_cndmask_b32_e64 v242, v244, v245, s[96:97]
	v_cndmask_b32_e32 v244, v3, v11, vcc
	v_cndmask_b32_e32 v245, v7, v15, vcc
	v_cndmask_b32_e64 v243, v244, v245, s[96:97]
	v_readfirstlane_b32 s98, v192
	s_lshr_b32 s98, s98, 6
	s_lshl_b32 s99, s12, 3
	s_add_i32 s98, s98, s99
	s_and_b32 s98, s98, 0x7f
	v_and_b32_e32 v216, 63, v192
	s_lshl_b32 s99, s98, 6
	v_or_b32_e32 v217, s99, v216
	v_lshlrev_b32_e32 v217, 4, v217
	s_add_u32 s100, s30, 0x80000
	s_addc_u32 s101, s31, 0
	global_load_dwordx4 v[212:215], v217, s[100:101]
	s_lshl_b32 s99, s98, 12
	s_add_u32 s100, s30, 0x100000
	s_addc_u32 s101, s31, 0
	s_add_u32 s100, s100, s99
	s_addc_u32 s101, s101, 0
	v_lshlrev_b32_e32 v216, 6, v216
	global_load_dwordx4 v[196:199], v216, s[100:101] offset:0
	global_load_dwordx4 v[200:203], v216, s[100:101] offset:16
	global_load_dwordx4 v[204:207], v216, s[100:101] offset:32
	global_load_dwordx4 v[208:211], v216, s[100:101] offset:48
	s_waitcnt vmcnt(0)
	v_mov_b32_e32 v246, v212
	v_mov_b32_e32 v247, v213
	v_xor_b32_e32 v248, 0x80000000, v213
	v_mul_f32_e32 v218, v213, v213
	v_fma_f32 v216, v212, v212, -v218
	v_mul_f32_e32 v218, v213, v212
	v_fma_f32 v217, v212, v213, v218
	v_mul_f32_e32 v218, v217, v217
	v_fma_f32 v146, v216, v216, -v218
	v_mul_f32_e32 v218, v217, v216
	v_fma_f32 v147, v216, v217, v218
	v_mul_f32_e32 v218, v147, v147
	v_fma_f32 v148, v146, v146, -v218
	v_mul_f32_e32 v218, v147, v146
	v_fma_f32 v149, v146, v147, v218
	v_mul_f32_e32 v218, v149, v149
	v_fma_f32 v140, v148, v148, -v218
	v_mul_f32_e32 v218, v149, v148
	v_fma_f32 v141, v148, v149, v218
	v_mul_f32_e32 v218, v141, v141
	v_fma_f32 v142, v140, v140, -v218
	v_mul_f32_e32 v218, v141, v140
	v_fma_f32 v143, v140, v141, v218
	v_mul_f32_e32 v218, v143, v141
	v_fma_f32 v144, v142, v140, -v218
	v_mul_f32_e32 v218, v143, v140
	v_fma_f32 v145, v142, v141, v218
	v_lshlrev_b32_e32 v152, 16, v196
	v_and_b32_e32 v153, 0xffff0000, v196
	v_lshlrev_b32_e32 v168, 16, v204
	v_and_b32_e32 v169, 0xffff0000, v204
	v_lshlrev_b32_e32 v154, 16, v197
	v_and_b32_e32 v155, 0xffff0000, v197
	v_lshlrev_b32_e32 v170, 16, v205
	v_and_b32_e32 v171, 0xffff0000, v205
	v_lshlrev_b32_e32 v156, 16, v198
	v_and_b32_e32 v157, 0xffff0000, v198
	v_lshlrev_b32_e32 v172, 16, v206
	v_and_b32_e32 v173, 0xffff0000, v206
	v_lshlrev_b32_e32 v158, 16, v199
	v_and_b32_e32 v159, 0xffff0000, v199
	v_lshlrev_b32_e32 v174, 16, v207
	v_and_b32_e32 v175, 0xffff0000, v207
	v_lshlrev_b32_e32 v160, 16, v200
; __device__ __forceinline__ unsigned pk2(float lo, float hi) { f32x2 v = {lo, hi}; nbf2 r = __builtin_convertvector(v, nbf2); return __builtin_bit_cast(unsigned, r); }
; __device__ __forceinline__ bf16x4 cscale_bf(const bf16x4 re, const bf16x4 im, float wr, float wi, bool want_im) {
;     bf16x4 o;
; #pragma unroll
;     for (int k = 0; k < 4; k += 2) {
;         const float r0 = __uint_as_float((unsigned)(unsigned short)re[k] << 16), r1 = __uint_as_float((unsigned)(unsigned short)re[k + 1] << 16);
;         const float i0 = __uint_as_float((unsigned)(unsigned short)im[k] << 16), i1 = __uint_as_float((unsigned)(unsigned short)im[k + 1] << 16);
;         const unsigned w = want_im ? pk2(wr * i0 + wi * r0, wr * i1 + wi * r1) : pk2(wr * r0 - wi * i0, wr * r1 - wi * i1);
;         o[k] = (short)(w & 0xffffu); o[k + 1] = (short)(w >> 16);
;     }
;     return o;
; }
; template <int DIR>
; __device__ __forceinline__ void s5_local_dir(const bf16_t* UZ, unsigned char* ws, int gw, int NGW, int lane) {
;     ...
;         const int e = DIR ? fq : 3 - fq;
;         wr_[t] = e == 0 ? 1.f : e == 1 ? r4 : e == 2 ? r8 : r12; wi_[t] = e == 0 ? 0.f : e == 1 ? i4 : e == 2 ? i8 : i12;
; #pragma unroll
;         for (int m = 0; m < 4; ++m) {
;             const int em = DIR ? m : 3 - m;
;             const float pr = em == 0 ? 1.f : em == 1 ? r16 : em == 2 ? r32 : r48, pi = em == 0 ? 0.f : em == 1 ? i16 : em == 2 ? i32 : i48;
;             Bre[m][t] = cscale_bf(b_re, b_im, pr, pi, false); Bim[m][t] = cscale_bf(b_re, b_im, pr, pi, true);
;         }
	v_and_b32_e32 v161, 0xffff0000, v200
	v_lshlrev_b32_e32 v176, 16, v208
	v_and_b32_e32 v177, 0xffff0000, v208
	v_lshlrev_b32_e32 v162, 16, v201
	v_and_b32_e32 v163, 0xffff0000, v201
	v_lshlrev_b32_e32 v178, 16, v209
	v_and_b32_e32 v179, 0xffff0000, v209
	v_lshlrev_b32_e32 v164, 16, v202
	v_and_b32_e32 v165, 0xffff0000, v202
	v_lshlrev_b32_e32 v180, 16, v210
	v_and_b32_e32 v181, 0xffff0000, v210
	v_lshlrev_b32_e32 v166, 16, v203
	v_and_b32_e32 v167, 0xffff0000, v203
	v_lshlrev_b32_e32 v182, 16, v211
	v_and_b32_e32 v183, 0xffff0000, v211
	v_cvt_pk_bf16_f32 v26, v152, v153
	v_cvt_pk_bf16_f32 v27, v154, v155
	v_cvt_pk_bf16_f32 v34, v168, v169
	v_cvt_pk_bf16_f32 v35, v170, v171
	v_cvt_pk_bf16_f32 v28, v156, v157
	v_cvt_pk_bf16_f32 v29, v158, v159
	v_cvt_pk_bf16_f32 v36, v172, v173
	v_cvt_pk_bf16_f32 v37, v174, v175
	v_cvt_pk_bf16_f32 v30, v160, v161
	v_cvt_pk_bf16_f32 v31, v162, v163
	v_cvt_pk_bf16_f32 v38, v176, v177
	v_cvt_pk_bf16_f32 v39, v178, v179
	v_cvt_pk_bf16_f32 v32, v164, v165
	v_cvt_pk_bf16_f32 v33, v166, v167
	v_cvt_pk_bf16_f32 v40, v180, v181
	v_cvt_pk_bf16_f32 v41, v182, v183
	v_mul_f32_e32 v218, v141, v168
	v_fma_f32 v220, v140, v152, -v218
	v_mul_f32_e32 v219, v141, v152
	v_fma_f32 v236, v140, v168, v219
	v_mul_f32_e32 v218, v141, v169
	v_fma_f32 v221, v140, v153, -v218
	v_mul_f32_e32 v219, v141, v153
	v_fma_f32 v237, v140, v169, v219
	v_mul_f32_e32 v218, v141, v170
	v_fma_f32 v222, v140, v154, -v218
	v_mul_f32_e32 v219, v141, v154
	v_fma_f32 v238, v140, v170, v219
	v_mul_f32_e32 v218, v141, v171
	v_fma_f32 v223, v140, v155, -v218
	v_mul_f32_e32 v219, v141, v155
	v_fma_f32 v239, v140, v171, v219
	v_cvt_pk_bf16_f32 v48, v220, v221
	v_cvt_pk_bf16_f32 v49, v222, v223
	v_cvt_pk_bf16_f32 v56, v236, v237
	v_cvt_pk_bf16_f32 v57, v238, v239
	v_mul_f32_e32 v218, v141, v172
	v_fma_f32 v220, v140, v156, -v218
	v_mul_f32_e32 v219, v141, v156
	v_fma_f32 v236, v140, v172, v219
	v_mul_f32_e32 v218, v141, v173
	v_fma_f32 v221, v140, v157, -v218
	v_mul_f32_e32 v219, v141, v157
	v_fma_f32 v237, v140, v173, v219
	v_mul_f32_e32 v218, v141, v174
	v_fma_f32 v222, v140, v158, -v218
	v_mul_f32_e32 v219, v141, v158
	v_fma_f32 v238, v140, v174, v219
	v_mul_f32_e32 v218, v141, v175
	v_fma_f32 v223, v140, v159, -v218
	v_mul_f32_e32 v219, v141, v159
	v_fma_f32 v239, v140, v175, v219
	v_cvt_pk_bf16_f32 v50, v220, v221
	v_cvt_pk_bf16_f32 v51, v222, v223
	v_cvt_pk_bf16_f32 v58, v236, v237
	v_cvt_pk_bf16_f32 v59, v238, v239
	v_mul_f32_e32 v218, v141, v176
	v_fma_f32 v220, v140, v160, -v218
	v_mul_f32_e32 v219, v141, v160
	v_fma_f32 v236, v140, v176, v219
	v_mul_f32_e32 v218, v141, v177
	v_fma_f32 v221, v140, v161, -v218
	v_mul_f32_e32 v219, v141, v161
	v_fma_f32 v237, v140, v177, v219
	v_mul_f32_e32 v218, v141, v178
	v_fma_f32 v222, v140, v162, -v218
	v_mul_f32_e32 v219, v141, v162
	v_fma_f32 v238, v140, v178, v219
	v_mul_f32_e32 v218, v141, v179
	v_fma_f32 v223, v140, v163, -v218
	v_mul_f32_e32 v219, v141, v163
	v_fma_f32 v239, v140, v179, v219
	v_cvt_pk_bf16_f32 v52, v220, v221
	v_cvt_pk_bf16_f32 v53, v222, v223
	v_cvt_pk_bf16_f32 v60, v236, v237
	v_cvt_pk_bf16_f32 v61, v238, v239
	v_mul_f32_e32 v218, v141, v180
	v_fma_f32 v220, v140, v164, -v218
	v_mul_f32_e32 v219, v141, v164
	v_fma_f32 v236, v140, v180, v219
	v_mul_f32_e32 v218, v141, v181
	v_fma_f32 v221, v140, v165, -v218
	v_mul_f32_e32 v219, v141, v165
	v_fma_f32 v237, v140, v181, v219
	v_mul_f32_e32 v218, v141, v182
	v_fma_f32 v222, v140, v166, -v218
	v_mul_f32_e32 v219, v141, v166
	v_fma_f32 v238, v140, v182, v219
	v_mul_f32_e32 v218, v141, v183
	v_fma_f32 v223, v140, v167, -v218
	v_mul_f32_e32 v219, v141, v167
	v_fma_f32 v239, v140, v183, v219
	v_cvt_pk_bf16_f32 v54, v220, v221
	v_cvt_pk_bf16_f32 v55, v222, v223
	v_cvt_pk_bf16_f32 v62, v236, v237
	v_cvt_pk_bf16_f32 v63, v238, v239
	v_mul_f32_e32 v218, v143, v168
	v_fma_f32 v220, v142, v152, -v218
	v_mul_f32_e32 v219, v143, v152
	v_fma_f32 v236, v142, v168, v219
	v_mul_f32_e32 v218, v143, v169
	v_fma_f32 v221, v142, v153, -v218
	v_mul_f32_e32 v219, v143, v153
	v_fma_f32 v237, v142, v169, v219
	v_mul_f32_e32 v218, v143, v170
	v_fma_f32 v222, v142, v154, -v218
	v_mul_f32_e32 v219, v143, v154
	v_fma_f32 v238, v142, v170, v219
	v_mul_f32_e32 v218, v143, v171
	v_fma_f32 v223, v142, v155, -v218
	v_mul_f32_e32 v219, v143, v155
	v_fma_f32 v239, v142, v171, v219
	v_cvt_pk_bf16_f32 v70, v220, v221
	v_cvt_pk_bf16_f32 v71, v222, v223
	v_cvt_pk_bf16_f32 v78, v236, v237
	v_cvt_pk_bf16_f32 v79, v238, v239
	v_mul_f32_e32 v218, v143, v172
	v_fma_f32 v220, v142, v156, -v218
	v_mul_f32_e32 v219, v143, v156
	v_fma_f32 v236, v142, v172, v219
; __device__ __forceinline__ unsigned pk2(float lo, float hi) { f32x2 v = {lo, hi}; nbf2 r = __builtin_convertvector(v, nbf2); return __builtin_bit_cast(unsigned, r); }
; __device__ __forceinline__ bf16x4 cscale_bf(const bf16x4 re, const bf16x4 im, float wr, float wi, bool want_im) {
;     bf16x4 o;
; #pragma unroll
;     for (int k = 0; k < 4; k += 2) {
;         const float r0 = __uint_as_float((unsigned)(unsigned short)re[k] << 16), r1 = __uint_as_float((unsigned)(unsigned short)re[k + 1] << 16);
;         const float i0 = __uint_as_float((unsigned)(unsigned short)im[k] << 16), i1 = __uint_as_float((unsigned)(unsigned short)im[k + 1] << 16);
;         const unsigned w = want_im ? pk2(wr * i0 + wi * r0, wr * i1 + wi * r1) : pk2(wr * r0 - wi * i0, wr * r1 - wi * i1);
;         o[k] = (short)(w & 0xffffu); o[k + 1] = (short)(w >> 16);
;     }
;     return o;
; }
; template <int DIR>
; __device__ __forceinline__ void s5_local_dir(const bf16_t* UZ, unsigned char* ws, int gw, int NGW, int lane) {
;     ...
;         const int e = DIR ? fq : 3 - fq;
;         wr_[t] = e == 0 ? 1.f : e == 1 ? r4 : e == 2 ? r8 : r12; wi_[t] = e == 0 ? 0.f : e == 1 ? i4 : e == 2 ? i8 : i12;
; #pragma unroll
;         for (int m = 0; m < 4; ++m) {
;             const int em = DIR ? m : 3 - m;
;             const float pr = em == 0 ? 1.f : em == 1 ? r16 : em == 2 ? r32 : r48, pi = em == 0 ? 0.f : em == 1 ? i16 : em == 2 ? i32 : i48;
;             Bre[m][t] = cscale_bf(b_re, b_im, pr, pi, false); Bim[m][t] = cscale_bf(b_re, b_im, pr, pi, true);
;         }
	v_mul_f32_e32 v218, v143, v173
	v_fma_f32 v221, v142, v157, -v218
	v_mul_f32_e32 v219, v143, v157
	v_fma_f32 v237, v142, v173, v219
	v_mul_f32_e32 v218, v143, v174
	v_fma_f32 v222, v142, v158, -v218
	v_mul_f32_e32 v219, v143, v158
	v_fma_f32 v238, v142, v174, v219
	v_mul_f32_e32 v218, v143, v175
	v_fma_f32 v223, v142, v159, -v218
	v_mul_f32_e32 v219, v143, v159
	v_fma_f32 v239, v142, v175, v219
	v_cvt_pk_bf16_f32 v72, v220, v221
	v_cvt_pk_bf16_f32 v73, v222, v223
	v_cvt_pk_bf16_f32 v80, v236, v237
	v_cvt_pk_bf16_f32 v81, v238, v239
	v_mul_f32_e32 v218, v143, v176
	v_fma_f32 v220, v142, v160, -v218
	v_mul_f32_e32 v219, v143, v160
	v_fma_f32 v236, v142, v176, v219
	v_mul_f32_e32 v218, v143, v177
	v_fma_f32 v221, v142, v161, -v218
	v_mul_f32_e32 v219, v143, v161
	v_fma_f32 v237, v142, v177, v219
	v_mul_f32_e32 v218, v143, v178
	v_fma_f32 v222, v142, v162, -v218
	v_mul_f32_e32 v219, v143, v162
	v_fma_f32 v238, v142, v178, v219
	v_mul_f32_e32 v218, v143, v179
	v_fma_f32 v223, v142, v163, -v218
	v_mul_f32_e32 v219, v143, v163
	v_fma_f32 v239, v142, v179, v219
	v_cvt_pk_bf16_f32 v74, v220, v221
	v_cvt_pk_bf16_f32 v75, v222, v223
	v_cvt_pk_bf16_f32 v82, v236, v237
	v_cvt_pk_bf16_f32 v83, v238, v239
	v_mul_f32_e32 v218, v143, v180
	v_fma_f32 v220, v142, v164, -v218
	v_mul_f32_e32 v219, v143, v164
	v_fma_f32 v236, v142, v180, v219
	v_mul_f32_e32 v218, v143, v181
	v_fma_f32 v221, v142, v165, -v218
	v_mul_f32_e32 v219, v143, v165
	v_fma_f32 v237, v142, v181, v219
	v_mul_f32_e32 v218, v143, v182
	v_fma_f32 v222, v142, v166, -v218
	v_mul_f32_e32 v219, v143, v166
	v_fma_f32 v238, v142, v182, v219
	v_mul_f32_e32 v218, v143, v183
	v_fma_f32 v223, v142, v167, -v218
	v_mul_f32_e32 v219, v143, v167
	v_fma_f32 v239, v142, v183, v219
	v_cvt_pk_bf16_f32 v76, v220, v221
	v_cvt_pk_bf16_f32 v77, v222, v223
	v_cvt_pk_bf16_f32 v84, v236, v237
	v_cvt_pk_bf16_f32 v85, v238, v239
	v_mul_f32_e32 v218, v145, v168
	v_fma_f32 v220, v144, v152, -v218
	v_mul_f32_e32 v219, v145, v152
	v_fma_f32 v236, v144, v168, v219
	v_mul_f32_e32 v218, v145, v169
	v_fma_f32 v221, v144, v153, -v218
	v_mul_f32_e32 v219, v145, v153
	v_fma_f32 v237, v144, v169, v219
	v_mul_f32_e32 v218, v145, v170
	v_fma_f32 v222, v144, v154, -v218
	v_mul_f32_e32 v219, v145, v154
	v_fma_f32 v238, v144, v170, v219
	v_mul_f32_e32 v218, v145, v171
	v_fma_f32 v223, v144, v155, -v218
	v_mul_f32_e32 v219, v145, v155
	v_fma_f32 v239, v144, v171, v219
	v_cvt_pk_bf16_f32 v92, v220, v221
	v_cvt_pk_bf16_f32 v93, v222, v223
	v_cvt_pk_bf16_f32 v100, v236, v237
	v_cvt_pk_bf16_f32 v101, v238, v239
	v_mul_f32_e32 v218, v145, v172
	v_fma_f32 v220, v144, v156, -v218
	v_mul_f32_e32 v219, v145, v156
	v_fma_f32 v236, v144, v172, v219
	v_mul_f32_e32 v218, v145, v173
	v_fma_f32 v221, v144, v157, -v218
	v_mul_f32_e32 v219, v145, v157
	v_fma_f32 v237, v144, v173, v219
	v_mul_f32_e32 v218, v145, v174
	v_fma_f32 v222, v144, v158, -v218
	v_mul_f32_e32 v219, v145, v158
	v_fma_f32 v238, v144, v174, v219
	v_mul_f32_e32 v218, v145, v175
	v_fma_f32 v223, v144, v159, -v218
	v_mul_f32_e32 v219, v145, v159
	v_fma_f32 v239, v144, v175, v219
	v_cvt_pk_bf16_f32 v94, v220, v221
	v_cvt_pk_bf16_f32 v95, v222, v223
	v_cvt_pk_bf16_f32 v102, v236, v237
	v_cvt_pk_bf16_f32 v103, v238, v239
	v_mul_f32_e32 v218, v145, v176
	v_fma_f32 v220, v144, v160, -v218
	v_mul_f32_e32 v219, v145, v160
	v_fma_f32 v236, v144, v176, v219
	v_mul_f32_e32 v218, v145, v177
	v_fma_f32 v221, v144, v161, -v218
	v_mul_f32_e32 v219, v145, v161
	v_fma_f32 v237, v144, v177, v219
	v_mul_f32_e32 v218, v145, v178
	v_fma_f32 v222, v144, v162, -v218
	v_mul_f32_e32 v219, v145, v162
	v_fma_f32 v238, v144, v178, v219
	v_mul_f32_e32 v218, v145, v179
	v_fma_f32 v223, v144, v163, -v218
	v_mul_f32_e32 v219, v145, v163
	v_fma_f32 v239, v144, v179, v219
	v_cvt_pk_bf16_f32 v96, v220, v221
	v_cvt_pk_bf16_f32 v97, v222, v223
	v_cvt_pk_bf16_f32 v104, v236, v237
	v_cvt_pk_bf16_f32 v105, v238, v239
	v_mul_f32_e32 v218, v145, v180
	v_fma_f32 v220, v144, v164, -v218
	v_mul_f32_e32 v219, v145, v164
	v_fma_f32 v236, v144, v180, v219
	v_mul_f32_e32 v218, v145, v181
	v_fma_f32 v221, v144, v165, -v218
	v_mul_f32_e32 v219, v145, v165
	v_fma_f32 v237, v144, v181, v219
	v_mul_f32_e32 v218, v145, v182
	v_fma_f32 v222, v144, v166, -v218
	v_mul_f32_e32 v219, v145, v166
	v_fma_f32 v238, v144, v182, v219
	v_mul_f32_e32 v218, v145, v183
	v_fma_f32 v223, v144, v167, -v218
	v_mul_f32_e32 v219, v145, v167
	v_fma_f32 v239, v144, v183, v219
	v_cvt_pk_bf16_f32 v98, v220, v221
	v_cvt_pk_bf16_f32 v99, v222, v223
	v_cvt_pk_bf16_f32 v106, v236, v237
	v_cvt_pk_bf16_f32 v107, v238, v239
	s_nop 1

; template <int DIR>
; __device__ __forceinline__ void s5_local_dir(const bf16_t* UZ, unsigned char* ws, int gw, int NGW, int lane) {
;     ...
;         for (int t = 0; t < 4; ++t) {
;             f32x4 cr = {0.f, 0.f, 0.f, 0.f}, ci = {0.f, 0.f, 0.f, 0.f};
; #pragma unroll
;             for (int m = 0; m < 4; ++m) {
;                 cr = __builtin_amdgcn_mfma_f32_16x16x16bf16_1k(Uf[m], Bre[m][t], cr, 0, 0, 0);
;                 ci = __builtin_amdgcn_mfma_f32_16x16x16bf16_1k(Uf[m], Bim[m][t], ci, 0, 0, 0);
;             }
.LBB0_652:
	global_store_dword v[116:117], v240, off offset:-256
	global_store_dword v[116:117], v241, off
	s_waitcnt vmcnt(9)
	v_mfma_f32_4x4x4_16b_bf16 v[140:143], v[110:111], v[26:27], 0 cbsz:4 abid:0
	v_mfma_f32_4x4x4_16b_bf16 v[144:147], v[110:111], v[34:35], 0 cbsz:4 abid:0
	v_mfma_f32_4x4x4_16b_bf16 v[196:199], v[110:111], v[26:27], 0 cbsz:4 abid:1
	v_mfma_f32_4x4x4_16b_bf16 v[200:203], v[110:111], v[34:35], 0 cbsz:4 abid:1
	v_mfma_f32_4x4x4_16b_bf16 v[204:207], v[110:111], v[26:27], 0 cbsz:4 abid:2
	v_mfma_f32_4x4x4_16b_bf16 v[208:211], v[110:111], v[34:35], 0 cbsz:4 abid:2
	v_mfma_f32_4x4x4_16b_bf16 v[212:215], v[110:111], v[26:27], 0 cbsz:4 abid:3
	v_mfma_f32_4x4x4_16b_bf16 v[216:219], v[110:111], v[34:35], 0 cbsz:4 abid:3
	v_mfma_f32_4x4x4_16b_bf16 v[140:143], v[110:111], v[28:29], v[140:143] cbsz:4 abid:4
	v_mfma_f32_4x4x4_16b_bf16 v[144:147], v[110:111], v[36:37], v[144:147] cbsz:4 abid:4
	v_mfma_f32_4x4x4_16b_bf16 v[196:199], v[110:111], v[28:29], v[196:199] cbsz:4 abid:5
	v_mfma_f32_4x4x4_16b_bf16 v[200:203], v[110:111], v[36:37], v[200:203] cbsz:4 abid:5
	v_mfma_f32_4x4x4_16b_bf16 v[204:207], v[110:111], v[28:29], v[204:207] cbsz:4 abid:6
	v_mfma_f32_4x4x4_16b_bf16 v[208:211], v[110:111], v[36:37], v[208:211] cbsz:4 abid:6
	v_mfma_f32_4x4x4_16b_bf16 v[212:215], v[110:111], v[28:29], v[212:215] cbsz:4 abid:7
	v_mfma_f32_4x4x4_16b_bf16 v[216:219], v[110:111], v[36:37], v[216:219] cbsz:4 abid:7
	v_mfma_f32_4x4x4_16b_bf16 v[140:143], v[110:111], v[30:31], v[140:143] cbsz:4 abid:8
	v_mfma_f32_4x4x4_16b_bf16 v[144:147], v[110:111], v[38:39], v[144:147] cbsz:4 abid:8
	v_mfma_f32_4x4x4_16b_bf16 v[196:199], v[110:111], v[30:31], v[196:199] cbsz:4 abid:9
	v_mfma_f32_4x4x4_16b_bf16 v[200:203], v[110:111], v[38:39], v[200:203] cbsz:4 abid:9
	v_mfma_f32_4x4x4_16b_bf16 v[204:207], v[110:111], v[30:31], v[204:207] cbsz:4 abid:10
	v_mfma_f32_4x4x4_16b_bf16 v[208:211], v[110:111], v[38:39], v[208:211] cbsz:4 abid:10
	v_mfma_f32_4x4x4_16b_bf16 v[212:215], v[110:111], v[30:31], v[212:215] cbsz:4 abid:11
	v_mfma_f32_4x4x4_16b_bf16 v[216:219], v[110:111], v[38:39], v[216:219] cbsz:4 abid:11
	v_mfma_f32_4x4x4_16b_bf16 v[140:143], v[110:111], v[32:33], v[140:143] cbsz:4 abid:12
	v_mfma_f32_4x4x4_16b_bf16 v[144:147], v[110:111], v[40:41], v[144:147] cbsz:4 abid:12
	v_mfma_f32_4x4x4_16b_bf16 v[196:199], v[110:111], v[32:33], v[196:199] cbsz:4 abid:13
	v_mfma_f32_4x4x4_16b_bf16 v[200:203], v[110:111], v[40:41], v[200:203] cbsz:4 abid:13
	v_mfma_f32_4x4x4_16b_bf16 v[204:207], v[110:111], v[32:33], v[204:207] cbsz:4 abid:14
	v_mfma_f32_4x4x4_16b_bf16 v[208:211], v[110:111], v[40:41], v[208:211] cbsz:4 abid:14
	v_mfma_f32_4x4x4_16b_bf16 v[212:215], v[110:111], v[32:33], v[212:215] cbsz:4 abid:15
	v_mfma_f32_4x4x4_16b_bf16 v[216:219], v[110:111], v[40:41], v[216:219] cbsz:4 abid:15
	s_waitcnt vmcnt(8)
	v_mfma_f32_4x4x4_16b_bf16 v[140:143], v[112:113], v[48:49], v[140:143] cbsz:4 abid:0
	v_mfma_f32_4x4x4_16b_bf16 v[144:147], v[112:113], v[56:57], v[144:147] cbsz:4 abid:0
	v_mfma_f32_4x4x4_16b_bf16 v[196:199], v[112:113], v[48:49], v[196:199] cbsz:4 abid:1
	v_mfma_f32_4x4x4_16b_bf16 v[200:203], v[112:113], v[56:57], v[200:203] cbsz:4 abid:1
	v_mfma_f32_4x4x4_16b_bf16 v[204:207], v[112:113], v[48:49], v[204:207] cbsz:4 abid:2
	v_mfma_f32_4x4x4_16b_bf16 v[208:211], v[112:113], v[56:57], v[208:211] cbsz:4 abid:2
	v_mfma_f32_4x4x4_16b_bf16 v[212:215], v[112:113], v[48:49], v[212:215] cbsz:4 abid:3
	v_mfma_f32_4x4x4_16b_bf16 v[216:219], v[112:113], v[56:57], v[216:219] cbsz:4 abid:3
	v_mfma_f32_4x4x4_16b_bf16 v[140:143], v[112:113], v[50:51], v[140:143] cbsz:4 abid:4
	v_mfma_f32_4x4x4_16b_bf16 v[144:147], v[112:113], v[58:59], v[144:147] cbsz:4 abid:4
	v_mfma_f32_4x4x4_16b_bf16 v[196:199], v[112:113], v[50:51], v[196:199] cbsz:4 abid:5
	v_mfma_f32_4x4x4_16b_bf16 v[200:203], v[112:113], v[58:59], v[200:203] cbsz:4 abid:5
	v_mfma_f32_4x4x4_16b_bf16 v[204:207], v[112:113], v[50:51], v[204:207] cbsz:4 abid:6
	v_mfma_f32_4x4x4_16b_bf16 v[208:211], v[112:113], v[58:59], v[208:211] cbsz:4 abid:6
	v_mfma_f32_4x4x4_16b_bf16 v[212:215], v[112:113], v[50:51], v[212:215] cbsz:4 abid:7
	v_mfma_f32_4x4x4_16b_bf16 v[216:219], v[112:113], v[58:59], v[216:219] cbsz:4 abid:7
	v_mfma_f32_4x4x4_16b_bf16 v[140:143], v[112:113], v[52:53], v[140:143] cbsz:4 abid:8
	v_mfma_f32_4x4x4_16b_bf16 v[144:147], v[112:113], v[60:61], v[144:147] cbsz:4 abid:8
	v_mfma_f32_4x4x4_16b_bf16 v[196:199], v[112:113], v[52:53], v[196:199] cbsz:4 abid:9
	v_mfma_f32_4x4x4_16b_bf16 v[200:203], v[112:113], v[60:61], v[200:203] cbsz:4 abid:9
	v_mfma_f32_4x4x4_16b_bf16 v[204:207], v[112:113], v[52:53], v[204:207] cbsz:4 abid:10
	v_mfma_f32_4x4x4_16b_bf16 v[208:211], v[112:113], v[60:61], v[208:211] cbsz:4 abid:10
	v_mfma_f32_4x4x4_16b_bf16 v[212:215], v[112:113], v[52:53], v[212:215] cbsz:4 abid:11
	v_mfma_f32_4x4x4_16b_bf16 v[216:219], v[112:113], v[60:61], v[216:219] cbsz:4 abid:11
	v_mfma_f32_4x4x4_16b_bf16 v[140:143], v[112:113], v[54:55], v[140:143] cbsz:4 abid:12
	v_mfma_f32_4x4x4_16b_bf16 v[144:147], v[112:113], v[62:63], v[144:147] cbsz:4 abid:12
	v_mfma_f32_4x4x4_16b_bf16 v[196:199], v[112:113], v[54:55], v[196:199] cbsz:4 abid:13
	v_mfma_f32_4x4x4_16b_bf16 v[200:203], v[112:113], v[62:63], v[200:203] cbsz:4 abid:13
	v_mfma_f32_4x4x4_16b_bf16 v[204:207], v[112:113], v[54:55], v[204:207] cbsz:4 abid:14
	v_mfma_f32_4x4x4_16b_bf16 v[208:211], v[112:113], v[62:63], v[208:211] cbsz:4 abid:14
	v_mfma_f32_4x4x4_16b_bf16 v[212:215], v[112:113], v[54:55], v[212:215] cbsz:4 abid:15
	v_mfma_f32_4x4x4_16b_bf16 v[216:219], v[112:113], v[62:63], v[216:219] cbsz:4 abid:15
	s_waitcnt vmcnt(7)
; template <int DIR>
; __device__ __forceinline__ void s5_local_dir(const bf16_t* UZ, unsigned char* ws, int gw, int NGW, int lane) {
;     ...
;         for (int t = 0; t < 4; ++t) {
;             f32x4 cr = {0.f, 0.f, 0.f, 0.f}, ci = {0.f, 0.f, 0.f, 0.f};
; #pragma unroll
;             for (int m = 0; m < 4; ++m) {
;                 cr = __builtin_amdgcn_mfma_f32_16x16x16bf16_1k(Uf[m], Bre[m][t], cr, 0, 0, 0);
;                 ci = __builtin_amdgcn_mfma_f32_16x16x16bf16_1k(Uf[m], Bim[m][t], ci, 0, 0, 0);
;             }
	v_mfma_f32_4x4x4_16b_bf16 v[140:143], v[114:115], v[70:71], v[140:143] cbsz:4 abid:0
	v_mfma_f32_4x4x4_16b_bf16 v[144:147], v[114:115], v[78:79], v[144:147] cbsz:4 abid:0
	v_mfma_f32_4x4x4_16b_bf16 v[196:199], v[114:115], v[70:71], v[196:199] cbsz:4 abid:1
	v_mfma_f32_4x4x4_16b_bf16 v[200:203], v[114:115], v[78:79], v[200:203] cbsz:4 abid:1
	v_mfma_f32_4x4x4_16b_bf16 v[204:207], v[114:115], v[70:71], v[204:207] cbsz:4 abid:2
	v_mfma_f32_4x4x4_16b_bf16 v[208:211], v[114:115], v[78:79], v[208:211] cbsz:4 abid:2
	v_mfma_f32_4x4x4_16b_bf16 v[212:215], v[114:115], v[70:71], v[212:215] cbsz:4 abid:3
	v_mfma_f32_4x4x4_16b_bf16 v[216:219], v[114:115], v[78:79], v[216:219] cbsz:4 abid:3
	v_mfma_f32_4x4x4_16b_bf16 v[140:143], v[114:115], v[72:73], v[140:143] cbsz:4 abid:4
	v_mfma_f32_4x4x4_16b_bf16 v[144:147], v[114:115], v[80:81], v[144:147] cbsz:4 abid:4
	v_mfma_f32_4x4x4_16b_bf16 v[196:199], v[114:115], v[72:73], v[196:199] cbsz:4 abid:5
	v_mfma_f32_4x4x4_16b_bf16 v[200:203], v[114:115], v[80:81], v[200:203] cbsz:4 abid:5
	v_mfma_f32_4x4x4_16b_bf16 v[204:207], v[114:115], v[72:73], v[204:207] cbsz:4 abid:6
	v_mfma_f32_4x4x4_16b_bf16 v[208:211], v[114:115], v[80:81], v[208:211] cbsz:4 abid:6
	v_mfma_f32_4x4x4_16b_bf16 v[212:215], v[114:115], v[72:73], v[212:215] cbsz:4 abid:7
	v_mfma_f32_4x4x4_16b_bf16 v[216:219], v[114:115], v[80:81], v[216:219] cbsz:4 abid:7
	v_mfma_f32_4x4x4_16b_bf16 v[140:143], v[114:115], v[74:75], v[140:143] cbsz:4 abid:8
	v_mfma_f32_4x4x4_16b_bf16 v[144:147], v[114:115], v[82:83], v[144:147] cbsz:4 abid:8
	v_mfma_f32_4x4x4_16b_bf16 v[196:199], v[114:115], v[74:75], v[196:199] cbsz:4 abid:9
	v_mfma_f32_4x4x4_16b_bf16 v[200:203], v[114:115], v[82:83], v[200:203] cbsz:4 abid:9
	v_mfma_f32_4x4x4_16b_bf16 v[204:207], v[114:115], v[74:75], v[204:207] cbsz:4 abid:10
	v_mfma_f32_4x4x4_16b_bf16 v[208:211], v[114:115], v[82:83], v[208:211] cbsz:4 abid:10
	v_mfma_f32_4x4x4_16b_bf16 v[212:215], v[114:115], v[74:75], v[212:215] cbsz:4 abid:11
	v_mfma_f32_4x4x4_16b_bf16 v[216:219], v[114:115], v[82:83], v[216:219] cbsz:4 abid:11
	v_mfma_f32_4x4x4_16b_bf16 v[140:143], v[114:115], v[76:77], v[140:143] cbsz:4 abid:12
	v_mfma_f32_4x4x4_16b_bf16 v[144:147], v[114:115], v[84:85], v[144:147] cbsz:4 abid:12
	v_mfma_f32_4x4x4_16b_bf16 v[196:199], v[114:115], v[76:77], v[196:199] cbsz:4 abid:13
	v_mfma_f32_4x4x4_16b_bf16 v[200:203], v[114:115], v[84:85], v[200:203] cbsz:4 abid:13
	v_mfma_f32_4x4x4_16b_bf16 v[204:207], v[114:115], v[76:77], v[204:207] cbsz:4 abid:14
	v_mfma_f32_4x4x4_16b_bf16 v[208:211], v[114:115], v[84:85], v[208:211] cbsz:4 abid:14
	v_mfma_f32_4x4x4_16b_bf16 v[212:215], v[114:115], v[76:77], v[212:215] cbsz:4 abid:15
	v_mfma_f32_4x4x4_16b_bf16 v[216:219], v[114:115], v[84:85], v[216:219] cbsz:4 abid:15
	s_waitcnt vmcnt(6)
; template <int DIR>
; __device__ __forceinline__ void s5_local_dir(const bf16_t* UZ, unsigned char* ws, int gw, int NGW, int lane) {
;     ...
;         for (int t = 0; t < 4; ++t) {
;             f32x4 cr = {0.f, 0.f, 0.f, 0.f}, ci = {0.f, 0.f, 0.f, 0.f};
; #pragma unroll
;             for (int m = 0; m < 4; ++m) {
;                 cr = __builtin_amdgcn_mfma_f32_16x16x16bf16_1k(Uf[m], Bre[m][t], cr, 0, 0, 0);
;                 ci = __builtin_amdgcn_mfma_f32_16x16x16bf16_1k(Uf[m], Bim[m][t], ci, 0, 0, 0);
;             }
;             f32x2 s2 = {DIR ? cr[3] : cr[0], DIR ? ci[3] : ci[0]};
; #pragma unroll
;             for (int ii = 1; ii < 4; ++ii) { const int i = DIR ? 3 - ii : ii;
;                 s2 = cmac(s2, (f32x2){a1r[t], a1r[t]}, (f32x2){-a1i[t], a1i[t]}, (f32x2){cr[i], ci[i]}); }
;             s2 = cmac(s2, (f32x2){wr_[t], wr_[t]}, (f32x2){-wi_[t], wi_[t]}, (f32x2){0.f, 0.f});
;             float sr = s2.x, si = s2.y;
;             sr += __shfl_xor(sr, 16); si += __shfl_xor(si, 16); sr += __shfl_xor(sr, 32); si += __shfl_xor(si, 32);
;             if (fq == 0) { e[16 * t + fr] = Rr[t]; e[64 + 16 * t + fr] = Ri[t]; }
;             const float nr = fmaf(a64r[t], Rr[t], fmaf(-a64i[t], Ri[t], sr)), ni = fmaf(a64r[t], Ri[t], fmaf(a64i[t], Rr[t], si)); Rr[t] = nr; Ri[t] = ni;
;         }
	v_mfma_f32_4x4x4_16b_bf16 v[140:143], v[108:109], v[92:93], v[140:143] cbsz:4 abid:0
	v_mfma_f32_4x4x4_16b_bf16 v[144:147], v[108:109], v[100:101], v[144:147] cbsz:4 abid:0
	v_mfma_f32_4x4x4_16b_bf16 v[196:199], v[108:109], v[92:93], v[196:199] cbsz:4 abid:1
	v_mfma_f32_4x4x4_16b_bf16 v[200:203], v[108:109], v[100:101], v[200:203] cbsz:4 abid:1
	v_mfma_f32_4x4x4_16b_bf16 v[204:207], v[108:109], v[92:93], v[204:207] cbsz:4 abid:2
	v_mfma_f32_4x4x4_16b_bf16 v[208:211], v[108:109], v[100:101], v[208:211] cbsz:4 abid:2
	v_mfma_f32_4x4x4_16b_bf16 v[212:215], v[108:109], v[92:93], v[212:215] cbsz:4 abid:3
	v_mfma_f32_4x4x4_16b_bf16 v[216:219], v[108:109], v[100:101], v[216:219] cbsz:4 abid:3
	v_mfma_f32_4x4x4_16b_bf16 v[140:143], v[108:109], v[94:95], v[140:143] cbsz:4 abid:4
	v_mfma_f32_4x4x4_16b_bf16 v[144:147], v[108:109], v[102:103], v[144:147] cbsz:4 abid:4
	v_mfma_f32_4x4x4_16b_bf16 v[196:199], v[108:109], v[94:95], v[196:199] cbsz:4 abid:5
	v_mfma_f32_4x4x4_16b_bf16 v[200:203], v[108:109], v[102:103], v[200:203] cbsz:4 abid:5
	v_mfma_f32_4x4x4_16b_bf16 v[204:207], v[108:109], v[94:95], v[204:207] cbsz:4 abid:6
	v_mfma_f32_4x4x4_16b_bf16 v[208:211], v[108:109], v[102:103], v[208:211] cbsz:4 abid:6
	v_mfma_f32_4x4x4_16b_bf16 v[212:215], v[108:109], v[94:95], v[212:215] cbsz:4 abid:7
	v_mfma_f32_4x4x4_16b_bf16 v[216:219], v[108:109], v[102:103], v[216:219] cbsz:4 abid:7
	v_mfma_f32_4x4x4_16b_bf16 v[140:143], v[108:109], v[96:97], v[140:143] cbsz:4 abid:8
	v_mfma_f32_4x4x4_16b_bf16 v[144:147], v[108:109], v[104:105], v[144:147] cbsz:4 abid:8
	v_mfma_f32_4x4x4_16b_bf16 v[196:199], v[108:109], v[96:97], v[196:199] cbsz:4 abid:9
	v_mfma_f32_4x4x4_16b_bf16 v[200:203], v[108:109], v[104:105], v[200:203] cbsz:4 abid:9
	v_mfma_f32_4x4x4_16b_bf16 v[204:207], v[108:109], v[96:97], v[204:207] cbsz:4 abid:10
	v_mfma_f32_4x4x4_16b_bf16 v[208:211], v[108:109], v[104:105], v[208:211] cbsz:4 abid:10
	v_mfma_f32_4x4x4_16b_bf16 v[212:215], v[108:109], v[96:97], v[212:215] cbsz:4 abid:11
	v_mfma_f32_4x4x4_16b_bf16 v[216:219], v[108:109], v[104:105], v[216:219] cbsz:4 abid:11
	v_mfma_f32_4x4x4_16b_bf16 v[140:143], v[108:109], v[98:99], v[140:143] cbsz:4 abid:12
	v_mfma_f32_4x4x4_16b_bf16 v[144:147], v[108:109], v[106:107], v[144:147] cbsz:4 abid:12
	v_mfma_f32_4x4x4_16b_bf16 v[196:199], v[108:109], v[98:99], v[196:199] cbsz:4 abid:13
	v_mfma_f32_4x4x4_16b_bf16 v[200:203], v[108:109], v[106:107], v[200:203] cbsz:4 abid:13
	v_mfma_f32_4x4x4_16b_bf16 v[204:207], v[108:109], v[98:99], v[204:207] cbsz:4 abid:14
	v_mfma_f32_4x4x4_16b_bf16 v[208:211], v[108:109], v[106:107], v[208:211] cbsz:4 abid:14
	v_mfma_f32_4x4x4_16b_bf16 v[212:215], v[108:109], v[98:99], v[212:215] cbsz:4 abid:15
	v_mfma_f32_4x4x4_16b_bf16 v[216:219], v[108:109], v[106:107], v[216:219] cbsz:4 abid:15
	s_nop 4
	v_fma_f32 v214, v246, v215, v214
	v_fma_f32 v218, v246, v219, v218
	v_fma_f32 v214, v248, v219, v214
	v_fma_f32 v218, v247, v215, v218
	v_fma_f32 v213, v246, v214, v213
	v_fma_f32 v217, v246, v218, v217
	v_fma_f32 v213, v248, v218, v213
	v_fma_f32 v217, v247, v214, v217
	v_fma_f32 v212, v246, v213, v212
	v_fma_f32 v216, v246, v217, v216
	v_fma_f32 v212, v248, v217, v212
	v_fma_f32 v216, v247, v213, v216
	v_fma_f32 v207, v246, v212, v207
	v_fma_f32 v211, v246, v216, v211
	v_fma_f32 v207, v248, v216, v207
	v_fma_f32 v211, v247, v212, v211
	v_fma_f32 v206, v246, v207, v206
	v_fma_f32 v210, v246, v211, v210
	v_fma_f32 v206, v248, v211, v206
	v_fma_f32 v210, v247, v207, v210
	v_fma_f32 v205, v246, v206, v205
	v_fma_f32 v209, v246, v210, v209
	v_fma_f32 v205, v248, v210, v205
	v_fma_f32 v209, v247, v206, v209
	v_fma_f32 v204, v246, v205, v204
	v_fma_f32 v208, v246, v209, v208
	v_fma_f32 v204, v248, v209, v204
	v_fma_f32 v208, v247, v205, v208
	v_fma_f32 v199, v246, v204, v199
	v_fma_f32 v203, v246, v208, v203
	v_fma_f32 v199, v248, v208, v199
	v_fma_f32 v203, v247, v204, v203
	v_fma_f32 v198, v246, v199, v198
	v_fma_f32 v202, v246, v203, v202
	v_fma_f32 v198, v248, v203, v198
	v_fma_f32 v202, v247, v199, v202
	v_fma_f32 v197, v246, v198, v197
	v_fma_f32 v201, v246, v202, v201
	v_fma_f32 v197, v248, v202, v197
	v_fma_f32 v201, v247, v198, v201
	v_fma_f32 v196, v246, v197, v196
	v_fma_f32 v200, v246, v201, v200
	v_fma_f32 v196, v248, v201, v196
	v_fma_f32 v200, v247, v197, v200
	v_fma_f32 v143, v246, v196, v143
	v_fma_f32 v147, v246, v200, v147
	v_fma_f32 v143, v248, v200, v143
	v_fma_f32 v147, v247, v196, v147
	v_fma_f32 v142, v246, v143, v142
	v_fma_f32 v146, v246, v147, v146
	v_fma_f32 v142, v248, v147, v142
	v_fma_f32 v146, v247, v143, v146
	v_fma_f32 v141, v246, v142, v141
	v_fma_f32 v145, v246, v146, v145
	v_fma_f32 v141, v248, v146, v141
	v_fma_f32 v145, v247, v142, v145
	v_fma_f32 v140, v246, v141, v140
	v_fma_f32 v144, v246, v145, v144
	v_fma_f32 v140, v248, v145, v140
	v_fma_f32 v144, v247, v141, v144
	v_fma_f32 v244, -v243, v241, v140
	v_fma_f32 v245, v243, v240, v144
	v_fma_f32 v240, v242, v240, v244
	v_fma_f32 v241, v242, v241, v245
	v_lshl_add_u64 v[116:117], v[116:117], 0, s[2:3]
	v_subrev_u32_e32 v16, 64, v16
	s_and_b64 vcc, exec, s[36:37]
	s_cbranch_vccnz .LBB0_684
	s_mov_b32 s38, s49
	s_waitcnt vmcnt(3)
	v_mov_b32_e32 v110, v118
	v_mov_b32_e32 v111, v119
	s_waitcnt vmcnt(2)
	v_mov_b32_e32 v112, v120
	v_mov_b32_e32 v113, v121
	s_waitcnt vmcnt(1)
	v_mov_b32_e32 v114, v122
	v_mov_b32_e32 v115, v123
	s_waitcnt vmcnt(0)
	v_mov_b32_e32 v108, v124
	v_mov_b32_e32 v109, v125
	s_branch .LBB0_649

; template <int DIR>
; __device__ __forceinline__ void s5_local_dir(const bf16_t* UZ, unsigned char* ws, int gw, int NGW, int lane) {
;     ...
;     for (int t = 0; t < 4; ++t) {
;         const int p = 16 * t + fr;
;         const bf16x4 b_re = *(const bf16x4*)(Bb + (2 * p) * 16 + 4 * fq), b_im = *(const bf16x4*)(Bb + (2 * p + 1) * 16 + 4 * fq);
;         const f32x4 ap = ((const f32x4*)(ws + WS_APOW))[pair * 64 + p];
;         const float ar = ap.x, ai = ap.y;
;         float r2 = ar, i2 = ai; cmul(r2, i2, ar, ai);
;         float r4 = r2, i4 = i2; cmul(r4, i4, r2, i2);
;         float r8 = r4, i8 = i4; cmul(r8, i8, r4, i4);
;         float r12 = r8, i12 = i8; cmul(r12, i12, r4, i4);
;         float r16 = r8, i16 = i8; cmul(r16, i16, r8, i8);
;     ...
;     const int qd = gw >> 7, b = qd >> 2, q = qd & 3;
;     if (qd >= 16) return;
;     const int c0 = 17 * q, c1 = q < 3 ? c0 + 17 : 67;
;     float Rr[4] = {0.f, 0.f, 0.f, 0.f}, Ri[4] = {0.f, 0.f, 0.f, 0.f};
;     float* ebase = E + ((size_t)((b * 2 + DIR) * 64 + g) * NCHUNK) * 128;
;     bf16x4 Un[4];
;     load_uf(Un, UZ, chunk_rowbase(b, DIR, c0), g, lane);
;     for (int c = c0; c < c1; ++c) {
;         bf16x4 Uf[4];
; #pragma unroll
;         for (int m = 0; m < 4; ++m) Uf[m] = Un[m];
;         if (c + 1 < c1) load_uf(Un, UZ, chunk_rowbase(b, DIR, c + 1), g, lane);
.LBB0_669:
	s_mul_i32 s24, s37, 17
	s_add_i32 s4, s24, 17
	s_cmp_lg_u32 s37, 3
	s_cselect_b64 s[8:9], -1, 0
	s_and_b64 s[2:3], s[8:9], exec
	s_cselect_b32 s39, s4, 0x43
	s_lshl_b32 s38, s23, 7
	v_mov_b32_e32 v115, 0
	v_mov_b32_e32 v240, 0
	v_mov_b32_e32 v241, 0
	s_cmp_ge_u32 s24, s39
	v_mov_b32_e32 v114, 0
	v_mov_b32_e32 v112, 0
	v_mov_b32_e32 v110, 0
	v_mov_b32_e32 v113, 0
	v_mov_b32_e32 v111, 0
	v_mov_b32_e32 v109, 0
	v_mov_b32_e32 v108, 0
	s_cbranch_scc1 .LBB0_702
	s_lshl_b32 s100, s36, 5
	s_add_u32 s100, s18, s100
	s_addc_u32 s101, s19, 0
	v_add_u32_e32 v160, s25, v127
	v_ashrrev_i32_e32 v161, 31, v160
	v_lshlrev_b64 v[162:163], 12, v[160:161]
	v_lshrrev_b32_e32 v164, 1, v192
	v_and_b32_e32 v164, 24, v164
	v_mov_b32_e32 v165, 0
	v_lshl_add_u64 v[162:163], s[100:101], 0, v[162:163]
	v_lshl_add_u64 v[162:163], v[162:163], 0, v[164:165]
	s_mov_b32 s98, 0x10000
	s_mov_b32 s99, 0
	v_lshl_add_u64 v[164:165], v[162:163], 0, s[98:99]
	v_lshl_add_u64 v[166:167], v[164:165], 0, s[98:99]
	v_lshl_add_u64 v[168:169], v[166:167], 0, s[98:99]
	global_load_dwordx2 v[152:153], v[162:163], off
	global_load_dwordx2 v[154:155], v[164:165], off
	global_load_dwordx2 v[156:157], v[166:167], off
	global_load_dwordx2 v[158:159], v[168:169], off
	s_waitcnt vmcnt(13)
	v_pk_mul_f32 v[22:23], v[0:1], v[0:1] op_sel:[1,1] op_sel_hi:[1,0]
	s_lshl_b32 s2, s36, 5
	v_pk_fma_f32 v[24:25], v[0:1], v[0:1], v[22:23] op_sel_hi:[1,0,1] neg_lo:[0,0,1] neg_hi:[0,0,1]
	v_pk_fma_f32 v[22:23], v[0:1], v[0:1], v[22:23] op_sel_hi:[1,0,1]
	v_mov_b32_e32 v30, v24
	v_pk_mov_b32 v[32:33], v[22:23], v[24:25] op_sel:[1,0]
	v_mov_b32_e32 v31, v23
	v_pk_mul_f32 v[22:23], v[22:23], v[32:33] op_sel:[1,0]
	v_mov_b32_e32 v18, v0
	v_pk_fma_f32 v[32:33], v[24:25], v[30:31], v[22:23] op_sel_hi:[0,1,1] neg_lo:[0,0,1] neg_hi:[0,0,1]
	v_pk_fma_f32 v[22:23], v[24:25], v[30:31], v[22:23] op_sel_hi:[0,1,1]
	v_pk_mov_b32 v[30:31], v[22:23], v[32:33] op_sel:[1,0]
	v_mov_b32_e32 v24, v32
	v_mov_b32_e32 v25, v23
	v_pk_mul_f32 v[30:31], v[22:23], v[30:31] op_sel:[1,0]
	v_mov_b32_e32 v19, v0
	v_pk_fma_f32 v[34:35], v[32:33], v[24:25], v[30:31] op_sel_hi:[0,1,1] neg_lo:[0,0,1] neg_hi:[0,0,1]
	v_pk_fma_f32 v[30:31], v[32:33], v[24:25], v[30:31] op_sel_hi:[0,1,1]
	v_mov_b32_e32 v35, v31
	v_pk_mul_f32 v[36:37], v[34:35], v[34:35]
	v_pk_mul_f32 v[38:39], v[30:31], v[34:35] op_sel:[1,0] op_sel_hi:[0,1]
	v_mov_b32_e32 v40, v36
	v_mov_b32_e32 v41, v38
	v_pk_mov_b32 v[36:37], v[36:37], v[38:39] op_sel:[1,0]
	s_add_u32 s2, s18, s2
	v_pk_add_f32 v[38:39], v[40:41], v[36:37] neg_lo:[0,1] neg_hi:[0,1]
	v_pk_add_f32 v[36:37], v[40:41], v[36:37]
	v_mov_b32_e32 v40, v38
	v_mov_b32_e32 v41, v37
	v_pk_mul_f32 v[44:45], v[40:41], v[40:41]
	v_pk_mul_f32 v[46:47], v[36:37], v[40:41] op_sel:[1,0] op_sel_hi:[0,1]
	v_mov_b32_e32 v52, v44
	v_mov_b32_e32 v53, v46
	v_pk_mov_b32 v[44:45], v[44:45], v[46:47] op_sel:[1,0]
	v_lshrrev_b32_e32 v16, 1, v192
	v_pk_add_f32 v[46:47], v[52:53], v[44:45] neg_lo:[0,1] neg_hi:[0,1]
	v_pk_add_f32 v[44:45], v[52:53], v[44:45]
	v_mov_b32_e32 v52, v46
	v_mov_b32_e32 v53, v45
	v_mul_f32_e32 v0, v37, v45
	v_pk_mov_b32 v[42:43], v[36:37], v[38:39] op_sel:[1,0]
	v_pk_fma_f32 v[40:41], v[40:41], v[52:53], v[0:1] op_sel_hi:[1,1,0] neg_lo:[0,0,1] neg_hi:[0,0,1]
	v_mul_f32_e32 v0, v38, v45
	s_addc_u32 s3, s19, 0
	v_and_b32_e32 v20, 24, v16
	v_mov_b32_e32 v21, 0
	v_pk_fma_f32 v[42:43], v[42:43], v[52:53], v[0:1] op_sel_hi:[1,1,0]
	v_mul_f32_e32 v0, v23, v34
	v_pk_mul_f32 v[24:25], v[24:25], v[34:35]
	v_and_b32_e32 v59, 0xffff0000, v27
	v_lshlrev_b32_e32 v58, 16, v27
	v_lshl_add_u64 v[16:17], s[2:3], 0, v[20:21]
	v_fmac_f32_e32 v0, v32, v31
	v_sub_f32_e32 v20, v24, v25
	v_cmp_eq_u32_e32 vcc, 1, v128
	v_and_b32_e32 v53, 0xffff0000, v28
	v_lshlrev_b32_e32 v52, 16, v28
	v_and_b32_e32 v55, 0xffff0000, v26
	v_lshlrev_b32_e32 v54, 16, v26
	v_and_b32_e32 v57, 0xffff0000, v29
	v_lshlrev_b32_e32 v56, 16, v29
	v_pk_mul_f32 v[28:29], v[42:43], v[58:59] op_sel_hi:[0,1]
	v_cndmask_b32_e32 v20, v20, v34, vcc
	v_cmp_eq_u32_e64 s[2:3], 2, v128
	v_cndmask_b32_e32 v0, v0, v31, vcc
	v_pk_mul_f32 v[26:27], v[42:43], v[54:55] op_sel_hi:[0,1]
	v_pk_fma_f32 v[28:29], v[40:41], v[56:57], v[28:29] op_sel_hi:[0,1,1] neg_lo:[0,0,1] neg_hi:[0,0,1]
	v_pk_mul_f32 v[30:31], v[42:43], v[56:57] op_sel_hi:[0,1]
	v_cndmask_b32_e64 v20, v20, v32, s[2:3]
	v_cndmask_b32_e64 v0, v0, v23, s[2:3]
	v_cmp_eq_u32_e64 s[4:5], 3, v128
	v_pk_fma_f32 v[26:27], v[40:41], v[52:53], v[26:27] op_sel_hi:[0,1,1] neg_lo:[0,0,1] neg_hi:[0,0,1]
	v_cvt_pk_bf16_f32 v23, v28, s0
	v_cvt_pk_bf16_f32 v24, v29, s0
	s_mov_b32 s41, 0x5040100
	v_pk_mul_f32 v[28:29], v[42:43], v[52:53] op_sel_hi:[0,1]
	v_pk_fma_f32 v[30:31], v[40:41], v[58:59], v[30:31] op_sel_hi:[0,1,1]
	v_pk_mul_f32 v[32:33], v[44:45], v[58:59] op_sel:[1,0]
	v_cndmask_b32_e64 v22, v20, 1.0, s[4:5]
	v_cndmask_b32_e64 v25, v0, 0, s[4:5]
	v_cvt_pk_bf16_f32 v0, v26, s0
	v_cvt_pk_bf16_f32 v20, v27, s0
	v_perm_b32 v27, v24, v23, s41
	v_pk_fma_f32 v[28:29], v[40:41], v[54:55], v[28:29] op_sel_hi:[0,1,1]
	v_cvt_pk_bf16_f32 v23, v30, s0
	v_cvt_pk_bf16_f32 v24, v31, s0
	v_pk_mul_f32 v[30:31], v[44:45], v[54:55] op_sel:[1,0]
	v_pk_fma_f32 v[32:33], v[46:47], v[56:57], v[32:33] op_sel_hi:[0,1,1] neg_lo:[0,0,1] neg_hi:[0,0,1]
	v_pk_mul_f32 v[34:35], v[44:45], v[56:57] op_sel:[1,0]
	v_perm_b32 v26, v20, v0, s41
	v_cvt_pk_bf16_f32 v0, v28, s0
	v_cvt_pk_bf16_f32 v20, v29, s0
	v_perm_b32 v29, v24, v23, s41
	v_pk_fma_f32 v[30:31], v[46:47], v[52:53], v[30:31] op_sel_hi:[0,1,1] neg_lo:[0,0,1] neg_hi:[0,0,1]
	v_cvt_pk_bf16_f32 v23, v32, s0
	v_cvt_pk_bf16_f32 v24, v33, s0
	v_pk_mul_f32 v[32:33], v[44:45], v[52:53] op_sel:[1,0]
	v_pk_fma_f32 v[34:35], v[46:47], v[58:59], v[34:35] op_sel_hi:[0,1,1]
	v_pk_mul_f32 v[40:41], v[36:37], v[58:59] op_sel:[1,0]
	v_perm_b32 v28, v20, v0, s41
	v_cvt_pk_bf16_f32 v0, v30, s0
	v_cvt_pk_bf16_f32 v20, v31, s0
	v_perm_b32 v31, v24, v23, s41
	v_pk_fma_f32 v[32:33], v[46:47], v[54:55], v[32:33] op_sel_hi:[0,1,1]
	v_cvt_pk_bf16_f32 v23, v34, s0
	v_cvt_pk_bf16_f32 v24, v35, s0
	v_pk_fma_f32 v[40:41], v[38:39], v[56:57], v[40:41] op_sel_hi:[0,1,1] neg_lo:[0,0,1] neg_hi:[0,0,1]
	s_waitcnt vmcnt(10)
; template <int DIR>
; __device__ __forceinline__ void s5_local_dir(const bf16_t* UZ, unsigned char* ws, int gw, int NGW, int lane) {
;     ...
;     for (int t = 0; t < 4; ++t) {
;         const int p = 16 * t + fr;
;         const bf16x4 b_re = *(const bf16x4*)(Bb + (2 * p) * 16 + 4 * fq), b_im = *(const bf16x4*)(Bb + (2 * p + 1) * 16 + 4 * fq);
;         const f32x4 ap = ((const f32x4*)(ws + WS_APOW))[pair * 64 + p];
;         const float ar = ap.x, ai = ap.y;
;         float r2 = ar, i2 = ai; cmul(r2, i2, ar, ai);
;         float r4 = r2, i4 = i2; cmul(r4, i4, r2, i2);
;         float r8 = r4, i8 = i4; cmul(r8, i8, r4, i4);
;         float r12 = r8, i12 = i8; cmul(r12, i12, r4, i4);
;         float r16 = r8, i16 = i8; cmul(r16, i16, r8, i8);
;         float r32 = r16, i32 = i16; cmul(r32, i32, r16, i16);
;         float r48 = r32, i48 = i32; cmul(r48, i48, r16, i16);
;         a1r[t] = ar; a1i[t] = ai; a64r[t] = ap.z; a64i[t] = ap.w;
;         const int e = DIR ? fq : 3 - fq;
;         wr_[t] = e == 0 ? 1.f : e == 1 ? r4 : e == 2 ? r8 : r12; wi_[t] = e == 0 ? 0.f : e == 1 ? i4 : e == 2 ? i8 : i12;
; #pragma unroll
;         for (int m = 0; m < 4; ++m) {
;             const int em = DIR ? m : 3 - m;
;             const float pr = em == 0 ? 1.f : em == 1 ? r16 : em == 2 ? r32 : r48, pi = em == 0 ? 0.f : em == 1 ? i16 : em == 2 ? i32 : i48;
;             Bre[m][t] = cscale_bf(b_re, b_im, pr, pi, false); Bim[m][t] = cscale_bf(b_re, b_im, pr, pi, true);
;         }
	v_pk_mul_f32 v[44:45], v[4:5], v[4:5] op_sel:[1,1] op_sel_hi:[1,0]
	v_perm_b32 v30, v20, v0, s41
	v_cvt_pk_bf16_f32 v20, v33, s0
	v_perm_b32 v33, v24, v23, s41
	v_pk_mul_f32 v[34:35], v[36:37], v[54:55] op_sel:[1,0]
	v_cvt_pk_bf16_f32 v23, v40, s0
	v_cvt_pk_bf16_f32 v24, v41, s0
	v_pk_mul_f32 v[40:41], v[36:37], v[52:53] op_sel:[1,0]
	v_pk_mul_f32 v[36:37], v[36:37], v[56:57] op_sel:[1,0]
	v_pk_fma_f32 v[46:47], v[4:5], v[4:5], v[44:45] op_sel_hi:[1,0,1] neg_lo:[0,0,1] neg_hi:[0,0,1]
	v_pk_fma_f32 v[44:45], v[4:5], v[4:5], v[44:45] op_sel_hi:[1,0,1]
	v_pk_fma_f32 v[34:35], v[38:39], v[52:53], v[34:35] op_sel_hi:[0,1,1] neg_lo:[0,0,1] neg_hi:[0,0,1]
	v_pk_fma_f32 v[36:37], v[38:39], v[58:59], v[36:37] op_sel_hi:[0,1,1]
	v_pk_fma_f32 v[38:39], v[38:39], v[54:55], v[40:41] op_sel_hi:[0,1,1]
	v_xor_b32_e32 v41, 0x80000000, v55
	v_xor_b32_e32 v40, 0x80000000, v54
	v_pk_fma_f32 v[42:43], v[52:53], 0, v[54:55] op_sel_hi:[1,0,1]
	v_pk_mov_b32 v[54:55], v[44:45], v[46:47] op_sel:[1,0]
	v_pk_fma_f32 v[40:41], v[40:41], 0, v[52:53] op_sel_hi:[1,0,1]
	v_mov_b32_e32 v52, v46
	v_mov_b32_e32 v53, v45
	v_pk_mul_f32 v[44:45], v[44:45], v[54:55] op_sel:[1,0]
	v_cvt_pk_bf16_f32 v0, v32, s0
	v_pk_fma_f32 v[54:55], v[46:47], v[52:53], v[44:45] op_sel_hi:[0,1,1] neg_lo:[0,0,1] neg_hi:[0,0,1]
	v_pk_fma_f32 v[44:45], v[46:47], v[52:53], v[44:45] op_sel_hi:[0,1,1]
	v_perm_b32 v32, v20, v0, s41
	v_cvt_pk_bf16_f32 v0, v34, s0
	v_cvt_pk_bf16_f32 v20, v35, s0
	v_pk_mov_b32 v[52:53], v[44:45], v[54:55] op_sel:[1,0]
	v_perm_b32 v34, v20, v0, s41
	v_cvt_pk_bf16_f32 v0, v38, s0
	v_cvt_pk_bf16_f32 v20, v39, s0
	v_xor_b32_e32 v39, 0x80000000, v59
	v_xor_b32_e32 v38, 0x80000000, v58
	v_mov_b32_e32 v46, v54
	v_mov_b32_e32 v47, v45
	v_pk_mul_f32 v[52:53], v[44:45], v[52:53] op_sel:[1,0]
	v_perm_b32 v35, v24, v23, s41
	v_cvt_pk_bf16_f32 v23, v36, s0
	v_perm_b32 v36, v20, v0, s41
	v_pk_fma_f32 v[38:39], v[38:39], 0, v[56:57] op_sel_hi:[1,0,1]
	v_cvt_pk_bf16_f32 v0, v40, s0
	v_cvt_pk_bf16_f32 v20, v41, s0
	v_pk_fma_f32 v[40:41], v[56:57], 0, v[58:59] op_sel_hi:[1,0,1]
	v_pk_fma_f32 v[56:57], v[54:55], v[46:47], v[52:53] op_sel_hi:[0,1,1] neg_lo:[0,0,1] neg_hi:[0,0,1]
	v_pk_fma_f32 v[52:53], v[54:55], v[46:47], v[52:53] op_sel_hi:[0,1,1]
	v_mov_b32_e32 v57, v53
	v_pk_mul_f32 v[58:59], v[56:57], v[56:57]
	v_pk_mul_f32 v[60:61], v[52:53], v[56:57] op_sel:[1,0] op_sel_hi:[0,1]
	v_mov_b32_e32 v62, v58
	v_mov_b32_e32 v63, v60
	v_pk_mov_b32 v[58:59], v[58:59], v[60:61] op_sel:[1,0]
	v_cvt_pk_bf16_f32 v24, v37, s0
	v_pk_add_f32 v[60:61], v[62:63], v[58:59] neg_lo:[0,1] neg_hi:[0,1]
	v_pk_add_f32 v[58:59], v[62:63], v[58:59]
	v_mov_b32_e32 v62, v60
	v_mov_b32_e32 v63, v59
	v_pk_mul_f32 v[66:67], v[62:63], v[62:63]
	v_pk_mul_f32 v[68:69], v[58:59], v[62:63] op_sel:[1,0] op_sel_hi:[0,1]
	v_mov_b32_e32 v74, v66
	v_mov_b32_e32 v75, v68
	v_pk_mov_b32 v[66:67], v[66:67], v[68:69] op_sel:[1,0]
	v_perm_b32 v37, v24, v23, s41
	v_cvt_pk_bf16_f32 v23, v38, s0
	v_cvt_pk_bf16_f32 v24, v39, s0
	v_perm_b32 v38, v20, v0, s41
	v_cvt_pk_bf16_f32 v0, v42, s0
	v_cvt_pk_bf16_f32 v20, v43, s0
	v_pk_add_f32 v[68:69], v[74:75], v[66:67] neg_lo:[0,1] neg_hi:[0,1]
	v_pk_add_f32 v[66:67], v[74:75], v[66:67]
	v_perm_b32 v39, v24, v23, s41
	v_cvt_pk_bf16_f32 v23, v40, s0
	v_perm_b32 v40, v20, v0, s41
	v_mov_b32_e32 v74, v68
	v_mov_b32_e32 v75, v67
	v_mul_f32_e32 v0, v59, v67
	v_pk_mov_b32 v[64:65], v[58:59], v[60:61] op_sel:[1,0]
	v_pk_fma_f32 v[62:63], v[62:63], v[74:75], v[0:1] op_sel_hi:[1,1,0] neg_lo:[0,0,1] neg_hi:[0,0,1]
	v_mul_f32_e32 v0, v60, v67
	v_pk_fma_f32 v[64:65], v[64:65], v[74:75], v[0:1] op_sel_hi:[1,1,0]
	v_mul_f32_e32 v0, v45, v56
	v_pk_mul_f32 v[46:47], v[46:47], v[56:57]
	v_and_b32_e32 v81, 0xffff0000, v51
	v_lshlrev_b32_e32 v80, 16, v51
	v_mov_b32_e32 v42, v4
	v_mov_b32_e32 v43, v4
	v_fmac_f32_e32 v0, v54, v53
	v_sub_f32_e32 v4, v46, v47
	v_and_b32_e32 v77, 0xffff0000, v50
	v_lshlrev_b32_e32 v76, 16, v50
	v_and_b32_e32 v79, 0xffff0000, v49
	v_lshlrev_b32_e32 v78, 16, v49
	v_pk_mul_f32 v[50:51], v[64:65], v[80:81] op_sel_hi:[0,1]
	v_cvt_pk_bf16_f32 v24, v41, s0
	v_cndmask_b32_e32 v4, v4, v56, vcc
	v_cndmask_b32_e32 v0, v0, v53, vcc
	v_and_b32_e32 v75, 0xffff0000, v48
	v_lshlrev_b32_e32 v74, 16, v48
	v_pk_mul_f32 v[48:49], v[64:65], v[76:77] op_sel_hi:[0,1]
	v_pk_fma_f32 v[50:51], v[62:63], v[78:79], v[50:51] op_sel_hi:[0,1,1] neg_lo:[0,0,1] neg_hi:[0,0,1]
	v_pk_mul_f32 v[52:53], v[64:65], v[78:79] op_sel_hi:[0,1]
	v_perm_b32 v41, v24, v23, s41
	v_cndmask_b32_e64 v4, v4, v54, s[2:3]
	v_cndmask_b32_e64 v0, v0, v45, s[2:3]
	v_pk_fma_f32 v[48:49], v[62:63], v[74:75], v[48:49] op_sel_hi:[0,1,1] neg_lo:[0,0,1] neg_hi:[0,0,1]
	v_cvt_pk_bf16_f32 v20, v50, s0
	v_cvt_pk_bf16_f32 v23, v51, s0
	v_pk_mul_f32 v[50:51], v[64:65], v[74:75] op_sel_hi:[0,1]
	v_pk_fma_f32 v[52:53], v[62:63], v[80:81], v[52:53] op_sel_hi:[0,1,1]
	v_pk_mul_f32 v[54:55], v[66:67], v[80:81] op_sel:[1,0]
	v_cndmask_b32_e64 v44, v4, 1.0, s[4:5]
	v_cndmask_b32_e64 v47, v0, 0, s[4:5]
	v_cvt_pk_bf16_f32 v0, v48, s0
	v_cvt_pk_bf16_f32 v4, v49, s0
	v_perm_b32 v49, v23, v20, s41
	v_pk_fma_f32 v[50:51], v[62:63], v[76:77], v[50:51] op_sel_hi:[0,1,1]
	v_cvt_pk_bf16_f32 v20, v52, s0
	v_cvt_pk_bf16_f32 v23, v53, s0
	v_pk_mul_f32 v[52:53], v[66:67], v[76:77] op_sel:[1,0]
	v_pk_fma_f32 v[54:55], v[68:69], v[78:79], v[54:55] op_sel_hi:[0,1,1] neg_lo:[0,0,1] neg_hi:[0,0,1]
	v_pk_mul_f32 v[56:57], v[66:67], v[78:79] op_sel:[1,0]
	v_perm_b32 v48, v4, v0, s41
	v_cvt_pk_bf16_f32 v0, v50, s0
	v_cvt_pk_bf16_f32 v4, v51, s0
	v_perm_b32 v51, v23, v20, s41
	v_pk_fma_f32 v[52:53], v[68:69], v[74:75], v[52:53] op_sel_hi:[0,1,1] neg_lo:[0,0,1] neg_hi:[0,0,1]
	v_cvt_pk_bf16_f32 v20, v54, s0
	v_cvt_pk_bf16_f32 v23, v55, s0
	v_pk_mul_f32 v[54:55], v[66:67], v[74:75] op_sel:[1,0]
	v_pk_fma_f32 v[56:57], v[68:69], v[80:81], v[56:57] op_sel_hi:[0,1,1]
	v_pk_mul_f32 v[62:63], v[58:59], v[80:81] op_sel:[1,0]
	v_perm_b32 v50, v4, v0, s41
	v_cvt_pk_bf16_f32 v0, v52, s0
	v_cvt_pk_bf16_f32 v4, v53, s0
	v_perm_b32 v53, v23, v20, s41
	v_pk_fma_f32 v[54:55], v[68:69], v[76:77], v[54:55] op_sel_hi:[0,1,1]
	v_cvt_pk_bf16_f32 v20, v56, s0
	v_cvt_pk_bf16_f32 v23, v57, s0
	v_pk_fma_f32 v[62:63], v[60:61], v[78:79], v[62:63] op_sel_hi:[0,1,1] neg_lo:[0,0,1] neg_hi:[0,0,1]
	s_waitcnt vmcnt(7)
; template <int DIR>
; __device__ __forceinline__ void s5_local_dir(const bf16_t* UZ, unsigned char* ws, int gw, int NGW, int lane) {
;     ...
;     for (int t = 0; t < 4; ++t) {
;         const int p = 16 * t + fr;
;         const bf16x4 b_re = *(const bf16x4*)(Bb + (2 * p) * 16 + 4 * fq), b_im = *(const bf16x4*)(Bb + (2 * p + 1) * 16 + 4 * fq);
;         const f32x4 ap = ((const f32x4*)(ws + WS_APOW))[pair * 64 + p];
;         const float ar = ap.x, ai = ap.y;
;         float r2 = ar, i2 = ai; cmul(r2, i2, ar, ai);
;         float r4 = r2, i4 = i2; cmul(r4, i4, r2, i2);
;         float r8 = r4, i8 = i4; cmul(r8, i8, r4, i4);
;         float r12 = r8, i12 = i8; cmul(r12, i12, r4, i4);
;         float r16 = r8, i16 = i8; cmul(r16, i16, r8, i8);
;         float r32 = r16, i32 = i16; cmul(r32, i32, r16, i16);
;         float r48 = r32, i48 = i32; cmul(r48, i48, r16, i16);
;         a1r[t] = ar; a1i[t] = ai; a64r[t] = ap.z; a64i[t] = ap.w;
;         const int e = DIR ? fq : 3 - fq;
;         wr_[t] = e == 0 ? 1.f : e == 1 ? r4 : e == 2 ? r8 : r12; wi_[t] = e == 0 ? 0.f : e == 1 ? i4 : e == 2 ? i8 : i12;
; #pragma unroll
;         for (int m = 0; m < 4; ++m) {
;             const int em = DIR ? m : 3 - m;
;             const float pr = em == 0 ? 1.f : em == 1 ? r16 : em == 2 ? r32 : r48, pi = em == 0 ? 0.f : em == 1 ? i16 : em == 2 ? i32 : i48;
;             Bre[m][t] = cscale_bf(b_re, b_im, pr, pi, false); Bim[m][t] = cscale_bf(b_re, b_im, pr, pi, true);
;         }
	v_pk_mul_f32 v[66:67], v[8:9], v[8:9] op_sel:[1,1] op_sel_hi:[1,0]
	v_perm_b32 v52, v4, v0, s41
	v_cvt_pk_bf16_f32 v4, v55, s0
	v_perm_b32 v55, v23, v20, s41
	v_pk_mul_f32 v[56:57], v[58:59], v[76:77] op_sel:[1,0]
	v_cvt_pk_bf16_f32 v20, v62, s0
	v_cvt_pk_bf16_f32 v23, v63, s0
	v_pk_mul_f32 v[62:63], v[58:59], v[74:75] op_sel:[1,0]
	v_pk_mul_f32 v[58:59], v[58:59], v[78:79] op_sel:[1,0]
	v_pk_fma_f32 v[68:69], v[8:9], v[8:9], v[66:67] op_sel_hi:[1,0,1] neg_lo:[0,0,1] neg_hi:[0,0,1]
	v_pk_fma_f32 v[66:67], v[8:9], v[8:9], v[66:67] op_sel_hi:[1,0,1]
	v_pk_fma_f32 v[56:57], v[60:61], v[74:75], v[56:57] op_sel_hi:[0,1,1] neg_lo:[0,0,1] neg_hi:[0,0,1]
	v_pk_fma_f32 v[58:59], v[60:61], v[80:81], v[58:59] op_sel_hi:[0,1,1]
	v_pk_fma_f32 v[60:61], v[60:61], v[76:77], v[62:63] op_sel_hi:[0,1,1]
	v_xor_b32_e32 v63, 0x80000000, v77
	v_xor_b32_e32 v62, 0x80000000, v76
	v_pk_fma_f32 v[64:65], v[74:75], 0, v[76:77] op_sel_hi:[1,0,1]
	v_pk_mov_b32 v[76:77], v[66:67], v[68:69] op_sel:[1,0]
	v_pk_fma_f32 v[62:63], v[62:63], 0, v[74:75] op_sel_hi:[1,0,1]
	v_mov_b32_e32 v74, v68
	v_mov_b32_e32 v75, v67
	v_pk_mul_f32 v[66:67], v[66:67], v[76:77] op_sel:[1,0]
	v_cvt_pk_bf16_f32 v0, v54, s0
	v_pk_fma_f32 v[76:77], v[68:69], v[74:75], v[66:67] op_sel_hi:[0,1,1] neg_lo:[0,0,1] neg_hi:[0,0,1]
	v_pk_fma_f32 v[66:67], v[68:69], v[74:75], v[66:67] op_sel_hi:[0,1,1]
	v_perm_b32 v54, v4, v0, s41
	v_cvt_pk_bf16_f32 v0, v56, s0
	v_cvt_pk_bf16_f32 v4, v57, s0
	v_pk_mov_b32 v[74:75], v[66:67], v[76:77] op_sel:[1,0]
	v_perm_b32 v56, v4, v0, s41
	v_cvt_pk_bf16_f32 v0, v60, s0
	v_cvt_pk_bf16_f32 v4, v61, s0
	v_xor_b32_e32 v61, 0x80000000, v81
	v_xor_b32_e32 v60, 0x80000000, v80
	v_mov_b32_e32 v68, v76
	v_mov_b32_e32 v69, v67
	v_pk_mul_f32 v[74:75], v[66:67], v[74:75] op_sel:[1,0]
	v_perm_b32 v57, v23, v20, s41
	v_cvt_pk_bf16_f32 v20, v58, s0
	v_perm_b32 v58, v4, v0, s41
	v_pk_fma_f32 v[60:61], v[60:61], 0, v[78:79] op_sel_hi:[1,0,1]
	v_cvt_pk_bf16_f32 v0, v62, s0
	v_cvt_pk_bf16_f32 v4, v63, s0
	v_pk_fma_f32 v[62:63], v[78:79], 0, v[80:81] op_sel_hi:[1,0,1]
	v_pk_fma_f32 v[78:79], v[76:77], v[68:69], v[74:75] op_sel_hi:[0,1,1] neg_lo:[0,0,1] neg_hi:[0,0,1]
	v_pk_fma_f32 v[74:75], v[76:77], v[68:69], v[74:75] op_sel_hi:[0,1,1]
	v_mov_b32_e32 v79, v75
	v_pk_mul_f32 v[80:81], v[78:79], v[78:79]
	v_pk_mul_f32 v[82:83], v[74:75], v[78:79] op_sel:[1,0] op_sel_hi:[0,1]
	v_mov_b32_e32 v84, v80
	v_mov_b32_e32 v85, v82
	v_pk_mov_b32 v[80:81], v[80:81], v[82:83] op_sel:[1,0]
	v_cvt_pk_bf16_f32 v23, v59, s0
	v_pk_add_f32 v[82:83], v[84:85], v[80:81] neg_lo:[0,1] neg_hi:[0,1]
	v_pk_add_f32 v[80:81], v[84:85], v[80:81]
	v_mov_b32_e32 v84, v82
	v_mov_b32_e32 v85, v81
	v_pk_mul_f32 v[92:93], v[84:85], v[84:85]
	v_pk_mul_f32 v[94:95], v[80:81], v[84:85] op_sel:[1,0] op_sel_hi:[0,1]
	v_mov_b32_e32 v96, v92
	v_mov_b32_e32 v97, v94
	v_pk_mov_b32 v[92:93], v[92:93], v[94:95] op_sel:[1,0]
	v_perm_b32 v59, v23, v20, s41
	v_cvt_pk_bf16_f32 v20, v60, s0
	v_cvt_pk_bf16_f32 v23, v61, s0
	v_perm_b32 v60, v4, v0, s41
	v_cvt_pk_bf16_f32 v0, v64, s0
	v_cvt_pk_bf16_f32 v4, v65, s0
	v_pk_add_f32 v[94:95], v[96:97], v[92:93] neg_lo:[0,1] neg_hi:[0,1]
	v_pk_add_f32 v[92:93], v[96:97], v[92:93]
	v_perm_b32 v61, v23, v20, s41
	v_cvt_pk_bf16_f32 v20, v62, s0
	v_perm_b32 v62, v4, v0, s41
	v_mov_b32_e32 v96, v94
	v_mov_b32_e32 v97, v93
	v_mul_f32_e32 v0, v81, v93
	v_pk_mov_b32 v[86:87], v[80:81], v[82:83] op_sel:[1,0]
	v_pk_fma_f32 v[84:85], v[84:85], v[96:97], v[0:1] op_sel_hi:[1,1,0] neg_lo:[0,0,1] neg_hi:[0,0,1]
	v_mul_f32_e32 v0, v82, v93
	v_pk_fma_f32 v[86:87], v[86:87], v[96:97], v[0:1] op_sel_hi:[1,1,0]
	v_mul_f32_e32 v0, v67, v78
	v_pk_mul_f32 v[68:69], v[68:69], v[78:79]
	v_and_b32_e32 v103, 0xffff0000, v71
	v_lshlrev_b32_e32 v102, 16, v71
	v_fmac_f32_e32 v0, v76, v75
	v_sub_f32_e32 v4, v68, v69
	v_and_b32_e32 v97, 0xffff0000, v72
	v_lshlrev_b32_e32 v96, 16, v72
	v_and_b32_e32 v99, 0xffff0000, v70
	v_lshlrev_b32_e32 v98, 16, v70
	v_and_b32_e32 v101, 0xffff0000, v73
	v_lshlrev_b32_e32 v100, 16, v73
	v_pk_mul_f32 v[72:73], v[86:87], v[102:103] op_sel_hi:[0,1]
	v_cvt_pk_bf16_f32 v23, v63, s0
	v_cndmask_b32_e32 v4, v4, v78, vcc
	v_cndmask_b32_e32 v0, v0, v75, vcc
	v_pk_mul_f32 v[70:71], v[86:87], v[98:99] op_sel_hi:[0,1]
	v_pk_fma_f32 v[72:73], v[84:85], v[100:101], v[72:73] op_sel_hi:[0,1,1] neg_lo:[0,0,1] neg_hi:[0,0,1]
	v_pk_mul_f32 v[74:75], v[86:87], v[100:101] op_sel_hi:[0,1]
	v_perm_b32 v63, v23, v20, s41
	v_mov_b32_e32 v64, v8
	v_mov_b32_e32 v65, v8
	v_cndmask_b32_e64 v4, v4, v76, s[2:3]
	v_cndmask_b32_e64 v0, v0, v67, s[2:3]
	v_pk_fma_f32 v[70:71], v[84:85], v[96:97], v[70:71] op_sel_hi:[0,1,1] neg_lo:[0,0,1] neg_hi:[0,0,1]
	v_cvt_pk_bf16_f32 v8, v72, s0
	v_cvt_pk_bf16_f32 v20, v73, s0
	v_pk_mul_f32 v[72:73], v[86:87], v[96:97] op_sel_hi:[0,1]
	v_pk_fma_f32 v[74:75], v[84:85], v[102:103], v[74:75] op_sel_hi:[0,1,1]
	v_pk_mul_f32 v[76:77], v[92:93], v[102:103] op_sel:[1,0]
	v_cndmask_b32_e64 v66, v4, 1.0, s[4:5]
	v_cndmask_b32_e64 v69, v0, 0, s[4:5]
	v_cvt_pk_bf16_f32 v0, v70, s0
	v_cvt_pk_bf16_f32 v4, v71, s0
	v_perm_b32 v71, v20, v8, s41
	v_pk_fma_f32 v[72:73], v[84:85], v[98:99], v[72:73] op_sel_hi:[0,1,1]
	v_cvt_pk_bf16_f32 v8, v74, s0
	v_cvt_pk_bf16_f32 v20, v75, s0
	v_pk_mul_f32 v[74:75], v[92:93], v[98:99] op_sel:[1,0]
	v_pk_fma_f32 v[76:77], v[94:95], v[100:101], v[76:77] op_sel_hi:[0,1,1] neg_lo:[0,0,1] neg_hi:[0,0,1]
	v_pk_mul_f32 v[78:79], v[92:93], v[100:101] op_sel:[1,0]
	v_perm_b32 v70, v4, v0, s41
	v_cvt_pk_bf16_f32 v0, v72, s0
	v_cvt_pk_bf16_f32 v4, v73, s0
	v_perm_b32 v73, v20, v8, s41
	v_pk_fma_f32 v[74:75], v[94:95], v[96:97], v[74:75] op_sel_hi:[0,1,1] neg_lo:[0,0,1] neg_hi:[0,0,1]
	v_cvt_pk_bf16_f32 v8, v76, s0
	v_cvt_pk_bf16_f32 v20, v77, s0
	v_pk_mul_f32 v[76:77], v[92:93], v[96:97] op_sel:[1,0]
	v_pk_fma_f32 v[78:79], v[94:95], v[102:103], v[78:79] op_sel_hi:[0,1,1]
	v_pk_mul_f32 v[84:85], v[80:81], v[102:103] op_sel:[1,0]
	v_perm_b32 v72, v4, v0, s41
	v_cvt_pk_bf16_f32 v0, v74, s0
	v_cvt_pk_bf16_f32 v4, v75, s0
	v_perm_b32 v75, v20, v8, s41
	v_pk_fma_f32 v[76:77], v[94:95], v[98:99], v[76:77] op_sel_hi:[0,1,1]
	v_cvt_pk_bf16_f32 v8, v78, s0
	v_cvt_pk_bf16_f32 v20, v79, s0
	v_pk_fma_f32 v[84:85], v[82:83], v[100:101], v[84:85] op_sel_hi:[0,1,1] neg_lo:[0,0,1] neg_hi:[0,0,1]
	s_waitcnt vmcnt(4)
; template <int DIR>
; __device__ __forceinline__ void s5_local_dir(const bf16_t* UZ, unsigned char* ws, int gw, int NGW, int lane) {
;     ...
;     for (int t = 0; t < 4; ++t) {
;         const int p = 16 * t + fr;
;         const bf16x4 b_re = *(const bf16x4*)(Bb + (2 * p) * 16 + 4 * fq), b_im = *(const bf16x4*)(Bb + (2 * p + 1) * 16 + 4 * fq);
;         const f32x4 ap = ((const f32x4*)(ws + WS_APOW))[pair * 64 + p];
;         const float ar = ap.x, ai = ap.y;
;         float r2 = ar, i2 = ai; cmul(r2, i2, ar, ai);
;         float r4 = r2, i4 = i2; cmul(r4, i4, r2, i2);
;         float r8 = r4, i8 = i4; cmul(r8, i8, r4, i4);
;         float r12 = r8, i12 = i8; cmul(r12, i12, r4, i4);
;         float r16 = r8, i16 = i8; cmul(r16, i16, r8, i8);
;         float r32 = r16, i32 = i16; cmul(r32, i32, r16, i16);
;         float r48 = r32, i48 = i32; cmul(r48, i48, r16, i16);
;         a1r[t] = ar; a1i[t] = ai; a64r[t] = ap.z; a64i[t] = ap.w;
;         const int e = DIR ? fq : 3 - fq;
;         wr_[t] = e == 0 ? 1.f : e == 1 ? r4 : e == 2 ? r8 : r12; wi_[t] = e == 0 ? 0.f : e == 1 ? i4 : e == 2 ? i8 : i12;
; #pragma unroll
;         for (int m = 0; m < 4; ++m) {
;             const int em = DIR ? m : 3 - m;
;             const float pr = em == 0 ? 1.f : em == 1 ? r16 : em == 2 ? r32 : r48, pi = em == 0 ? 0.f : em == 1 ? i16 : em == 2 ? i32 : i48;
;             Bre[m][t] = cscale_bf(b_re, b_im, pr, pi, false); Bim[m][t] = cscale_bf(b_re, b_im, pr, pi, true);
;         }
	v_pk_mul_f32 v[92:93], v[12:13], v[12:13] op_sel:[1,1] op_sel_hi:[1,0]
	v_perm_b32 v74, v4, v0, s41
	v_cvt_pk_bf16_f32 v4, v77, s0
	v_perm_b32 v77, v20, v8, s41
	v_pk_mul_f32 v[78:79], v[80:81], v[98:99] op_sel:[1,0]
	v_cvt_pk_bf16_f32 v8, v84, s0
	v_cvt_pk_bf16_f32 v20, v85, s0
	v_pk_mul_f32 v[84:85], v[80:81], v[96:97] op_sel:[1,0]
	v_pk_mul_f32 v[80:81], v[80:81], v[100:101] op_sel:[1,0]
	v_pk_fma_f32 v[94:95], v[12:13], v[12:13], v[92:93] op_sel_hi:[1,0,1] neg_lo:[0,0,1] neg_hi:[0,0,1]
	v_pk_fma_f32 v[92:93], v[12:13], v[12:13], v[92:93] op_sel_hi:[1,0,1]
	v_pk_fma_f32 v[78:79], v[82:83], v[96:97], v[78:79] op_sel_hi:[0,1,1] neg_lo:[0,0,1] neg_hi:[0,0,1]
	v_pk_fma_f32 v[80:81], v[82:83], v[102:103], v[80:81] op_sel_hi:[0,1,1]
	v_pk_fma_f32 v[82:83], v[82:83], v[98:99], v[84:85] op_sel_hi:[0,1,1]
	v_xor_b32_e32 v85, 0x80000000, v99
	v_xor_b32_e32 v84, 0x80000000, v98
	v_pk_fma_f32 v[86:87], v[96:97], 0, v[98:99] op_sel_hi:[1,0,1]
	v_pk_mov_b32 v[98:99], v[92:93], v[94:95] op_sel:[1,0]
	v_pk_fma_f32 v[84:85], v[84:85], 0, v[96:97] op_sel_hi:[1,0,1]
	v_mov_b32_e32 v96, v94
	v_mov_b32_e32 v97, v93
	v_pk_mul_f32 v[92:93], v[92:93], v[98:99] op_sel:[1,0]
	v_cvt_pk_bf16_f32 v0, v76, s0
	v_pk_fma_f32 v[98:99], v[94:95], v[96:97], v[92:93] op_sel_hi:[0,1,1] neg_lo:[0,0,1] neg_hi:[0,0,1]
	v_pk_fma_f32 v[92:93], v[94:95], v[96:97], v[92:93] op_sel_hi:[0,1,1]
	v_perm_b32 v76, v4, v0, s41
	v_cvt_pk_bf16_f32 v0, v78, s0
	v_cvt_pk_bf16_f32 v4, v79, s0
	v_pk_mov_b32 v[96:97], v[92:93], v[98:99] op_sel:[1,0]
	v_perm_b32 v78, v4, v0, s41
	v_cvt_pk_bf16_f32 v0, v82, s0
	v_cvt_pk_bf16_f32 v4, v83, s0
	v_xor_b32_e32 v83, 0x80000000, v103
	v_xor_b32_e32 v82, 0x80000000, v102
	v_mov_b32_e32 v94, v98
	v_mov_b32_e32 v95, v93
	v_pk_mul_f32 v[96:97], v[92:93], v[96:97] op_sel:[1,0]
	v_perm_b32 v79, v20, v8, s41
	v_cvt_pk_bf16_f32 v8, v80, s0
	v_perm_b32 v80, v4, v0, s41
	v_pk_fma_f32 v[82:83], v[82:83], 0, v[100:101] op_sel_hi:[1,0,1]
	v_cvt_pk_bf16_f32 v0, v84, s0
	v_cvt_pk_bf16_f32 v4, v85, s0
	v_pk_fma_f32 v[84:85], v[100:101], 0, v[102:103] op_sel_hi:[1,0,1]
	v_pk_fma_f32 v[100:101], v[98:99], v[94:95], v[96:97] op_sel_hi:[0,1,1] neg_lo:[0,0,1] neg_hi:[0,0,1]
	v_pk_fma_f32 v[96:97], v[98:99], v[94:95], v[96:97] op_sel_hi:[0,1,1]
	v_mov_b32_e32 v101, v97
	v_pk_mul_f32 v[102:103], v[100:101], v[100:101]
	v_pk_mul_f32 v[104:105], v[96:97], v[100:101] op_sel:[1,0] op_sel_hi:[0,1]
	v_mov_b32_e32 v106, v102
	v_mov_b32_e32 v107, v104
	v_pk_mov_b32 v[102:103], v[102:103], v[104:105] op_sel:[1,0]
	v_cvt_pk_bf16_f32 v20, v81, s0
	v_pk_add_f32 v[104:105], v[106:107], v[102:103] neg_lo:[0,1] neg_hi:[0,1]
	v_pk_add_f32 v[102:103], v[106:107], v[102:103]
	v_mov_b32_e32 v106, v104
	v_mov_b32_e32 v107, v103
	v_pk_mul_f32 v[110:111], v[106:107], v[106:107]
	v_pk_mul_f32 v[112:113], v[102:103], v[106:107] op_sel:[1,0] op_sel_hi:[0,1]
	v_mov_b32_e32 v114, v110
	v_mov_b32_e32 v115, v112
	v_pk_mov_b32 v[110:111], v[110:111], v[112:113] op_sel:[1,0]
	v_perm_b32 v81, v20, v8, s41
	v_cvt_pk_bf16_f32 v8, v82, s0
	v_cvt_pk_bf16_f32 v20, v83, s0
	v_perm_b32 v82, v4, v0, s41
	v_cvt_pk_bf16_f32 v0, v86, s0
	v_cvt_pk_bf16_f32 v4, v87, s0
	v_pk_add_f32 v[112:113], v[114:115], v[110:111] neg_lo:[0,1] neg_hi:[0,1]
	v_pk_add_f32 v[110:111], v[114:115], v[110:111]
	v_perm_b32 v83, v20, v8, s41
	v_cvt_pk_bf16_f32 v8, v84, s0
	v_perm_b32 v84, v4, v0, s41
	v_mov_b32_e32 v114, v112
	v_mov_b32_e32 v115, v111
	v_mul_f32_e32 v0, v103, v111
	v_pk_mov_b32 v[108:109], v[102:103], v[104:105] op_sel:[1,0]
	v_pk_fma_f32 v[106:107], v[106:107], v[114:115], v[0:1] op_sel_hi:[1,1,0] neg_lo:[0,0,1] neg_hi:[0,0,1]
	v_mul_f32_e32 v0, v104, v111
	v_pk_fma_f32 v[108:109], v[108:109], v[114:115], v[0:1] op_sel_hi:[1,1,0]
	v_mul_f32_e32 v0, v93, v100
	v_pk_mul_f32 v[94:95], v[94:95], v[100:101]
	v_and_b32_e32 v123, 0xffff0000, v91
	v_lshlrev_b32_e32 v122, 16, v91
	v_fmac_f32_e32 v0, v98, v97
	v_sub_f32_e32 v4, v94, v95
	v_and_b32_e32 v119, 0xffff0000, v90
	v_lshlrev_b32_e32 v118, 16, v90
	v_and_b32_e32 v121, 0xffff0000, v89
	v_lshlrev_b32_e32 v120, 16, v89
	v_pk_mul_f32 v[90:91], v[108:109], v[122:123] op_sel_hi:[0,1]
	v_cvt_pk_bf16_f32 v20, v85, s0
	v_cndmask_b32_e32 v4, v4, v100, vcc
	v_cndmask_b32_e32 v0, v0, v97, vcc
	v_and_b32_e32 v117, 0xffff0000, v88
	v_lshlrev_b32_e32 v116, 16, v88
	v_pk_mul_f32 v[88:89], v[108:109], v[118:119] op_sel_hi:[0,1]
	v_pk_fma_f32 v[90:91], v[106:107], v[120:121], v[90:91] op_sel_hi:[0,1,1] neg_lo:[0,0,1] neg_hi:[0,0,1]
	v_pk_mul_f32 v[96:97], v[108:109], v[120:121] op_sel_hi:[0,1]
	v_perm_b32 v85, v20, v8, s41
	v_mov_b32_e32 v86, v12
	v_mov_b32_e32 v87, v12
	v_cndmask_b32_e64 v4, v4, v98, s[2:3]
	v_cndmask_b32_e64 v0, v0, v93, s[2:3]
	v_pk_fma_f32 v[88:89], v[106:107], v[116:117], v[88:89] op_sel_hi:[0,1,1] neg_lo:[0,0,1] neg_hi:[0,0,1]
	v_cvt_pk_bf16_f32 v8, v90, s0
	v_cvt_pk_bf16_f32 v12, v91, s0
	v_pk_mul_f32 v[90:91], v[108:109], v[116:117] op_sel_hi:[0,1]
	v_pk_fma_f32 v[96:97], v[106:107], v[122:123], v[96:97] op_sel_hi:[0,1,1]
	v_pk_mul_f32 v[98:99], v[110:111], v[122:123] op_sel:[1,0]
	v_cndmask_b32_e64 v92, v4, 1.0, s[4:5]
	v_cndmask_b32_e64 v95, v0, 0, s[4:5]
	v_cvt_pk_bf16_f32 v0, v88, s0
	v_cvt_pk_bf16_f32 v4, v89, s0
	v_perm_b32 v89, v12, v8, s41
	v_pk_fma_f32 v[90:91], v[106:107], v[118:119], v[90:91] op_sel_hi:[0,1,1]
	v_cvt_pk_bf16_f32 v8, v96, s0
	v_cvt_pk_bf16_f32 v12, v97, s0
	v_pk_mul_f32 v[96:97], v[110:111], v[118:119] op_sel:[1,0]
	v_pk_fma_f32 v[98:99], v[112:113], v[120:121], v[98:99] op_sel_hi:[0,1,1] neg_lo:[0,0,1] neg_hi:[0,0,1]
	v_pk_mul_f32 v[100:101], v[110:111], v[120:121] op_sel:[1,0]
	v_perm_b32 v88, v4, v0, s41
	v_cvt_pk_bf16_f32 v0, v90, s0
; template <int DIR>
; __device__ __forceinline__ void s5_local_dir(const bf16_t* UZ, unsigned char* ws, int gw, int NGW, int lane) {
;     ...
;     const int pair = gw & 127, g = pair & 63, fr = lane & 15, fq = lane >> 4;
;     const bf16_t* Bb = (const bf16_t*)(ws + WS_BB) + (size_t)pair * 128 * 16;
;     bf16x4 Bre[4][4], Bim[4][4]; float a1r[4], a1i[4], a64r[4], a64i[4], wr_[4], wi_[4];
; #pragma unroll
;     for (int t = 0; t < 4; ++t) {
;         const int p = 16 * t + fr;
;         const bf16x4 b_re = *(const bf16x4*)(Bb + (2 * p) * 16 + 4 * fq), b_im = *(const bf16x4*)(Bb + (2 * p + 1) * 16 + 4 * fq);
;         const f32x4 ap = ((const f32x4*)(ws + WS_APOW))[pair * 64 + p];
;         const float ar = ap.x, ai = ap.y;
;         float r2 = ar, i2 = ai; cmul(r2, i2, ar, ai);
;         float r4 = r2, i4 = i2; cmul(r4, i4, r2, i2);
;         float r8 = r4, i8 = i4; cmul(r8, i8, r4, i4);
;         float r12 = r8, i12 = i8; cmul(r12, i12, r4, i4);
;         float r16 = r8, i16 = i8; cmul(r16, i16, r8, i8);
;         float r32 = r16, i32 = i16; cmul(r32, i32, r16, i16);
;         float r48 = r32, i48 = i32; cmul(r48, i48, r16, i16);
;         a1r[t] = ar; a1i[t] = ai; a64r[t] = ap.z; a64i[t] = ap.w;
;         const int e = DIR ? fq : 3 - fq;
;         wr_[t] = e == 0 ? 1.f : e == 1 ? r4 : e == 2 ? r8 : r12; wi_[t] = e == 0 ? 0.f : e == 1 ? i4 : e == 2 ? i8 : i12;
; #pragma unroll
;         for (int m = 0; m < 4; ++m) {
;             const int em = DIR ? m : 3 - m;
;             const float pr = em == 0 ? 1.f : em == 1 ? r16 : em == 2 ? r32 : r48, pi = em == 0 ? 0.f : em == 1 ? i16 : em == 2 ? i32 : i48;
;             Bre[m][t] = cscale_bf(b_re, b_im, pr, pi, false); Bim[m][t] = cscale_bf(b_re, b_im, pr, pi, true);
;         }
;     }
;     const int qd = gw >> 7, b = qd >> 2, q = qd & 3;
;     if (qd >= 16) return;
;     const int c0 = 17 * q, c1 = q < 3 ? c0 + 17 : 67;
;     float Rr[4] = {0.f, 0.f, 0.f, 0.f}, Ri[4] = {0.f, 0.f, 0.f, 0.f};
;     float* ebase = E + ((size_t)((b * 2 + DIR) * 64 + g) * NCHUNK) * 128;
	v_cvt_pk_bf16_f32 v4, v91, s0
	v_perm_b32 v91, v12, v8, s41
	v_pk_fma_f32 v[96:97], v[112:113], v[116:117], v[96:97] op_sel_hi:[0,1,1] neg_lo:[0,0,1] neg_hi:[0,0,1]
	v_cvt_pk_bf16_f32 v8, v98, s0
	v_cvt_pk_bf16_f32 v12, v99, s0
	v_pk_mul_f32 v[98:99], v[110:111], v[116:117] op_sel:[1,0]
	v_pk_fma_f32 v[100:101], v[112:113], v[122:123], v[100:101] op_sel_hi:[0,1,1]
	v_pk_mul_f32 v[106:107], v[102:103], v[122:123] op_sel:[1,0]
	v_perm_b32 v90, v4, v0, s41
	v_cvt_pk_bf16_f32 v0, v96, s0
	v_cvt_pk_bf16_f32 v4, v97, s0
	v_perm_b32 v97, v12, v8, s41
	v_pk_fma_f32 v[98:99], v[112:113], v[118:119], v[98:99] op_sel_hi:[0,1,1]
	v_cvt_pk_bf16_f32 v8, v100, s0
	v_cvt_pk_bf16_f32 v12, v101, s0
	v_pk_fma_f32 v[106:107], v[104:105], v[120:121], v[106:107] op_sel_hi:[0,1,1] neg_lo:[0,0,1] neg_hi:[0,0,1]
	v_perm_b32 v96, v4, v0, s41
	v_cvt_pk_bf16_f32 v4, v99, s0
	v_perm_b32 v99, v12, v8, s41
	v_pk_mul_f32 v[100:101], v[102:103], v[118:119] op_sel:[1,0]
	v_cvt_pk_bf16_f32 v8, v106, s0
	v_cvt_pk_bf16_f32 v12, v107, s0
	v_pk_mul_f32 v[106:107], v[102:103], v[116:117] op_sel:[1,0]
	v_pk_mul_f32 v[102:103], v[102:103], v[120:121] op_sel:[1,0]
	v_pk_fma_f32 v[100:101], v[104:105], v[116:117], v[100:101] op_sel_hi:[0,1,1] neg_lo:[0,0,1] neg_hi:[0,0,1]
	v_pk_fma_f32 v[102:103], v[104:105], v[122:123], v[102:103] op_sel_hi:[0,1,1]
	v_pk_fma_f32 v[104:105], v[104:105], v[118:119], v[106:107] op_sel_hi:[0,1,1]
	v_add_u32_e32 v106, s25, v127
	v_ashrrev_i32_e32 v107, 31, v106
	v_lshlrev_b64 v[106:107], 12, v[106:107]
	v_lshl_add_u64 v[106:107], v[16:17], 0, v[106:107]
	s_mov_b32 s2, 0x10000
	v_add_co_u32_e32 v124, vcc, s2, v106
	s_mov_b32 s2, 0x20000
	s_nop 0
	v_addc_co_u32_e32 v125, vcc, 0, v107, vcc
	v_add_co_u32_e32 v128, vcc, s2, v106
	s_mov_b32 s2, 0x30000
	s_nop 0
	v_addc_co_u32_e32 v129, vcc, 0, v107, vcc
	v_add_co_u32_e32 v130, vcc, s2, v106
	v_cvt_pk_bf16_f32 v0, v98, s0
	s_nop 0
	v_addc_co_u32_e32 v131, vcc, 0, v107, vcc
	s_waitcnt vmcnt(0)
	v_mov_b64_e32 v[108:109], v[152:153]
	v_mov_b64_e32 v[112:113], v[154:155]
	v_mov_b64_e32 v[114:115], v[156:157]
	v_mov_b64_e32 v[110:111], v[158:159]
	v_perm_b32 v98, v4, v0, s41
	v_cvt_pk_bf16_f32 v0, v100, s0
	v_cvt_pk_bf16_f32 v4, v101, s0
	v_xor_b32_e32 v107, 0x80000000, v119
	v_xor_b32_e32 v106, 0x80000000, v118
	v_perm_b32 v100, v4, v0, s41
	v_cvt_pk_bf16_f32 v0, v104, s0
	v_cvt_pk_bf16_f32 v4, v105, s0
	v_xor_b32_e32 v105, 0x80000000, v123
	v_xor_b32_e32 v104, 0x80000000, v122
	v_pk_fma_f32 v[106:107], v[106:107], 0, v[116:117] op_sel_hi:[1,0,1]
	v_perm_b32 v101, v12, v8, s41
	v_cvt_pk_bf16_f32 v8, v102, s0
	v_cvt_pk_bf16_f32 v12, v103, s0
	v_perm_b32 v102, v4, v0, s41
	v_pk_fma_f32 v[104:105], v[104:105], 0, v[120:121] op_sel_hi:[1,0,1]
	v_cvt_pk_bf16_f32 v0, v106, s0
	v_cvt_pk_bf16_f32 v4, v107, s0
	v_pk_fma_f32 v[116:117], v[116:117], 0, v[118:119] op_sel_hi:[1,0,1]
	v_perm_b32 v103, v12, v8, s41
	v_cvt_pk_bf16_f32 v8, v104, s0
	v_cvt_pk_bf16_f32 v12, v105, s0
	v_perm_b32 v104, v4, v0, s41
	v_pk_fma_f32 v[106:107], v[120:121], 0, v[122:123] op_sel_hi:[1,0,1]
	v_cvt_pk_bf16_f32 v0, v116, s0
	v_cvt_pk_bf16_f32 v4, v117, s0
	v_perm_b32 v105, v12, v8, s41
	v_cvt_pk_bf16_f32 v8, v106, s0
	v_perm_b32 v106, v4, v0, s41
	v_mbcnt_lo_u32_b32 v0, -1, 0
	v_cvt_pk_bf16_f32 v12, v107, s0
	v_mbcnt_hi_u32_b32 v0, -1, v0
	v_perm_b32 v107, v12, v8, s41
	s_lshl_b32 s41, s23, 12
	s_lshl_b32 s42, s23, 8
	v_and_b32_e32 v8, 64, v0
	s_add_i32 s4, s38, s36
	s_bfe_u32 s23, s40, 0x20007
	s_addk_i32 s41, 0xff00
	s_addk_i32 s42, 0x4000
	v_xor_b32_e32 v4, 16, v0
	v_add_u32_e32 v8, 64, v8
	s_mul_hi_i32 s5, s4, 0x8800
	s_mul_i32 s4, s4, 0x8800
	s_mulk_i32 s23, 0x2200
	v_cmp_lt_i32_e32 vcc, v4, v8
	s_add_u32 s4, s4, s23
	s_addc_u32 s5, s5, 0
	v_cndmask_b32_e32 v4, v0, v4, vcc
	v_lshlrev_b32_e32 v128, 2, v4
	v_xor_b32_e32 v4, 32, v0
	s_add_u32 s4, s30, s4
	v_cmp_lt_i32_e32 vcc, v4, v8
	v_lshlrev_b32_e32 v20, 2, v126
	s_addc_u32 s5, s31, s5
	v_cndmask_b32_e32 v0, v0, v4, vcc
	v_lshl_add_u64 v[116:117], s[4:5], 0, v[20:21]
	s_mov_b64 s[4:5], 0x1700100
	v_or_b32_e32 v20, s22, v127
	v_lshlrev_b32_e32 v129, 2, v0
	v_cmp_gt_u32_e64 s[2:3], 16, v126
	v_xor_b32_e32 v0, 0x80000000, v1
	v_mov_b32_e32 v23, v22
	v_xor_b32_e32 v24, 0x80000000, v25
	v_xor_b32_e32 v4, 0x80000000, v5
	v_mov_b32_e32 v45, v44
	v_xor_b32_e32 v46, 0x80000000, v47
	v_xor_b32_e32 v8, 0x80000000, v9
	v_mov_b32_e32 v67, v66
	v_xor_b32_e32 v68, 0x80000000, v69
	v_xor_b32_e32 v12, 0x80000000, v13
	v_mov_b32_e32 v93, v92
	v_xor_b32_e32 v94, 0x80000000, v95
	v_lshl_add_u64 v[116:117], v[116:117], 0, s[4:5]
	v_add_u32_e32 v20, 0x70, v20
	s_mov_b64 s[4:5], 0x200
	v_mov_b32_e32 v133, v21
	v_mov_b32_e32 v131, v21
	v_mov_b32_e32 v127, v21
	v_mov_b32_e32 v135, v21
	v_mov_b32_e32 v134, v21
	v_mov_b32_e32 v132, v21
	v_mov_b32_e32 v130, v21
	v_and_b32_e32 v244, 16, v126
	v_and_b32_e32 v245, 32, v126
	v_cmp_ne_u32_e64 s[96:97], 0, v244
	v_cmp_ne_u32_e32 vcc, 0, v245
	s_nop 1
	v_cndmask_b32_e32 v244, v2, v10, vcc
	v_cndmask_b32_e32 v245, v6, v14, vcc
	v_cndmask_b32_e64 v242, v244, v245, s[96:97]
	v_cndmask_b32_e32 v244, v3, v11, vcc
	v_cndmask_b32_e32 v245, v7, v15, vcc
	v_cndmask_b32_e64 v243, v244, v245, s[96:97]
	v_readfirstlane_b32 s98, v192
	s_lshr_b32 s98, s98, 6
	s_lshl_b32 s99, s12, 3
	s_add_i32 s98, s98, s99
	s_and_b32 s98, s98, 0x7f
	v_and_b32_e32 v216, 63, v192
	s_lshl_b32 s99, s98, 6
	v_or_b32_e32 v217, s99, v216
	v_lshlrev_b32_e32 v217, 4, v217
	s_add_u32 s100, s30, 0x80000
	s_addc_u32 s101, s31, 0
	global_load_dwordx4 v[212:215], v217, s[100:101]
	s_lshl_b32 s99, s98, 12
	s_add_u32 s100, s30, 0x100000
	s_addc_u32 s101, s31, 0
	s_add_u32 s100, s100, s99
	s_addc_u32 s101, s101, 0
	v_lshlrev_b32_e32 v216, 6, v216
	global_load_dwordx4 v[196:199], v216, s[100:101] offset:0
	global_load_dwordx4 v[200:203], v216, s[100:101] offset:16
	global_load_dwordx4 v[204:207], v216, s[100:101] offset:32
	global_load_dwordx4 v[208:211], v216, s[100:101] offset:48
	s_waitcnt vmcnt(0)
; template <int DIR>
; __device__ __forceinline__ void s5_local_dir(const bf16_t* UZ, unsigned char* ws, int gw, int NGW, int lane) {
;     ...
;     for (int t = 0; t < 4; ++t) {
;         const int p = 16 * t + fr;
;         const bf16x4 b_re = *(const bf16x4*)(Bb + (2 * p) * 16 + 4 * fq), b_im = *(const bf16x4*)(Bb + (2 * p + 1) * 16 + 4 * fq);
;         const f32x4 ap = ((const f32x4*)(ws + WS_APOW))[pair * 64 + p];
;         const float ar = ap.x, ai = ap.y;
;         float r2 = ar, i2 = ai; cmul(r2, i2, ar, ai);
;         float r4 = r2, i4 = i2; cmul(r4, i4, r2, i2);
;         float r8 = r4, i8 = i4; cmul(r8, i8, r4, i4);
;         float r12 = r8, i12 = i8; cmul(r12, i12, r4, i4);
;         float r16 = r8, i16 = i8; cmul(r16, i16, r8, i8);
;         float r32 = r16, i32 = i16; cmul(r32, i32, r16, i16);
;         float r48 = r32, i48 = i32; cmul(r48, i48, r16, i16);
;         a1r[t] = ar; a1i[t] = ai; a64r[t] = ap.z; a64i[t] = ap.w;
;         const int e = DIR ? fq : 3 - fq;
;         wr_[t] = e == 0 ? 1.f : e == 1 ? r4 : e == 2 ? r8 : r12; wi_[t] = e == 0 ? 0.f : e == 1 ? i4 : e == 2 ? i8 : i12;
; #pragma unroll
;         for (int m = 0; m < 4; ++m) {
;             const int em = DIR ? m : 3 - m;
;             const float pr = em == 0 ? 1.f : em == 1 ? r16 : em == 2 ? r32 : r48, pi = em == 0 ? 0.f : em == 1 ? i16 : em == 2 ? i32 : i48;
;             Bre[m][t] = cscale_bf(b_re, b_im, pr, pi, false); Bim[m][t] = cscale_bf(b_re, b_im, pr, pi, true);
;         }
	v_mov_b32_e32 v246, v212
	v_mov_b32_e32 v247, v213
	v_xor_b32_e32 v248, 0x80000000, v213
	v_mul_f32_e32 v218, v213, v213
	v_fma_f32 v216, v212, v212, -v218
	v_mul_f32_e32 v218, v213, v212
	v_fma_f32 v217, v212, v213, v218
	v_mul_f32_e32 v218, v217, v217
	v_fma_f32 v146, v216, v216, -v218
	v_mul_f32_e32 v218, v217, v216
	v_fma_f32 v147, v216, v217, v218
	v_mul_f32_e32 v218, v147, v147
	v_fma_f32 v148, v146, v146, -v218
	v_mul_f32_e32 v218, v147, v146
	v_fma_f32 v149, v146, v147, v218
	v_mul_f32_e32 v218, v149, v149
	v_fma_f32 v140, v148, v148, -v218
	v_mul_f32_e32 v218, v149, v148
	v_fma_f32 v141, v148, v149, v218
	v_mul_f32_e32 v218, v141, v141
	v_fma_f32 v142, v140, v140, -v218
	v_mul_f32_e32 v218, v141, v140
	v_fma_f32 v143, v140, v141, v218
	v_mul_f32_e32 v218, v143, v141
	v_fma_f32 v144, v142, v140, -v218
	v_mul_f32_e32 v218, v143, v140
	v_fma_f32 v145, v142, v141, v218
	v_lshlrev_b32_e32 v152, 16, v196
	v_and_b32_e32 v153, 0xffff0000, v196
	v_lshlrev_b32_e32 v168, 16, v204
	v_and_b32_e32 v169, 0xffff0000, v204
	v_lshlrev_b32_e32 v154, 16, v197
	v_and_b32_e32 v155, 0xffff0000, v197
	v_lshlrev_b32_e32 v170, 16, v205
	v_and_b32_e32 v171, 0xffff0000, v205
	v_lshlrev_b32_e32 v156, 16, v198
	v_and_b32_e32 v157, 0xffff0000, v198
	v_lshlrev_b32_e32 v172, 16, v206
	v_and_b32_e32 v173, 0xffff0000, v206
	v_lshlrev_b32_e32 v158, 16, v199
	v_and_b32_e32 v159, 0xffff0000, v199
	v_lshlrev_b32_e32 v174, 16, v207
	v_and_b32_e32 v175, 0xffff0000, v207
	v_lshlrev_b32_e32 v160, 16, v200
	v_and_b32_e32 v161, 0xffff0000, v200
	v_lshlrev_b32_e32 v176, 16, v208
	v_and_b32_e32 v177, 0xffff0000, v208
	v_lshlrev_b32_e32 v162, 16, v201
	v_and_b32_e32 v163, 0xffff0000, v201
	v_lshlrev_b32_e32 v178, 16, v209
	v_and_b32_e32 v179, 0xffff0000, v209
	v_lshlrev_b32_e32 v164, 16, v202
	v_and_b32_e32 v165, 0xffff0000, v202
	v_lshlrev_b32_e32 v180, 16, v210
	v_and_b32_e32 v181, 0xffff0000, v210
	v_lshlrev_b32_e32 v166, 16, v203
	v_and_b32_e32 v167, 0xffff0000, v203
	v_lshlrev_b32_e32 v182, 16, v211
	v_and_b32_e32 v183, 0xffff0000, v211
	v_mul_f32_e32 v218, v145, v168
	v_fma_f32 v220, v144, v152, -v218
	v_mul_f32_e32 v219, v145, v152
	v_fma_f32 v236, v144, v168, v219
	v_mul_f32_e32 v218, v145, v169
	v_fma_f32 v221, v144, v153, -v218
	v_mul_f32_e32 v219, v145, v153
	v_fma_f32 v237, v144, v169, v219
	v_mul_f32_e32 v218, v145, v170
	v_fma_f32 v222, v144, v154, -v218
	v_mul_f32_e32 v219, v145, v154
	v_fma_f32 v238, v144, v170, v219
	v_mul_f32_e32 v218, v145, v171
	v_fma_f32 v223, v144, v155, -v218
	v_mul_f32_e32 v219, v145, v155
	v_fma_f32 v239, v144, v171, v219
	v_cvt_pk_bf16_f32 v26, v220, v221
	v_cvt_pk_bf16_f32 v27, v222, v223
	v_cvt_pk_bf16_f32 v34, v236, v237
	v_cvt_pk_bf16_f32 v35, v238, v239
	v_mul_f32_e32 v218, v145, v172
	v_fma_f32 v220, v144, v156, -v218
	v_mul_f32_e32 v219, v145, v156
	v_fma_f32 v236, v144, v172, v219
	v_mul_f32_e32 v218, v145, v173
	v_fma_f32 v221, v144, v157, -v218
	v_mul_f32_e32 v219, v145, v157
	v_fma_f32 v237, v144, v173, v219
	v_mul_f32_e32 v218, v145, v174
	v_fma_f32 v222, v144, v158, -v218
	v_mul_f32_e32 v219, v145, v158
	v_fma_f32 v238, v144, v174, v219
	v_mul_f32_e32 v218, v145, v175
	v_fma_f32 v223, v144, v159, -v218
	v_mul_f32_e32 v219, v145, v159
	v_fma_f32 v239, v144, v175, v219
	v_cvt_pk_bf16_f32 v28, v220, v221
	v_cvt_pk_bf16_f32 v29, v222, v223
	v_cvt_pk_bf16_f32 v36, v236, v237
	v_cvt_pk_bf16_f32 v37, v238, v239
	v_mul_f32_e32 v218, v145, v176
	v_fma_f32 v220, v144, v160, -v218
	v_mul_f32_e32 v219, v145, v160
	v_fma_f32 v236, v144, v176, v219
	v_mul_f32_e32 v218, v145, v177
	v_fma_f32 v221, v144, v161, -v218
	v_mul_f32_e32 v219, v145, v161
	v_fma_f32 v237, v144, v177, v219
	v_mul_f32_e32 v218, v145, v178
	v_fma_f32 v222, v144, v162, -v218
	v_mul_f32_e32 v219, v145, v162
	v_fma_f32 v238, v144, v178, v219
	v_mul_f32_e32 v218, v145, v179
	v_fma_f32 v223, v144, v163, -v218
	v_mul_f32_e32 v219, v145, v163
	v_fma_f32 v239, v144, v179, v219
	v_cvt_pk_bf16_f32 v30, v220, v221
	v_cvt_pk_bf16_f32 v31, v222, v223
	v_cvt_pk_bf16_f32 v38, v236, v237
	v_cvt_pk_bf16_f32 v39, v238, v239
	v_mul_f32_e32 v218, v145, v180
	v_fma_f32 v220, v144, v164, -v218
	v_mul_f32_e32 v219, v145, v164
	v_fma_f32 v236, v144, v180, v219
	v_mul_f32_e32 v218, v145, v181
	v_fma_f32 v221, v144, v165, -v218
	v_mul_f32_e32 v219, v145, v165
	v_fma_f32 v237, v144, v181, v219
	v_mul_f32_e32 v218, v145, v182
	v_fma_f32 v222, v144, v166, -v218
	v_mul_f32_e32 v219, v145, v166
	v_fma_f32 v238, v144, v182, v219
	v_mul_f32_e32 v218, v145, v183
	v_fma_f32 v223, v144, v167, -v218
	v_mul_f32_e32 v219, v145, v167
	v_fma_f32 v239, v144, v183, v219
	v_cvt_pk_bf16_f32 v32, v220, v221
	v_cvt_pk_bf16_f32 v33, v222, v223
	v_cvt_pk_bf16_f32 v40, v236, v237
	v_cvt_pk_bf16_f32 v41, v238, v239
	v_mul_f32_e32 v218, v143, v168
	v_fma_f32 v220, v142, v152, -v218
	v_mul_f32_e32 v219, v143, v152
	v_fma_f32 v236, v142, v168, v219
	v_mul_f32_e32 v218, v143, v169
	v_fma_f32 v221, v142, v153, -v218
	v_mul_f32_e32 v219, v143, v153
	v_fma_f32 v237, v142, v169, v219
	v_mul_f32_e32 v218, v143, v170
	v_fma_f32 v222, v142, v154, -v218
	v_mul_f32_e32 v219, v143, v154
	v_fma_f32 v238, v142, v170, v219
	v_mul_f32_e32 v218, v143, v171
	v_fma_f32 v223, v142, v155, -v218
	v_mul_f32_e32 v219, v143, v155
	v_fma_f32 v239, v142, v171, v219
	v_cvt_pk_bf16_f32 v48, v220, v221
	v_cvt_pk_bf16_f32 v49, v222, v223
; __device__ __forceinline__ unsigned pk2(float lo, float hi) { f32x2 v = {lo, hi}; nbf2 r = __builtin_convertvector(v, nbf2); return __builtin_bit_cast(unsigned, r); }
; __device__ __forceinline__ bf16x4 cscale_bf(const bf16x4 re, const bf16x4 im, float wr, float wi, bool want_im) {
;     bf16x4 o;
; #pragma unroll
;     for (int k = 0; k < 4; k += 2) {
;         const float r0 = __uint_as_float((unsigned)(unsigned short)re[k] << 16), r1 = __uint_as_float((unsigned)(unsigned short)re[k + 1] << 16);
;         const float i0 = __uint_as_float((unsigned)(unsigned short)im[k] << 16), i1 = __uint_as_float((unsigned)(unsigned short)im[k + 1] << 16);
;         const unsigned w = want_im ? pk2(wr * i0 + wi * r0, wr * i1 + wi * r1) : pk2(wr * r0 - wi * i0, wr * r1 - wi * i1);
;         o[k] = (short)(w & 0xffffu); o[k + 1] = (short)(w >> 16);
;     }
;     return o;
; }
; template <int DIR>
; __device__ __forceinline__ void s5_local_dir(const bf16_t* UZ, unsigned char* ws, int gw, int NGW, int lane) {
;     ...
;         const int e = DIR ? fq : 3 - fq;
;         wr_[t] = e == 0 ? 1.f : e == 1 ? r4 : e == 2 ? r8 : r12; wi_[t] = e == 0 ? 0.f : e == 1 ? i4 : e == 2 ? i8 : i12;
; #pragma unroll
;         for (int m = 0; m < 4; ++m) {
;             const int em = DIR ? m : 3 - m;
;             const float pr = em == 0 ? 1.f : em == 1 ? r16 : em == 2 ? r32 : r48, pi = em == 0 ? 0.f : em == 1 ? i16 : em == 2 ? i32 : i48;
;             Bre[m][t] = cscale_bf(b_re, b_im, pr, pi, false); Bim[m][t] = cscale_bf(b_re, b_im, pr, pi, true);
;         }
	v_cvt_pk_bf16_f32 v56, v236, v237
	v_cvt_pk_bf16_f32 v57, v238, v239
	v_mul_f32_e32 v218, v143, v172
	v_fma_f32 v220, v142, v156, -v218
	v_mul_f32_e32 v219, v143, v156
	v_fma_f32 v236, v142, v172, v219
	v_mul_f32_e32 v218, v143, v173
	v_fma_f32 v221, v142, v157, -v218
	v_mul_f32_e32 v219, v143, v157
	v_fma_f32 v237, v142, v173, v219
	v_mul_f32_e32 v218, v143, v174
	v_fma_f32 v222, v142, v158, -v218
	v_mul_f32_e32 v219, v143, v158
	v_fma_f32 v238, v142, v174, v219
	v_mul_f32_e32 v218, v143, v175
	v_fma_f32 v223, v142, v159, -v218
	v_mul_f32_e32 v219, v143, v159
	v_fma_f32 v239, v142, v175, v219
	v_cvt_pk_bf16_f32 v50, v220, v221
	v_cvt_pk_bf16_f32 v51, v222, v223
	v_cvt_pk_bf16_f32 v58, v236, v237
	v_cvt_pk_bf16_f32 v59, v238, v239
	v_mul_f32_e32 v218, v143, v176
	v_fma_f32 v220, v142, v160, -v218
	v_mul_f32_e32 v219, v143, v160
	v_fma_f32 v236, v142, v176, v219
	v_mul_f32_e32 v218, v143, v177
	v_fma_f32 v221, v142, v161, -v218
	v_mul_f32_e32 v219, v143, v161
	v_fma_f32 v237, v142, v177, v219
	v_mul_f32_e32 v218, v143, v178
	v_fma_f32 v222, v142, v162, -v218
	v_mul_f32_e32 v219, v143, v162
	v_fma_f32 v238, v142, v178, v219
	v_mul_f32_e32 v218, v143, v179
	v_fma_f32 v223, v142, v163, -v218
	v_mul_f32_e32 v219, v143, v163
	v_fma_f32 v239, v142, v179, v219
	v_cvt_pk_bf16_f32 v52, v220, v221
	v_cvt_pk_bf16_f32 v53, v222, v223
	v_cvt_pk_bf16_f32 v60, v236, v237
	v_cvt_pk_bf16_f32 v61, v238, v239
	v_mul_f32_e32 v218, v143, v180
	v_fma_f32 v220, v142, v164, -v218
	v_mul_f32_e32 v219, v143, v164
	v_fma_f32 v236, v142, v180, v219
	v_mul_f32_e32 v218, v143, v181
	v_fma_f32 v221, v142, v165, -v218
	v_mul_f32_e32 v219, v143, v165
	v_fma_f32 v237, v142, v181, v219
	v_mul_f32_e32 v218, v143, v182
	v_fma_f32 v222, v142, v166, -v218
	v_mul_f32_e32 v219, v143, v166
	v_fma_f32 v238, v142, v182, v219
	v_mul_f32_e32 v218, v143, v183
	v_fma_f32 v223, v142, v167, -v218
	v_mul_f32_e32 v219, v143, v167
	v_fma_f32 v239, v142, v183, v219
	v_cvt_pk_bf16_f32 v54, v220, v221
	v_cvt_pk_bf16_f32 v55, v222, v223
	v_cvt_pk_bf16_f32 v62, v236, v237
	v_cvt_pk_bf16_f32 v63, v238, v239
	v_mul_f32_e32 v218, v141, v168
	v_fma_f32 v220, v140, v152, -v218
	v_mul_f32_e32 v219, v141, v152
	v_fma_f32 v236, v140, v168, v219
	v_mul_f32_e32 v218, v141, v169
	v_fma_f32 v221, v140, v153, -v218
	v_mul_f32_e32 v219, v141, v153
	v_fma_f32 v237, v140, v169, v219
	v_mul_f32_e32 v218, v141, v170
	v_fma_f32 v222, v140, v154, -v218
	v_mul_f32_e32 v219, v141, v154
	v_fma_f32 v238, v140, v170, v219
	v_mul_f32_e32 v218, v141, v171
	v_fma_f32 v223, v140, v155, -v218
	v_mul_f32_e32 v219, v141, v155
	v_fma_f32 v239, v140, v171, v219
	v_cvt_pk_bf16_f32 v70, v220, v221
	v_cvt_pk_bf16_f32 v71, v222, v223
	v_cvt_pk_bf16_f32 v78, v236, v237
	v_cvt_pk_bf16_f32 v79, v238, v239
	v_mul_f32_e32 v218, v141, v172
	v_fma_f32 v220, v140, v156, -v218
	v_mul_f32_e32 v219, v141, v156
	v_fma_f32 v236, v140, v172, v219
	v_mul_f32_e32 v218, v141, v173
	v_fma_f32 v221, v140, v157, -v218
	v_mul_f32_e32 v219, v141, v157
	v_fma_f32 v237, v140, v173, v219
	v_mul_f32_e32 v218, v141, v174
	v_fma_f32 v222, v140, v158, -v218
	v_mul_f32_e32 v219, v141, v158
	v_fma_f32 v238, v140, v174, v219
	v_mul_f32_e32 v218, v141, v175
	v_fma_f32 v223, v140, v159, -v218
	v_mul_f32_e32 v219, v141, v159
	v_fma_f32 v239, v140, v175, v219
	v_cvt_pk_bf16_f32 v72, v220, v221
	v_cvt_pk_bf16_f32 v73, v222, v223
	v_cvt_pk_bf16_f32 v80, v236, v237
	v_cvt_pk_bf16_f32 v81, v238, v239
	v_mul_f32_e32 v218, v141, v176
	v_fma_f32 v220, v140, v160, -v218
	v_mul_f32_e32 v219, v141, v160
	v_fma_f32 v236, v140, v176, v219
	v_mul_f32_e32 v218, v141, v177
	v_fma_f32 v221, v140, v161, -v218
	v_mul_f32_e32 v219, v141, v161
	v_fma_f32 v237, v140, v177, v219
	v_mul_f32_e32 v218, v141, v178
	v_fma_f32 v222, v140, v162, -v218
	v_mul_f32_e32 v219, v141, v162
	v_fma_f32 v238, v140, v178, v219
	v_mul_f32_e32 v218, v141, v179
	v_fma_f32 v223, v140, v163, -v218
	v_mul_f32_e32 v219, v141, v163
	v_fma_f32 v239, v140, v179, v219
	v_cvt_pk_bf16_f32 v74, v220, v221
	v_cvt_pk_bf16_f32 v75, v222, v223
	v_cvt_pk_bf16_f32 v82, v236, v237
	v_cvt_pk_bf16_f32 v83, v238, v239
	v_mul_f32_e32 v218, v141, v180
	v_fma_f32 v220, v140, v164, -v218
	v_mul_f32_e32 v219, v141, v164
	v_fma_f32 v236, v140, v180, v219
	v_mul_f32_e32 v218, v141, v181
	v_fma_f32 v221, v140, v165, -v218
	v_mul_f32_e32 v219, v141, v165
	v_fma_f32 v237, v140, v181, v219
	v_mul_f32_e32 v218, v141, v182
	v_fma_f32 v222, v140, v166, -v218
	v_mul_f32_e32 v219, v141, v166
	v_fma_f32 v238, v140, v182, v219
	v_mul_f32_e32 v218, v141, v183
	v_fma_f32 v223, v140, v167, -v218
	v_mul_f32_e32 v219, v141, v167
	v_fma_f32 v239, v140, v183, v219
	v_cvt_pk_bf16_f32 v76, v220, v221
	v_cvt_pk_bf16_f32 v77, v222, v223
	v_cvt_pk_bf16_f32 v84, v236, v237
	v_cvt_pk_bf16_f32 v85, v238, v239
	v_cvt_pk_bf16_f32 v88, v152, v153
	v_cvt_pk_bf16_f32 v89, v154, v155
	v_cvt_pk_bf16_f32 v100, v168, v169
	v_cvt_pk_bf16_f32 v101, v170, v171
	v_cvt_pk_bf16_f32 v90, v156, v157
	v_cvt_pk_bf16_f32 v91, v158, v159
	v_cvt_pk_bf16_f32 v102, v172, v173
	v_cvt_pk_bf16_f32 v103, v174, v175
	v_cvt_pk_bf16_f32 v96, v160, v161
	v_cvt_pk_bf16_f32 v97, v162, v163
	v_cvt_pk_bf16_f32 v104, v176, v177
	v_cvt_pk_bf16_f32 v105, v178, v179
	v_cvt_pk_bf16_f32 v98, v164, v165
	v_cvt_pk_bf16_f32 v99, v166, v167
	v_cvt_pk_bf16_f32 v106, v180, v181
	v_cvt_pk_bf16_f32 v107, v182, v183
	s_nop 1

; template <int DIR>
; __device__ __forceinline__ void s5_local_dir(const bf16_t* UZ, unsigned char* ws, int gw, int NGW, int lane) {
;     ...
;         for (int t = 0; t < 4; ++t) {
;             f32x4 cr = {0.f, 0.f, 0.f, 0.f}, ci = {0.f, 0.f, 0.f, 0.f};
; #pragma unroll
;             for (int m = 0; m < 4; ++m) {
;                 cr = __builtin_amdgcn_mfma_f32_16x16x16bf16_1k(Uf[m], Bre[m][t], cr, 0, 0, 0);
;                 ci = __builtin_amdgcn_mfma_f32_16x16x16bf16_1k(Uf[m], Bim[m][t], ci, 0, 0, 0);
;             }
.LBB0_674:
	global_store_dword v[116:117], v240, off offset:-256
	global_store_dword v[116:117], v241, off
	s_waitcnt vmcnt(9)
	v_mfma_f32_4x4x4_16b_bf16 v[140:143], v[108:109], v[26:27], 0 cbsz:4 abid:0
	v_mfma_f32_4x4x4_16b_bf16 v[144:147], v[108:109], v[34:35], 0 cbsz:4 abid:0
	v_mfma_f32_4x4x4_16b_bf16 v[196:199], v[108:109], v[26:27], 0 cbsz:4 abid:1
	v_mfma_f32_4x4x4_16b_bf16 v[200:203], v[108:109], v[34:35], 0 cbsz:4 abid:1
	v_mfma_f32_4x4x4_16b_bf16 v[204:207], v[108:109], v[26:27], 0 cbsz:4 abid:2
	v_mfma_f32_4x4x4_16b_bf16 v[208:211], v[108:109], v[34:35], 0 cbsz:4 abid:2
	v_mfma_f32_4x4x4_16b_bf16 v[212:215], v[108:109], v[26:27], 0 cbsz:4 abid:3
	v_mfma_f32_4x4x4_16b_bf16 v[216:219], v[108:109], v[34:35], 0 cbsz:4 abid:3
	v_mfma_f32_4x4x4_16b_bf16 v[140:143], v[108:109], v[28:29], v[140:143] cbsz:4 abid:4
	v_mfma_f32_4x4x4_16b_bf16 v[144:147], v[108:109], v[36:37], v[144:147] cbsz:4 abid:4
	v_mfma_f32_4x4x4_16b_bf16 v[196:199], v[108:109], v[28:29], v[196:199] cbsz:4 abid:5
	v_mfma_f32_4x4x4_16b_bf16 v[200:203], v[108:109], v[36:37], v[200:203] cbsz:4 abid:5
	v_mfma_f32_4x4x4_16b_bf16 v[204:207], v[108:109], v[28:29], v[204:207] cbsz:4 abid:6
	v_mfma_f32_4x4x4_16b_bf16 v[208:211], v[108:109], v[36:37], v[208:211] cbsz:4 abid:6
	v_mfma_f32_4x4x4_16b_bf16 v[212:215], v[108:109], v[28:29], v[212:215] cbsz:4 abid:7
	v_mfma_f32_4x4x4_16b_bf16 v[216:219], v[108:109], v[36:37], v[216:219] cbsz:4 abid:7
	v_mfma_f32_4x4x4_16b_bf16 v[140:143], v[108:109], v[30:31], v[140:143] cbsz:4 abid:8
	v_mfma_f32_4x4x4_16b_bf16 v[144:147], v[108:109], v[38:39], v[144:147] cbsz:4 abid:8
	v_mfma_f32_4x4x4_16b_bf16 v[196:199], v[108:109], v[30:31], v[196:199] cbsz:4 abid:9
	v_mfma_f32_4x4x4_16b_bf16 v[200:203], v[108:109], v[38:39], v[200:203] cbsz:4 abid:9
	v_mfma_f32_4x4x4_16b_bf16 v[204:207], v[108:109], v[30:31], v[204:207] cbsz:4 abid:10
	v_mfma_f32_4x4x4_16b_bf16 v[208:211], v[108:109], v[38:39], v[208:211] cbsz:4 abid:10
	v_mfma_f32_4x4x4_16b_bf16 v[212:215], v[108:109], v[30:31], v[212:215] cbsz:4 abid:11
	v_mfma_f32_4x4x4_16b_bf16 v[216:219], v[108:109], v[38:39], v[216:219] cbsz:4 abid:11
	v_mfma_f32_4x4x4_16b_bf16 v[140:143], v[108:109], v[32:33], v[140:143] cbsz:4 abid:12
	v_mfma_f32_4x4x4_16b_bf16 v[144:147], v[108:109], v[40:41], v[144:147] cbsz:4 abid:12
	v_mfma_f32_4x4x4_16b_bf16 v[196:199], v[108:109], v[32:33], v[196:199] cbsz:4 abid:13
	v_mfma_f32_4x4x4_16b_bf16 v[200:203], v[108:109], v[40:41], v[200:203] cbsz:4 abid:13
	v_mfma_f32_4x4x4_16b_bf16 v[204:207], v[108:109], v[32:33], v[204:207] cbsz:4 abid:14
	v_mfma_f32_4x4x4_16b_bf16 v[208:211], v[108:109], v[40:41], v[208:211] cbsz:4 abid:14
	v_mfma_f32_4x4x4_16b_bf16 v[212:215], v[108:109], v[32:33], v[212:215] cbsz:4 abid:15
	v_mfma_f32_4x4x4_16b_bf16 v[216:219], v[108:109], v[40:41], v[216:219] cbsz:4 abid:15
	s_waitcnt vmcnt(8)
	v_mfma_f32_4x4x4_16b_bf16 v[140:143], v[112:113], v[48:49], v[140:143] cbsz:4 abid:0
	v_mfma_f32_4x4x4_16b_bf16 v[144:147], v[112:113], v[56:57], v[144:147] cbsz:4 abid:0
	v_mfma_f32_4x4x4_16b_bf16 v[196:199], v[112:113], v[48:49], v[196:199] cbsz:4 abid:1
	v_mfma_f32_4x4x4_16b_bf16 v[200:203], v[112:113], v[56:57], v[200:203] cbsz:4 abid:1
	v_mfma_f32_4x4x4_16b_bf16 v[204:207], v[112:113], v[48:49], v[204:207] cbsz:4 abid:2
	v_mfma_f32_4x4x4_16b_bf16 v[208:211], v[112:113], v[56:57], v[208:211] cbsz:4 abid:2
	v_mfma_f32_4x4x4_16b_bf16 v[212:215], v[112:113], v[48:49], v[212:215] cbsz:4 abid:3
	v_mfma_f32_4x4x4_16b_bf16 v[216:219], v[112:113], v[56:57], v[216:219] cbsz:4 abid:3
	v_mfma_f32_4x4x4_16b_bf16 v[140:143], v[112:113], v[50:51], v[140:143] cbsz:4 abid:4
	v_mfma_f32_4x4x4_16b_bf16 v[144:147], v[112:113], v[58:59], v[144:147] cbsz:4 abid:4
	v_mfma_f32_4x4x4_16b_bf16 v[196:199], v[112:113], v[50:51], v[196:199] cbsz:4 abid:5
	v_mfma_f32_4x4x4_16b_bf16 v[200:203], v[112:113], v[58:59], v[200:203] cbsz:4 abid:5
	v_mfma_f32_4x4x4_16b_bf16 v[204:207], v[112:113], v[50:51], v[204:207] cbsz:4 abid:6
	v_mfma_f32_4x4x4_16b_bf16 v[208:211], v[112:113], v[58:59], v[208:211] cbsz:4 abid:6
	v_mfma_f32_4x4x4_16b_bf16 v[212:215], v[112:113], v[50:51], v[212:215] cbsz:4 abid:7
	v_mfma_f32_4x4x4_16b_bf16 v[216:219], v[112:113], v[58:59], v[216:219] cbsz:4 abid:7
	v_mfma_f32_4x4x4_16b_bf16 v[140:143], v[112:113], v[52:53], v[140:143] cbsz:4 abid:8
	v_mfma_f32_4x4x4_16b_bf16 v[144:147], v[112:113], v[60:61], v[144:147] cbsz:4 abid:8
	v_mfma_f32_4x4x4_16b_bf16 v[196:199], v[112:113], v[52:53], v[196:199] cbsz:4 abid:9
	v_mfma_f32_4x4x4_16b_bf16 v[200:203], v[112:113], v[60:61], v[200:203] cbsz:4 abid:9
	v_mfma_f32_4x4x4_16b_bf16 v[204:207], v[112:113], v[52:53], v[204:207] cbsz:4 abid:10
	v_mfma_f32_4x4x4_16b_bf16 v[208:211], v[112:113], v[60:61], v[208:211] cbsz:4 abid:10
	v_mfma_f32_4x4x4_16b_bf16 v[212:215], v[112:113], v[52:53], v[212:215] cbsz:4 abid:11
	v_mfma_f32_4x4x4_16b_bf16 v[216:219], v[112:113], v[60:61], v[216:219] cbsz:4 abid:11
	v_mfma_f32_4x4x4_16b_bf16 v[140:143], v[112:113], v[54:55], v[140:143] cbsz:4 abid:12
	v_mfma_f32_4x4x4_16b_bf16 v[144:147], v[112:113], v[62:63], v[144:147] cbsz:4 abid:12
	v_mfma_f32_4x4x4_16b_bf16 v[196:199], v[112:113], v[54:55], v[196:199] cbsz:4 abid:13
	v_mfma_f32_4x4x4_16b_bf16 v[200:203], v[112:113], v[62:63], v[200:203] cbsz:4 abid:13
	v_mfma_f32_4x4x4_16b_bf16 v[204:207], v[112:113], v[54:55], v[204:207] cbsz:4 abid:14
	v_mfma_f32_4x4x4_16b_bf16 v[208:211], v[112:113], v[62:63], v[208:211] cbsz:4 abid:14
	v_mfma_f32_4x4x4_16b_bf16 v[212:215], v[112:113], v[54:55], v[212:215] cbsz:4 abid:15
	v_mfma_f32_4x4x4_16b_bf16 v[216:219], v[112:113], v[62:63], v[216:219] cbsz:4 abid:15
	s_waitcnt vmcnt(7)
; template <int DIR>
; __device__ __forceinline__ void s5_local_dir(const bf16_t* UZ, unsigned char* ws, int gw, int NGW, int lane) {
;     ...
;         for (int t = 0; t < 4; ++t) {
;             f32x4 cr = {0.f, 0.f, 0.f, 0.f}, ci = {0.f, 0.f, 0.f, 0.f};
; #pragma unroll
;             for (int m = 0; m < 4; ++m) {
;                 cr = __builtin_amdgcn_mfma_f32_16x16x16bf16_1k(Uf[m], Bre[m][t], cr, 0, 0, 0);
;                 ci = __builtin_amdgcn_mfma_f32_16x16x16bf16_1k(Uf[m], Bim[m][t], ci, 0, 0, 0);
;             }
	v_mfma_f32_4x4x4_16b_bf16 v[140:143], v[114:115], v[70:71], v[140:143] cbsz:4 abid:0
	v_mfma_f32_4x4x4_16b_bf16 v[144:147], v[114:115], v[78:79], v[144:147] cbsz:4 abid:0
	v_mfma_f32_4x4x4_16b_bf16 v[196:199], v[114:115], v[70:71], v[196:199] cbsz:4 abid:1
	v_mfma_f32_4x4x4_16b_bf16 v[200:203], v[114:115], v[78:79], v[200:203] cbsz:4 abid:1
	v_mfma_f32_4x4x4_16b_bf16 v[204:207], v[114:115], v[70:71], v[204:207] cbsz:4 abid:2
	v_mfma_f32_4x4x4_16b_bf16 v[208:211], v[114:115], v[78:79], v[208:211] cbsz:4 abid:2
	v_mfma_f32_4x4x4_16b_bf16 v[212:215], v[114:115], v[70:71], v[212:215] cbsz:4 abid:3
	v_mfma_f32_4x4x4_16b_bf16 v[216:219], v[114:115], v[78:79], v[216:219] cbsz:4 abid:3
	v_mfma_f32_4x4x4_16b_bf16 v[140:143], v[114:115], v[72:73], v[140:143] cbsz:4 abid:4
	v_mfma_f32_4x4x4_16b_bf16 v[144:147], v[114:115], v[80:81], v[144:147] cbsz:4 abid:4
	v_mfma_f32_4x4x4_16b_bf16 v[196:199], v[114:115], v[72:73], v[196:199] cbsz:4 abid:5
	v_mfma_f32_4x4x4_16b_bf16 v[200:203], v[114:115], v[80:81], v[200:203] cbsz:4 abid:5
	v_mfma_f32_4x4x4_16b_bf16 v[204:207], v[114:115], v[72:73], v[204:207] cbsz:4 abid:6
	v_mfma_f32_4x4x4_16b_bf16 v[208:211], v[114:115], v[80:81], v[208:211] cbsz:4 abid:6
	v_mfma_f32_4x4x4_16b_bf16 v[212:215], v[114:115], v[72:73], v[212:215] cbsz:4 abid:7
	v_mfma_f32_4x4x4_16b_bf16 v[216:219], v[114:115], v[80:81], v[216:219] cbsz:4 abid:7
	v_mfma_f32_4x4x4_16b_bf16 v[140:143], v[114:115], v[74:75], v[140:143] cbsz:4 abid:8
	v_mfma_f32_4x4x4_16b_bf16 v[144:147], v[114:115], v[82:83], v[144:147] cbsz:4 abid:8
	v_mfma_f32_4x4x4_16b_bf16 v[196:199], v[114:115], v[74:75], v[196:199] cbsz:4 abid:9
	v_mfma_f32_4x4x4_16b_bf16 v[200:203], v[114:115], v[82:83], v[200:203] cbsz:4 abid:9
	v_mfma_f32_4x4x4_16b_bf16 v[204:207], v[114:115], v[74:75], v[204:207] cbsz:4 abid:10
	v_mfma_f32_4x4x4_16b_bf16 v[208:211], v[114:115], v[82:83], v[208:211] cbsz:4 abid:10
	v_mfma_f32_4x4x4_16b_bf16 v[212:215], v[114:115], v[74:75], v[212:215] cbsz:4 abid:11
	v_mfma_f32_4x4x4_16b_bf16 v[216:219], v[114:115], v[82:83], v[216:219] cbsz:4 abid:11
	v_mfma_f32_4x4x4_16b_bf16 v[140:143], v[114:115], v[76:77], v[140:143] cbsz:4 abid:12
	v_mfma_f32_4x4x4_16b_bf16 v[144:147], v[114:115], v[84:85], v[144:147] cbsz:4 abid:12
	v_mfma_f32_4x4x4_16b_bf16 v[196:199], v[114:115], v[76:77], v[196:199] cbsz:4 abid:13
	v_mfma_f32_4x4x4_16b_bf16 v[200:203], v[114:115], v[84:85], v[200:203] cbsz:4 abid:13
	v_mfma_f32_4x4x4_16b_bf16 v[204:207], v[114:115], v[76:77], v[204:207] cbsz:4 abid:14
	v_mfma_f32_4x4x4_16b_bf16 v[208:211], v[114:115], v[84:85], v[208:211] cbsz:4 abid:14
	v_mfma_f32_4x4x4_16b_bf16 v[212:215], v[114:115], v[76:77], v[212:215] cbsz:4 abid:15
	v_mfma_f32_4x4x4_16b_bf16 v[216:219], v[114:115], v[84:85], v[216:219] cbsz:4 abid:15
	s_waitcnt vmcnt(6)
; template <int DIR>
; __device__ __forceinline__ void s5_local_dir(const bf16_t* UZ, unsigned char* ws, int gw, int NGW, int lane) {
;     ...
;     for (int c = c0; c < c1; ++c) {
;         bf16x4 Uf[4];
; #pragma unroll
;         for (int m = 0; m < 4; ++m) Uf[m] = Un[m];
;         if (c + 1 < c1) load_uf(Un, UZ, chunk_rowbase(b, DIR, c + 1), g, lane);
;         float* e = ebase + (size_t)c * 128;
; #pragma unroll
;         for (int t = 0; t < 4; ++t) {
;             f32x4 cr = {0.f, 0.f, 0.f, 0.f}, ci = {0.f, 0.f, 0.f, 0.f};
; #pragma unroll
;             for (int m = 0; m < 4; ++m) {
;                 cr = __builtin_amdgcn_mfma_f32_16x16x16bf16_1k(Uf[m], Bre[m][t], cr, 0, 0, 0);
;                 ci = __builtin_amdgcn_mfma_f32_16x16x16bf16_1k(Uf[m], Bim[m][t], ci, 0, 0, 0);
;             }
;             f32x2 s2 = {DIR ? cr[3] : cr[0], DIR ? ci[3] : ci[0]};
; #pragma unroll
;             for (int ii = 1; ii < 4; ++ii) { const int i = DIR ? 3 - ii : ii;
;                 s2 = cmac(s2, (f32x2){a1r[t], a1r[t]}, (f32x2){-a1i[t], a1i[t]}, (f32x2){cr[i], ci[i]}); }
;             s2 = cmac(s2, (f32x2){wr_[t], wr_[t]}, (f32x2){-wi_[t], wi_[t]}, (f32x2){0.f, 0.f});
;             float sr = s2.x, si = s2.y;
;             sr += __shfl_xor(sr, 16); si += __shfl_xor(si, 16); sr += __shfl_xor(sr, 32); si += __shfl_xor(si, 32);
;             if (fq == 0) { e[16 * t + fr] = Rr[t]; e[64 + 16 * t + fr] = Ri[t]; }
;             const float nr = fmaf(a64r[t], Rr[t], fmaf(-a64i[t], Ri[t], sr)), ni = fmaf(a64r[t], Ri[t], fmaf(a64i[t], Rr[t], si)); Rr[t] = nr; Ri[t] = ni;
;         }
;     }
	v_mfma_f32_4x4x4_16b_bf16 v[140:143], v[110:111], v[88:89], v[140:143] cbsz:4 abid:0
	v_mfma_f32_4x4x4_16b_bf16 v[144:147], v[110:111], v[100:101], v[144:147] cbsz:4 abid:0
	v_mfma_f32_4x4x4_16b_bf16 v[196:199], v[110:111], v[88:89], v[196:199] cbsz:4 abid:1
	v_mfma_f32_4x4x4_16b_bf16 v[200:203], v[110:111], v[100:101], v[200:203] cbsz:4 abid:1
	v_mfma_f32_4x4x4_16b_bf16 v[204:207], v[110:111], v[88:89], v[204:207] cbsz:4 abid:2
	v_mfma_f32_4x4x4_16b_bf16 v[208:211], v[110:111], v[100:101], v[208:211] cbsz:4 abid:2
	v_mfma_f32_4x4x4_16b_bf16 v[212:215], v[110:111], v[88:89], v[212:215] cbsz:4 abid:3
	v_mfma_f32_4x4x4_16b_bf16 v[216:219], v[110:111], v[100:101], v[216:219] cbsz:4 abid:3
	v_mfma_f32_4x4x4_16b_bf16 v[140:143], v[110:111], v[90:91], v[140:143] cbsz:4 abid:4
	v_mfma_f32_4x4x4_16b_bf16 v[144:147], v[110:111], v[102:103], v[144:147] cbsz:4 abid:4
	v_mfma_f32_4x4x4_16b_bf16 v[196:199], v[110:111], v[90:91], v[196:199] cbsz:4 abid:5
	v_mfma_f32_4x4x4_16b_bf16 v[200:203], v[110:111], v[102:103], v[200:203] cbsz:4 abid:5
	v_mfma_f32_4x4x4_16b_bf16 v[204:207], v[110:111], v[90:91], v[204:207] cbsz:4 abid:6
	v_mfma_f32_4x4x4_16b_bf16 v[208:211], v[110:111], v[102:103], v[208:211] cbsz:4 abid:6
	v_mfma_f32_4x4x4_16b_bf16 v[212:215], v[110:111], v[90:91], v[212:215] cbsz:4 abid:7
	v_mfma_f32_4x4x4_16b_bf16 v[216:219], v[110:111], v[102:103], v[216:219] cbsz:4 abid:7
	v_mfma_f32_4x4x4_16b_bf16 v[140:143], v[110:111], v[96:97], v[140:143] cbsz:4 abid:8
	v_mfma_f32_4x4x4_16b_bf16 v[144:147], v[110:111], v[104:105], v[144:147] cbsz:4 abid:8
	v_mfma_f32_4x4x4_16b_bf16 v[196:199], v[110:111], v[96:97], v[196:199] cbsz:4 abid:9
	v_mfma_f32_4x4x4_16b_bf16 v[200:203], v[110:111], v[104:105], v[200:203] cbsz:4 abid:9
	v_mfma_f32_4x4x4_16b_bf16 v[204:207], v[110:111], v[96:97], v[204:207] cbsz:4 abid:10
	v_mfma_f32_4x4x4_16b_bf16 v[208:211], v[110:111], v[104:105], v[208:211] cbsz:4 abid:10
	v_mfma_f32_4x4x4_16b_bf16 v[212:215], v[110:111], v[96:97], v[212:215] cbsz:4 abid:11
	v_mfma_f32_4x4x4_16b_bf16 v[216:219], v[110:111], v[104:105], v[216:219] cbsz:4 abid:11
	v_mfma_f32_4x4x4_16b_bf16 v[140:143], v[110:111], v[98:99], v[140:143] cbsz:4 abid:12
	v_mfma_f32_4x4x4_16b_bf16 v[144:147], v[110:111], v[106:107], v[144:147] cbsz:4 abid:12
	v_mfma_f32_4x4x4_16b_bf16 v[196:199], v[110:111], v[98:99], v[196:199] cbsz:4 abid:13
	v_mfma_f32_4x4x4_16b_bf16 v[200:203], v[110:111], v[106:107], v[200:203] cbsz:4 abid:13
	v_mfma_f32_4x4x4_16b_bf16 v[204:207], v[110:111], v[98:99], v[204:207] cbsz:4 abid:14
	v_mfma_f32_4x4x4_16b_bf16 v[208:211], v[110:111], v[106:107], v[208:211] cbsz:4 abid:14
	v_mfma_f32_4x4x4_16b_bf16 v[212:215], v[110:111], v[98:99], v[212:215] cbsz:4 abid:15
	v_mfma_f32_4x4x4_16b_bf16 v[216:219], v[110:111], v[106:107], v[216:219] cbsz:4 abid:15
	s_nop 4
	v_fma_f32 v141, v246, v140, v141
	v_fma_f32 v145, v246, v144, v145
	v_fma_f32 v141, v248, v144, v141
	v_fma_f32 v145, v247, v140, v145
	v_fma_f32 v142, v246, v141, v142
	v_fma_f32 v146, v246, v145, v146
	v_fma_f32 v142, v248, v145, v142
	v_fma_f32 v146, v247, v141, v146
	v_fma_f32 v143, v246, v142, v143
	v_fma_f32 v147, v246, v146, v147
	v_fma_f32 v143, v248, v146, v143
	v_fma_f32 v147, v247, v142, v147
	v_fma_f32 v196, v246, v143, v196
	v_fma_f32 v200, v246, v147, v200
	v_fma_f32 v196, v248, v147, v196
	v_fma_f32 v200, v247, v143, v200
	v_fma_f32 v197, v246, v196, v197
	v_fma_f32 v201, v246, v200, v201
	v_fma_f32 v197, v248, v200, v197
	v_fma_f32 v201, v247, v196, v201
	v_fma_f32 v198, v246, v197, v198
	v_fma_f32 v202, v246, v201, v202
	v_fma_f32 v198, v248, v201, v198
	v_fma_f32 v202, v247, v197, v202
	v_fma_f32 v199, v246, v198, v199
	v_fma_f32 v203, v246, v202, v203
	v_fma_f32 v199, v248, v202, v199
	v_fma_f32 v203, v247, v198, v203
	v_fma_f32 v204, v246, v199, v204
	v_fma_f32 v208, v246, v203, v208
	v_fma_f32 v204, v248, v203, v204
	v_fma_f32 v208, v247, v199, v208
	v_fma_f32 v205, v246, v204, v205
	v_fma_f32 v209, v246, v208, v209
	v_fma_f32 v205, v248, v208, v205
	v_fma_f32 v209, v247, v204, v209
	v_fma_f32 v206, v246, v205, v206
	v_fma_f32 v210, v246, v209, v210
	v_fma_f32 v206, v248, v209, v206
	v_fma_f32 v210, v247, v205, v210
	v_fma_f32 v207, v246, v206, v207
	v_fma_f32 v211, v246, v210, v211
	v_fma_f32 v207, v248, v210, v207
	v_fma_f32 v211, v247, v206, v211
	v_fma_f32 v212, v246, v207, v212
	v_fma_f32 v216, v246, v211, v216
	v_fma_f32 v212, v248, v211, v212
	v_fma_f32 v216, v247, v207, v216
	v_fma_f32 v213, v246, v212, v213
	v_fma_f32 v217, v246, v216, v217
	v_fma_f32 v213, v248, v216, v213
	v_fma_f32 v217, v247, v212, v217
	v_fma_f32 v214, v246, v213, v214
	v_fma_f32 v218, v246, v217, v218
	v_fma_f32 v214, v248, v217, v214
	v_fma_f32 v218, v247, v213, v218
	v_fma_f32 v215, v246, v214, v215
	v_fma_f32 v219, v246, v218, v219
	v_fma_f32 v215, v248, v218, v215
	v_fma_f32 v219, v247, v214, v219
	v_fma_f32 v244, -v243, v241, v215
	v_fma_f32 v245, v243, v240, v219
	v_fma_f32 v240, v242, v240, v244
	v_fma_f32 v241, v242, v241, v245
	v_lshl_add_u64 v[116:117], v[116:117], 0, s[4:5]
	v_add_u32_e32 v20, 64, v20
	s_and_b64 vcc, exec, s[22:23]
	s_cbranch_vccnz .LBB0_702
	s_mov_b32 s24, s40
	s_waitcnt vmcnt(3)
	v_mov_b32_e32 v108, v118
	v_mov_b32_e32 v109, v119
	s_waitcnt vmcnt(2)
	v_mov_b32_e32 v112, v120
	v_mov_b32_e32 v113, v121
	s_waitcnt vmcnt(1)
	v_mov_b32_e32 v114, v122
	v_mov_b32_e32 v115, v123
	s_waitcnt vmcnt(0)
	v_mov_b32_e32 v110, v124
	v_mov_b32_e32 v111, v125
	s_branch .LBB0_671
